# K-loop MFMA block exit: closing barrier directly after the last MFMA, priority drop after the barrier
# speedup vs baseline: 1.0047x; 1.0013x over previous
; #define PG8_STAGE(bufoff, gbase, voff) do { _Pragma("unroll") for (int _i = 0; _i < 2; ++_i) \
;         __builtin_amdgcn_global_load_lds((const unsigned*)((const char*)(gbase) + (voff)[_i]), (PG8_LAS unsigned*)(lds + (bufoff) + ldsw + _i * 8192), 16, 0, 0); } while (0)
; #define PG8_LDA(dst, b, h) do { _Pragma("unroll") for (int m = 0; m < 4; ++m) _Pragma("unroll") for (int k = 0; k < 2; ++k) dst[m][k] = *(const PG8_LAS bf16x8*)(lds + PG8_SA(b, h) + aoff + m * 2048 + k * 1024); } while (0)
; #define PG8_LDB(dst, b, h) do { _Pragma("unroll") for (int n = 0; n < 2; ++n) _Pragma("unroll") for (int k = 0; k < 2; ++k) dst[n][k] = *(const PG8_LAS bf16x8*)(lds + PG8_SB(b, h) + boff + n * 2048 + k * 1024); } while (0)
; #define PG8_MMA(ai, bj, At, Bt) do { __builtin_amdgcn_s_setprio(1); _Pragma("unroll") for (int m = 0; m < 4; ++m) _Pragma("unroll") for (int n = 0; n < 2; ++n) _Pragma("unroll") for (int k = 0; k < 2; ++k) \
;         acc[ai][bj][m][n] = __builtin_amdgcn_mfma_f32_16x16x32_bf16(Bt[n][k], At[m][k], acc[ai][bj][m][n], 0, 0, 0); __builtin_amdgcn_s_setprio(0); } while (0)
; #define PG8_WAIT_V(n) asm volatile("s_waitcnt vmcnt(" #n ")" ::: "memory")
; #define PG8_WAIT_VN(n) asm volatile("s_waitcnt vmcnt(%0)" :: "n"(n) : "memory")
; #define PG8_WAIT_L(n) asm volatile("s_waitcnt lgkmcnt(" #n ")" ::: "memory")
; #define PG8_BAR __builtin_amdgcn_s_barrier()
; #define PG8_SCHED __builtin_amdgcn_sched_barrier(0)
; template <class Epi, class Sched, bool ALIGN_EPI = false, bool SP2 = false>
; __device__ __forceinline__ void gemm_phase(PG8_LAS unsigned char* lds, const Gemm g, const Sched& S, const Epi& E, const int wave_id) {
;     ...
;             PG8_WAIT_VN(8 + Epi::NS); if (strict) PG8_WAIT_V(8); PG8_WAIT_L(0); PG8_BAR; PG8_MMA(1, 0, At, B0); PG8_MMA(1, 1, At, B1); PG8_BAR; PG8_SCHED;
;             PG8_LDB(B0, 1, 0); PG8_LDB(B1, 1, 1); PG8_SCHED; PG8_LDA(At, 1, 0); PG8_STAGE(PG8_SA(0, 1), a2 + hstep, voffA);
;             PG8_WAIT_V(8); PG8_WAIT_L(0); PG8_BAR; PG8_MMA(0, 0, At, B0); PG8_MMA(0, 1, At, B1); PG8_BAR; PG8_SCHED;
.LBB0_157:
	s_waitcnt lgkmcnt(0)
	s_setprio 1
	s_barrier
	v_mfma_f32_16x16x32_bf16 v[62:65], v[146:149], v[186:189], v[62:65]
	v_mfma_f32_16x16x32_bf16 v[58:61], v[154:157], v[186:189], v[58:61]
	v_mfma_f32_16x16x32_bf16 v[54:57], v[146:149], v[178:181], v[54:57]
	v_mfma_f32_16x16x32_bf16 v[50:53], v[154:157], v[178:181], v[50:53]
	v_mfma_f32_16x16x32_bf16 v[30:33], v[146:149], v[170:173], v[30:33]
	v_mfma_f32_16x16x32_bf16 v[26:29], v[154:157], v[170:173], v[26:29]
	v_mfma_f32_16x16x32_bf16 v[22:25], v[146:149], v[162:165], v[22:25]
	v_mfma_f32_16x16x32_bf16 v[18:21], v[154:157], v[162:165], v[18:21]
	v_mfma_f32_16x16x32_bf16 v[62:65], v[150:153], v[190:193], v[62:65]
	v_mfma_f32_16x16x32_bf16 v[58:61], v[158:161], v[190:193], v[58:61]
	v_mfma_f32_16x16x32_bf16 v[54:57], v[150:153], v[182:185], v[54:57]
	v_mfma_f32_16x16x32_bf16 v[50:53], v[158:161], v[182:185], v[50:53]
	v_mfma_f32_16x16x32_bf16 v[30:33], v[150:153], v[174:177], v[30:33]
	v_mfma_f32_16x16x32_bf16 v[26:29], v[158:161], v[174:177], v[26:29]
	v_mfma_f32_16x16x32_bf16 v[22:25], v[150:153], v[166:169], v[22:25]
	v_mfma_f32_16x16x32_bf16 v[18:21], v[158:161], v[166:169], v[18:21]
	s_setprio 0
	s_setprio 1
	v_mfma_f32_16x16x32_bf16 v[46:49], v[130:133], v[186:189], v[46:49]
	v_mfma_f32_16x16x32_bf16 v[42:45], v[138:141], v[186:189], v[42:45]
	v_mfma_f32_16x16x32_bf16 v[38:41], v[130:133], v[178:181], v[38:41]
	v_mfma_f32_16x16x32_bf16 v[34:37], v[138:141], v[178:181], v[34:37]
	v_mfma_f32_16x16x32_bf16 v[14:17], v[130:133], v[170:173], v[14:17]
	v_mfma_f32_16x16x32_bf16 v[10:13], v[138:141], v[170:173], v[10:13]
	v_mfma_f32_16x16x32_bf16 v[6:9], v[130:133], v[162:165], v[6:9]
	v_mfma_f32_16x16x32_bf16 v[2:5], v[138:141], v[162:165], v[2:5]
	v_mfma_f32_16x16x32_bf16 v[46:49], v[134:137], v[190:193], v[46:49]
	v_mfma_f32_16x16x32_bf16 v[42:45], v[142:145], v[190:193], v[42:45]
	v_mfma_f32_16x16x32_bf16 v[38:41], v[134:137], v[182:185], v[38:41]
	v_mfma_f32_16x16x32_bf16 v[34:37], v[142:145], v[182:185], v[34:37]
	v_mfma_f32_16x16x32_bf16 v[14:17], v[134:137], v[174:177], v[14:17]
	v_mfma_f32_16x16x32_bf16 v[10:13], v[142:145], v[174:177], v[10:13]
	v_mfma_f32_16x16x32_bf16 v[6:9], v[134:137], v[166:169], v[6:9]
	v_mfma_f32_16x16x32_bf16 v[2:5], v[142:145], v[166:169], v[2:5]
	s_barrier
	s_setprio 0
	s_add_i32 s28, 0, 0x18000
	s_add_i32 s29, 0, 0x1c000
	v_add_u32_e32 v142, s28, v246
	v_add_u32_e32 v158, s29, v246
	ds_read_b128 v[130:133], v142
	ds_read_b128 v[134:137], v142 offset:1024
	ds_read_b128 v[138:141], v142 offset:2048
	ds_read_b128 v[142:145], v142 offset:3072
	ds_read_b128 v[146:149], v158
	ds_read_b128 v[150:153], v158 offset:1024
	ds_read_b128 v[154:157], v158 offset:2048
	ds_read_b128 v[158:161], v158 offset:3072
	s_add_u32 s26, s26, 0x40000
	s_addc_u32 s27, s27, 0
	s_mov_b32 m0, s52
	v_lshl_add_u64 v[194:195], s[26:27], 0, v[210:211]
	ds_read_b128 v[162:165], v249 offset:32768
	ds_read_b128 v[166:169], v249 offset:33792
	ds_read_b128 v[170:173], v249 offset:34816
	ds_read_b128 v[174:177], v249 offset:35840
	ds_read_b128 v[178:181], v249 offset:36864
	ds_read_b128 v[182:185], v249 offset:37888
	ds_read_b128 v[186:189], v249 offset:38912
	ds_read_b128 v[190:193], v249 offset:39936
	global_load_lds_dwordx4 v[194:195], off
	v_lshl_add_u64 v[194:195], s[26:27], 0, v[214:215]
	s_mov_b32 m0, s54
	s_nop 0
	global_load_lds_dwordx4 v[194:195], off
	s_waitcnt vmcnt(18)
	s_cmp_eq_u32 s100, 0
	s_cbranch_scc1 .Lthird_wait_relaxed_6
	s_waitcnt vmcnt(8)
; #define PG8_STAGE(bufoff, gbase, voff) do { _Pragma("unroll") for (int _i = 0; _i < 2; ++_i) \
;         __builtin_amdgcn_global_load_lds((const unsigned*)((const char*)(gbase) + (voff)[_i]), (PG8_LAS unsigned*)(lds + (bufoff) + ldsw + _i * 8192), 16, 0, 0); } while (0)
; #define PG8_WAIT_V(n) asm volatile("s_waitcnt vmcnt(" #n ")" ::: "memory")
; #define PG8_WAIT_VN(n) asm volatile("s_waitcnt vmcnt(%0)" :: "n"(n) : "memory")
; template <class Epi, class Sched, bool ALIGN_EPI = false, bool SP2 = false>
; __device__ __forceinline__ void gemm_phase(PG8_LAS unsigned char* lds, const Gemm g, const Sched& S, const Epi& E, const int wave_id) {
;     ...
;         for (int t = 0; t < nt; t += 2) {
;             const bool last = (t == nt - 2);
;             const char* a1 = cA + (size_t)(t + 1) * kstep;
;             const char* a2 = last ? nA : cA + (size_t)(t + 2) * kstep; const char* b2 = last ? nB : cB + (size_t)(t + 2) * kstep;
;             const char* a3 = a2 + kstep; const char* b3 = b2 + kstep;
;             if (last && has_next) S.a_ready(nxt);
;             if constexpr (SP2) {
;             int tz_ = __builtin_amdgcn_readfirstlane(t | (ui > 0 ? 0 : 1)); asm volatile("" : "+s"(tz_));
;             const bool strict = !(Epi::NS > 0 && tz_ == 0);
;             PG8_LDB(B0, 0, 0); PG8_LDB(B1, 0, 1); PG8_SCHED; PG8_LDA(At, 0, 0); PG8_STAGE(PG8_SA(1, 1), a1 + hstep, voffA);
;             PG8_WAIT_VN(8 + Epi::NS); if (strict) PG8_WAIT_V(8); PG8_WAIT_L(0); PG8_BAR; PG8_MMA(0, 0, At, B0); PG8_MMA(0, 1, At, B1); PG8_BAR; PG8_SCHED;
;             PG8_LDA(At, 0, 1); PG8_STAGE(PG8_SB(0, 0), b2, voffB); PG8_STAGE(PG8_SB(0, 1), b2 + hstep, voffB); PG8_STAGE(PG8_SA(0, 0), a2, voffA);
;             PG8_WAIT_VN(8 + Epi::NS); if (strict) PG8_WAIT_V(8); PG8_WAIT_L(0); PG8_BAR; PG8_MMA(1, 0, At, B0); PG8_MMA(1, 1, At, B1); PG8_BAR; PG8_SCHED;
;             PG8_LDB(B0, 1, 0); PG8_LDB(B1, 1, 1); PG8_SCHED; PG8_LDA(At, 1, 0); PG8_STAGE(PG8_SA(0, 1), a2 + hstep, voffA);
;             PG8_WAIT_V(8); PG8_WAIT_L(0); PG8_BAR; PG8_MMA(0, 0, At, B0); PG8_MMA(0, 1, At, B1); PG8_BAR; PG8_SCHED;
;             PG8_LDA(At, 1, 1); PG8_STAGE(PG8_SB(1, 0), b3, voffB); PG8_STAGE(PG8_SB(1, 1), b3 + hstep, voffB); PG8_STAGE(PG8_SA(1, 0), a3, voffA);
;             PG8_WAIT_V(8); PG8_WAIT_L(0); PG8_BAR; PG8_MMA(1, 0, At, B0); PG8_MMA(1, 1, At, B1); PG8_BAR; PG8_SCHED;
.Lthird_wait_relaxed_6:
	s_waitcnt lgkmcnt(0)
	s_setprio 1
	s_barrier
	v_mfma_f32_16x16x32_bf16 v[126:129], v[130:133], v[162:165], v[126:129]
	v_mfma_f32_16x16x32_bf16 v[122:125], v[138:141], v[162:165], v[122:125]
	v_mfma_f32_16x16x32_bf16 v[118:121], v[130:133], v[170:173], v[118:121]
	v_mfma_f32_16x16x32_bf16 v[114:117], v[138:141], v[170:173], v[114:117]
	v_mfma_f32_16x16x32_bf16 v[94:97], v[130:133], v[178:181], v[94:97]
	v_mfma_f32_16x16x32_bf16 v[90:93], v[138:141], v[178:181], v[90:93]
	v_mfma_f32_16x16x32_bf16 v[86:89], v[130:133], v[186:189], v[86:89]
	v_mfma_f32_16x16x32_bf16 v[82:85], v[138:141], v[186:189], v[82:85]
	v_mfma_f32_16x16x32_bf16 v[126:129], v[134:137], v[166:169], v[126:129]
	v_mfma_f32_16x16x32_bf16 v[122:125], v[142:145], v[166:169], v[122:125]
	v_mfma_f32_16x16x32_bf16 v[118:121], v[134:137], v[174:177], v[118:121]
	v_mfma_f32_16x16x32_bf16 v[114:117], v[142:145], v[174:177], v[114:117]
	v_mfma_f32_16x16x32_bf16 v[94:97], v[134:137], v[182:185], v[94:97]
	v_mfma_f32_16x16x32_bf16 v[90:93], v[142:145], v[182:185], v[90:93]
	v_mfma_f32_16x16x32_bf16 v[86:89], v[134:137], v[190:193], v[86:89]
	v_mfma_f32_16x16x32_bf16 v[82:85], v[142:145], v[190:193], v[82:85]
	s_setprio 0
	s_setprio 1
	v_mfma_f32_16x16x32_bf16 v[110:113], v[146:149], v[162:165], v[110:113]
	v_mfma_f32_16x16x32_bf16 v[106:109], v[154:157], v[162:165], v[106:109]
	v_mfma_f32_16x16x32_bf16 v[102:105], v[146:149], v[170:173], v[102:105]
	v_mfma_f32_16x16x32_bf16 v[98:101], v[154:157], v[170:173], v[98:101]
	v_mfma_f32_16x16x32_bf16 v[78:81], v[146:149], v[178:181], v[78:81]
	v_mfma_f32_16x16x32_bf16 v[74:77], v[154:157], v[178:181], v[74:77]
	v_mfma_f32_16x16x32_bf16 v[70:73], v[146:149], v[186:189], v[70:73]
	v_mfma_f32_16x16x32_bf16 v[66:69], v[154:157], v[186:189], v[66:69]
	v_mfma_f32_16x16x32_bf16 v[110:113], v[150:153], v[166:169], v[110:113]
	v_mfma_f32_16x16x32_bf16 v[106:109], v[158:161], v[166:169], v[106:109]
	v_mfma_f32_16x16x32_bf16 v[102:105], v[150:153], v[174:177], v[102:105]
	v_mfma_f32_16x16x32_bf16 v[98:101], v[158:161], v[174:177], v[98:101]
	v_mfma_f32_16x16x32_bf16 v[78:81], v[150:153], v[182:185], v[78:81]
	v_mfma_f32_16x16x32_bf16 v[74:77], v[158:161], v[182:185], v[74:77]
	v_mfma_f32_16x16x32_bf16 v[70:73], v[150:153], v[190:193], v[70:73]
	v_mfma_f32_16x16x32_bf16 v[66:69], v[158:161], v[190:193], v[66:69]
	s_barrier
	s_setprio 0
	s_add_i32 s26, s28, s40
	v_lshl_add_u64 v[194:195], v[232:233], 0, s[64:65]
	s_mov_b32 m0, s26
	ds_read_b128 v[162:165], v249 offset:49152
	ds_read_b128 v[166:169], v249 offset:50176
	ds_read_b128 v[170:173], v249 offset:51200
	ds_read_b128 v[174:177], v249 offset:52224
	ds_read_b128 v[178:181], v249 offset:53248
	ds_read_b128 v[182:185], v249 offset:54272
	ds_read_b128 v[186:189], v249 offset:55296
	ds_read_b128 v[190:193], v249 offset:56320
	global_load_lds_dwordx4 v[194:195], off
	s_add_i32 m0, s26, 0x2000
	s_add_u32 s24, s24, 0x40080
	v_lshl_add_u64 v[194:195], v[230:231], 0, s[64:65]
	s_addc_u32 s25, s25, 0
	s_add_i32 s26, s29, s40
	global_load_lds_dwordx4 v[194:195], off
	v_lshl_add_u64 v[194:195], s[24:25], 0, v[212:213]
	s_mov_b32 m0, s26
	s_nop 0
	global_load_lds_dwordx4 v[194:195], off
	v_lshl_add_u64 v[194:195], s[24:25], 0, v[216:217]
	s_add_i32 m0, s26, 0x2000
	s_nop 0
	global_load_lds_dwordx4 v[194:195], off
	v_lshl_add_u64 v[194:195], v[226:227], 0, s[64:65]
	s_mov_b32 m0, s57
	s_nop 0
	global_load_lds_dwordx4 v[194:195], off
	v_lshl_add_u64 v[194:195], v[228:229], 0, s[64:65]
	s_mov_b32 m0, s62
	s_nop 0
	global_load_lds_dwordx4 v[194:195], off
	s_waitcnt vmcnt(8)
	s_waitcnt lgkmcnt(0)
	s_setprio 1
	s_barrier
	v_mfma_f32_16x16x32_bf16 v[62:65], v[130:133], v[162:165], v[62:65]
	v_mfma_f32_16x16x32_bf16 v[58:61], v[138:141], v[162:165], v[58:61]
	v_mfma_f32_16x16x32_bf16 v[54:57], v[130:133], v[170:173], v[54:57]
	v_mfma_f32_16x16x32_bf16 v[50:53], v[138:141], v[170:173], v[50:53]
	v_mfma_f32_16x16x32_bf16 v[30:33], v[130:133], v[178:181], v[30:33]
	v_mfma_f32_16x16x32_bf16 v[26:29], v[138:141], v[178:181], v[26:29]
	v_mfma_f32_16x16x32_bf16 v[22:25], v[130:133], v[186:189], v[22:25]
	v_mfma_f32_16x16x32_bf16 v[18:21], v[138:141], v[186:189], v[18:21]
	v_mfma_f32_16x16x32_bf16 v[62:65], v[134:137], v[166:169], v[62:65]
	v_mfma_f32_16x16x32_bf16 v[58:61], v[142:145], v[166:169], v[58:61]
	v_mfma_f32_16x16x32_bf16 v[54:57], v[134:137], v[174:177], v[54:57]
	v_mfma_f32_16x16x32_bf16 v[50:53], v[142:145], v[174:177], v[50:53]
	v_mfma_f32_16x16x32_bf16 v[30:33], v[134:137], v[182:185], v[30:33]
	v_mfma_f32_16x16x32_bf16 v[26:29], v[142:145], v[182:185], v[26:29]
	v_mfma_f32_16x16x32_bf16 v[22:25], v[134:137], v[190:193], v[22:25]
	v_mfma_f32_16x16x32_bf16 v[18:21], v[142:145], v[190:193], v[18:21]
	s_setprio 0
	s_setprio 1
	v_mfma_f32_16x16x32_bf16 v[46:49], v[146:149], v[162:165], v[46:49]
	v_mfma_f32_16x16x32_bf16 v[42:45], v[154:157], v[162:165], v[42:45]
	v_mfma_f32_16x16x32_bf16 v[38:41], v[146:149], v[170:173], v[38:41]
	v_mfma_f32_16x16x32_bf16 v[34:37], v[154:157], v[170:173], v[34:37]
	v_mfma_f32_16x16x32_bf16 v[14:17], v[146:149], v[178:181], v[14:17]
	v_mfma_f32_16x16x32_bf16 v[10:13], v[154:157], v[178:181], v[10:13]
	v_mfma_f32_16x16x32_bf16 v[6:9], v[146:149], v[186:189], v[6:9]
	v_mfma_f32_16x16x32_bf16 v[2:5], v[154:157], v[186:189], v[2:5]
	v_mfma_f32_16x16x32_bf16 v[46:49], v[150:153], v[166:169], v[46:49]
	v_mfma_f32_16x16x32_bf16 v[42:45], v[158:161], v[166:169], v[42:45]
	v_mfma_f32_16x16x32_bf16 v[38:41], v[150:153], v[174:177], v[38:41]
	v_mfma_f32_16x16x32_bf16 v[34:37], v[158:161], v[174:177], v[34:37]
	v_mfma_f32_16x16x32_bf16 v[14:17], v[150:153], v[182:185], v[14:17]
	v_mfma_f32_16x16x32_bf16 v[10:13], v[158:161], v[182:185], v[10:13]
	v_mfma_f32_16x16x32_bf16 v[6:9], v[150:153], v[190:193], v[6:9]
	v_mfma_f32_16x16x32_bf16 v[2:5], v[158:161], v[190:193], v[2:5]
	s_barrier
	s_setprio 0
	s_add_i32 s76, s76, 2
	s_add_u32 s22, s22, 0x100
	s_addc_u32 s23, s23, 0
	s_cmp_gt_u32 s76, 13
	s_cbranch_scc1 .LBB0_162

; #define PG8_STAGE(bufoff, gbase, voff) do { _Pragma("unroll") for (int _i = 0; _i < 2; ++_i) \
;         __builtin_amdgcn_global_load_lds((const unsigned*)((const char*)(gbase) + (voff)[_i]), (PG8_LAS unsigned*)(lds + (bufoff) + ldsw + _i * 8192), 16, 0, 0); } while (0)
; #define PG8_LDA(dst, b, h) do { _Pragma("unroll") for (int m = 0; m < 4; ++m) _Pragma("unroll") for (int k = 0; k < 2; ++k) dst[m][k] = *(const PG8_LAS bf16x8*)(lds + PG8_SA(b, h) + aoff + m * 2048 + k * 1024); } while (0)
; #define PG8_LDB(dst, b, h) do { _Pragma("unroll") for (int n = 0; n < 2; ++n) _Pragma("unroll") for (int k = 0; k < 2; ++k) dst[n][k] = *(const PG8_LAS bf16x8*)(lds + PG8_SB(b, h) + boff + n * 2048 + k * 1024); } while (0)
; #define PG8_WAIT_V(n) asm volatile("s_waitcnt vmcnt(" #n ")" ::: "memory")
; #define PG8_WAIT_VN(n) asm volatile("s_waitcnt vmcnt(%0)" :: "n"(n) : "memory")
; #define PG8_WAIT_L(n) asm volatile("s_waitcnt lgkmcnt(" #n ")" ::: "memory")
; template <class Epi, class Sched, bool ALIGN_EPI = false, bool SP2 = false>
; __device__ __forceinline__ void gemm_phase(PG8_LAS unsigned char* lds, const Gemm g, const Sched& S, const Epi& E, const int wave_id) {
;     ...
;         for (int t = 0; t < nt; t += 2) {
;             const bool last = (t == nt - 2);
;             const char* a1 = cA + (size_t)(t + 1) * kstep;
;             const char* a2 = last ? nA : cA + (size_t)(t + 2) * kstep; const char* b2 = last ? nB : cB + (size_t)(t + 2) * kstep;
;             const char* a3 = a2 + kstep; const char* b3 = b2 + kstep;
;             if (last && has_next) S.a_ready(nxt);
;             if constexpr (SP2) {
;             int tz_ = __builtin_amdgcn_readfirstlane(t | (ui > 0 ? 0 : 1)); asm volatile("" : "+s"(tz_));
;             const bool strict = !(Epi::NS > 0 && tz_ == 0);
;             PG8_LDB(B0, 0, 0); PG8_LDB(B1, 0, 1); PG8_SCHED; PG8_LDA(At, 0, 0); PG8_STAGE(PG8_SA(1, 1), a1 + hstep, voffA);
;             PG8_WAIT_VN(8 + Epi::NS); if (strict) PG8_WAIT_V(8); PG8_WAIT_L(0); PG8_BAR; PG8_MMA(0, 0, At, B0); PG8_MMA(0, 1, At, B1); PG8_BAR; PG8_SCHED;
;             PG8_LDA(At, 0, 1); PG8_STAGE(PG8_SB(0, 0), b2, voffB); PG8_STAGE(PG8_SB(0, 1), b2 + hstep, voffB); PG8_STAGE(PG8_SA(0, 0), a2, voffA);
;             PG8_WAIT_VN(8 + Epi::NS); if (strict) PG8_WAIT_V(8); PG8_WAIT_L(0); PG8_BAR; PG8_MMA(1, 0, At, B0); PG8_MMA(1, 1, At, B1); PG8_BAR; PG8_SCHED;
.LBB0_160:
	s_add_u32 s24, s20, s22
	s_addc_u32 s25, s21, s23
	s_add_u32 s24, s24, 0x100
	s_addc_u32 s25, s25, 0
	s_add_u32 s53, s74, s22
	s_addc_u32 s78, s75, s23
	s_cmpk_eq_i32 s22, 0x700
	s_cselect_b32 s27, s13, s25
	s_cselect_b32 s26, s68, s24
	s_cselect_b32 s25, s11, s78
	s_cselect_b32 s24, s69, s53
	s_waitcnt lgkmcnt(0)
	s_setprio 1
	s_barrier
	v_mfma_f32_16x16x32_bf16 v[126:129], v[146:149], v[186:189], v[126:129]
	v_mfma_f32_16x16x32_bf16 v[122:125], v[154:157], v[186:189], v[122:125]
	v_mfma_f32_16x16x32_bf16 v[118:121], v[146:149], v[178:181], v[118:121]
	v_mfma_f32_16x16x32_bf16 v[114:117], v[154:157], v[178:181], v[114:117]
	v_mfma_f32_16x16x32_bf16 v[94:97], v[146:149], v[170:173], v[94:97]
	v_mfma_f32_16x16x32_bf16 v[90:93], v[154:157], v[170:173], v[90:93]
	v_mfma_f32_16x16x32_bf16 v[86:89], v[146:149], v[162:165], v[86:89]
	v_mfma_f32_16x16x32_bf16 v[82:85], v[154:157], v[162:165], v[82:85]
	v_mfma_f32_16x16x32_bf16 v[126:129], v[150:153], v[190:193], v[126:129]
	v_mfma_f32_16x16x32_bf16 v[122:125], v[158:161], v[190:193], v[122:125]
	v_mfma_f32_16x16x32_bf16 v[118:121], v[150:153], v[182:185], v[118:121]
	v_mfma_f32_16x16x32_bf16 v[114:117], v[158:161], v[182:185], v[114:117]
	v_mfma_f32_16x16x32_bf16 v[94:97], v[150:153], v[174:177], v[94:97]
	v_mfma_f32_16x16x32_bf16 v[90:93], v[158:161], v[174:177], v[90:93]
	v_mfma_f32_16x16x32_bf16 v[86:89], v[150:153], v[166:169], v[86:89]
	v_mfma_f32_16x16x32_bf16 v[82:85], v[158:161], v[166:169], v[82:85]
	s_setprio 0
	s_setprio 1
	v_mfma_f32_16x16x32_bf16 v[110:113], v[130:133], v[186:189], v[110:113]
	v_mfma_f32_16x16x32_bf16 v[106:109], v[138:141], v[186:189], v[106:109]
	v_mfma_f32_16x16x32_bf16 v[102:105], v[130:133], v[178:181], v[102:105]
	v_mfma_f32_16x16x32_bf16 v[98:101], v[138:141], v[178:181], v[98:101]
	v_mfma_f32_16x16x32_bf16 v[78:81], v[130:133], v[170:173], v[78:81]
	v_mfma_f32_16x16x32_bf16 v[74:77], v[138:141], v[170:173], v[74:77]
	v_mfma_f32_16x16x32_bf16 v[70:73], v[130:133], v[162:165], v[70:73]
	v_mfma_f32_16x16x32_bf16 v[66:69], v[138:141], v[162:165], v[66:69]
	v_mfma_f32_16x16x32_bf16 v[110:113], v[134:137], v[190:193], v[110:113]
	v_mfma_f32_16x16x32_bf16 v[106:109], v[142:145], v[190:193], v[106:109]
	v_mfma_f32_16x16x32_bf16 v[102:105], v[134:137], v[182:185], v[102:105]
	v_mfma_f32_16x16x32_bf16 v[98:101], v[142:145], v[182:185], v[98:101]
	v_mfma_f32_16x16x32_bf16 v[78:81], v[134:137], v[174:177], v[78:81]
	v_mfma_f32_16x16x32_bf16 v[74:77], v[142:145], v[174:177], v[74:77]
	v_mfma_f32_16x16x32_bf16 v[70:73], v[134:137], v[166:169], v[70:73]
	v_mfma_f32_16x16x32_bf16 v[66:69], v[142:145], v[166:169], v[66:69]
	s_barrier
	s_setprio 0
	s_mov_b32 m0, s42
	v_lshl_add_u64 v[232:233], s[24:25], 0, v[212:213]
	s_add_u32 s90, s24, 0x40000
	ds_read_b128 v[186:189], v249 offset:16384
	ds_read_b128 v[190:193], v249 offset:17408
	ds_read_b128 v[178:181], v249 offset:18432
	ds_read_b128 v[182:185], v249 offset:19456
	ds_read_b128 v[170:173], v249 offset:20480
	ds_read_b128 v[174:177], v249 offset:21504
	ds_read_b128 v[162:165], v249 offset:22528
	ds_read_b128 v[166:169], v249 offset:23552
	global_load_lds_dwordx4 v[232:233], off
	v_lshl_add_u64 v[230:231], s[24:25], 0, v[216:217]
	s_mov_b32 m0, s43
	s_addc_u32 s91, s25, 0
	global_load_lds_dwordx4 v[230:231], off
	v_lshl_add_u64 v[194:195], s[90:91], 0, v[212:213]
	s_mov_b32 m0, s49
	v_lshl_add_u64 v[226:227], s[26:27], 0, v[210:211]
	global_load_lds_dwordx4 v[194:195], off
	v_lshl_add_u64 v[194:195], s[90:91], 0, v[216:217]
	s_mov_b32 m0, s50
	v_lshl_add_u64 v[228:229], s[26:27], 0, v[214:215]
	global_load_lds_dwordx4 v[194:195], off
	s_mov_b32 m0, s41
	s_andn2_b64 vcc, exec, s[28:29]
	global_load_lds_dwordx4 v[226:227], off
	s_mov_b32 m0, s51
	s_nop 0
	global_load_lds_dwordx4 v[228:229], off
	s_waitcnt vmcnt(16)
	s_cbranch_vccnz .LBB0_157
	s_waitcnt vmcnt(8)
	s_branch .LBB0_157

; #define PG8_STAGE(bufoff, gbase, voff) do { _Pragma("unroll") for (int _i = 0; _i < 2; ++_i) \
;         __builtin_amdgcn_global_load_lds((const unsigned*)((const char*)(gbase) + (voff)[_i]), (PG8_LAS unsigned*)(lds + (bufoff) + ldsw + _i * 8192), 16, 0, 0); } while (0)
; #define PG8_LDA(dst, b, h) do { _Pragma("unroll") for (int m = 0; m < 4; ++m) _Pragma("unroll") for (int k = 0; k < 2; ++k) dst[m][k] = *(const PG8_LAS bf16x8*)(lds + PG8_SA(b, h) + aoff + m * 2048 + k * 1024); } while (0)
; #define PG8_LDB(dst, b, h) do { _Pragma("unroll") for (int n = 0; n < 2; ++n) _Pragma("unroll") for (int k = 0; k < 2; ++k) dst[n][k] = *(const PG8_LAS bf16x8*)(lds + PG8_SB(b, h) + boff + n * 2048 + k * 1024); } while (0)
; #define PG8_MMA(ai, bj, At, Bt) do { __builtin_amdgcn_s_setprio(1); _Pragma("unroll") for (int m = 0; m < 4; ++m) _Pragma("unroll") for (int n = 0; n < 2; ++n) _Pragma("unroll") for (int k = 0; k < 2; ++k) \
;         acc[ai][bj][m][n] = __builtin_amdgcn_mfma_f32_16x16x32_bf16(Bt[n][k], At[m][k], acc[ai][bj][m][n], 0, 0, 0); __builtin_amdgcn_s_setprio(0); } while (0)
; #define PG8_WAIT_V(n) asm volatile("s_waitcnt vmcnt(" #n ")" ::: "memory")
; #define PG8_WAIT_VN(n) asm volatile("s_waitcnt vmcnt(%0)" :: "n"(n) : "memory")
; #define PG8_WAIT_L(n) asm volatile("s_waitcnt lgkmcnt(" #n ")" ::: "memory")
; template <class Epi, class Sched, bool ALIGN_EPI = false, bool SP2 = false>
; __device__ __forceinline__ void gemm_phase(PG8_LAS unsigned char* lds, const Gemm g, const Sched& S, const Epi& E, const int wave_id) {
;     ...
;             PG8_LDB(B0, 0, 0); PG8_LDB(B1, 0, 1); PG8_SCHED; PG8_LDA(At, 0, 0); PG8_STAGE(PG8_SA(1, 1), a1 + hstep, voffA);
;             PG8_WAIT_VN(8 + Epi::NS); if (strict) PG8_WAIT_V(8); PG8_WAIT_L(0); PG8_BAR; PG8_MMA(0, 0, At, B0); PG8_MMA(0, 1, At, B1); PG8_BAR; PG8_SCHED;
;             PG8_LDA(At, 0, 1); PG8_STAGE(PG8_SB(0, 0), b2, voffB); PG8_STAGE(PG8_SB(0, 1), b2 + hstep, voffB); PG8_STAGE(PG8_SA(0, 0), a2, voffA);
;             PG8_WAIT_VN(8 + Epi::NS); if (strict) PG8_WAIT_V(8); PG8_WAIT_L(0); PG8_BAR; PG8_MMA(1, 0, At, B0); PG8_MMA(1, 1, At, B1); PG8_BAR; PG8_SCHED;
;             PG8_LDB(B0, 1, 0); PG8_LDB(B1, 1, 1); PG8_SCHED; PG8_LDA(At, 1, 0); PG8_STAGE(PG8_SA(0, 1), a2 + hstep, voffA);
;             PG8_WAIT_V(8); PG8_WAIT_L(0); PG8_BAR; PG8_MMA(0, 0, At, B0); PG8_MMA(0, 1, At, B1); PG8_BAR; PG8_SCHED;
.LBB0_235:
	s_waitcnt lgkmcnt(0)
	s_setprio 1
	s_barrier
	v_mfma_f32_16x16x32_bf16 v[62:65], v[146:149], v[186:189], v[62:65]
	v_mfma_f32_16x16x32_bf16 v[58:61], v[154:157], v[186:189], v[58:61]
	v_mfma_f32_16x16x32_bf16 v[46:49], v[146:149], v[178:181], v[46:49]
	v_mfma_f32_16x16x32_bf16 v[42:45], v[154:157], v[178:181], v[42:45]
	v_mfma_f32_16x16x32_bf16 v[30:33], v[146:149], v[170:173], v[30:33]
	v_mfma_f32_16x16x32_bf16 v[26:29], v[154:157], v[170:173], v[26:29]
	v_mfma_f32_16x16x32_bf16 v[14:17], v[146:149], v[162:165], v[14:17]
	v_mfma_f32_16x16x32_bf16 v[10:13], v[154:157], v[162:165], v[10:13]
	v_mfma_f32_16x16x32_bf16 v[62:65], v[150:153], v[190:193], v[62:65]
	v_mfma_f32_16x16x32_bf16 v[58:61], v[158:161], v[190:193], v[58:61]
	v_mfma_f32_16x16x32_bf16 v[46:49], v[150:153], v[182:185], v[46:49]
	v_mfma_f32_16x16x32_bf16 v[42:45], v[158:161], v[182:185], v[42:45]
	v_mfma_f32_16x16x32_bf16 v[30:33], v[150:153], v[174:177], v[30:33]
	v_mfma_f32_16x16x32_bf16 v[26:29], v[158:161], v[174:177], v[26:29]
	v_mfma_f32_16x16x32_bf16 v[14:17], v[150:153], v[166:169], v[14:17]
	v_mfma_f32_16x16x32_bf16 v[10:13], v[158:161], v[166:169], v[10:13]
	s_setprio 0
	s_setprio 1
	v_mfma_f32_16x16x32_bf16 v[54:57], v[130:133], v[186:189], v[54:57]
	v_mfma_f32_16x16x32_bf16 v[50:53], v[138:141], v[186:189], v[50:53]
	v_mfma_f32_16x16x32_bf16 v[38:41], v[130:133], v[178:181], v[38:41]
	v_mfma_f32_16x16x32_bf16 v[34:37], v[138:141], v[178:181], v[34:37]
	v_mfma_f32_16x16x32_bf16 v[22:25], v[130:133], v[170:173], v[22:25]
	v_mfma_f32_16x16x32_bf16 v[18:21], v[138:141], v[170:173], v[18:21]
	v_mfma_f32_16x16x32_bf16 v[6:9], v[130:133], v[162:165], v[6:9]
	v_mfma_f32_16x16x32_bf16 v[2:5], v[138:141], v[162:165], v[2:5]
	v_mfma_f32_16x16x32_bf16 v[54:57], v[134:137], v[190:193], v[54:57]
	v_mfma_f32_16x16x32_bf16 v[50:53], v[142:145], v[190:193], v[50:53]
	v_mfma_f32_16x16x32_bf16 v[38:41], v[134:137], v[182:185], v[38:41]
	v_mfma_f32_16x16x32_bf16 v[34:37], v[142:145], v[182:185], v[34:37]
	v_mfma_f32_16x16x32_bf16 v[22:25], v[134:137], v[174:177], v[22:25]
	v_mfma_f32_16x16x32_bf16 v[18:21], v[142:145], v[174:177], v[18:21]
	v_mfma_f32_16x16x32_bf16 v[6:9], v[134:137], v[166:169], v[6:9]
	v_mfma_f32_16x16x32_bf16 v[2:5], v[142:145], v[166:169], v[2:5]
	s_barrier
	s_setprio 0
	s_add_i32 s20, 0, 0x18000
	s_add_i32 s21, 0, 0x1c000
	v_add_u32_e32 v142, s20, v246
	v_add_u32_e32 v158, s21, v246
	ds_read_b128 v[130:133], v142
	ds_read_b128 v[134:137], v142 offset:1024
	ds_read_b128 v[138:141], v142 offset:2048
	ds_read_b128 v[142:145], v142 offset:3072
	ds_read_b128 v[146:149], v158
	ds_read_b128 v[150:153], v158 offset:1024
	ds_read_b128 v[154:157], v158 offset:2048
	ds_read_b128 v[158:161], v158 offset:3072
	s_add_u32 s18, s18, 0xb0000
	s_addc_u32 s19, s19, 0
	s_mov_b32 m0, s39
	v_lshl_add_u64 v[194:195], s[18:19], 0, v[210:211]
	ds_read_b128 v[162:165], v247 offset:32768
	ds_read_b128 v[166:169], v247 offset:33792
	ds_read_b128 v[170:173], v247 offset:34816
	ds_read_b128 v[174:177], v247 offset:35840
	ds_read_b128 v[178:181], v247 offset:36864
	ds_read_b128 v[182:185], v247 offset:37888
	ds_read_b128 v[186:189], v247 offset:38912
	ds_read_b128 v[190:193], v247 offset:39936
	global_load_lds_dwordx4 v[194:195], off
	v_lshl_add_u64 v[194:195], s[18:19], 0, v[214:215]
	s_mov_b32 m0, s40
	s_nop 0
	global_load_lds_dwordx4 v[194:195], off
	s_waitcnt vmcnt(26)
	s_cmp_eq_u32 s100, 0
	s_cbranch_scc1 .Lthird_wait_relaxed_5
	s_waitcnt vmcnt(8)
; #define PG8_STAGE(bufoff, gbase, voff) do { _Pragma("unroll") for (int _i = 0; _i < 2; ++_i) \
;         __builtin_amdgcn_global_load_lds((const unsigned*)((const char*)(gbase) + (voff)[_i]), (PG8_LAS unsigned*)(lds + (bufoff) + ldsw + _i * 8192), 16, 0, 0); } while (0)
; #define PG8_WAIT_V(n) asm volatile("s_waitcnt vmcnt(" #n ")" ::: "memory")
; #define PG8_WAIT_VN(n) asm volatile("s_waitcnt vmcnt(%0)" :: "n"(n) : "memory")
; template <class Epi, class Sched, bool ALIGN_EPI = false, bool SP2 = false>
; __device__ __forceinline__ void gemm_phase(PG8_LAS unsigned char* lds, const Gemm g, const Sched& S, const Epi& E, const int wave_id) {
;     ...
;         for (int t = 0; t < nt; t += 2) {
;             const bool last = (t == nt - 2);
;             const char* a1 = cA + (size_t)(t + 1) * kstep;
;             const char* a2 = last ? nA : cA + (size_t)(t + 2) * kstep; const char* b2 = last ? nB : cB + (size_t)(t + 2) * kstep;
;             const char* a3 = a2 + kstep; const char* b3 = b2 + kstep;
;             if (last && has_next) S.a_ready(nxt);
;             if constexpr (SP2) {
;             int tz_ = __builtin_amdgcn_readfirstlane(t | (ui > 0 ? 0 : 1)); asm volatile("" : "+s"(tz_));
;             const bool strict = !(Epi::NS > 0 && tz_ == 0);
;             PG8_LDB(B0, 0, 0); PG8_LDB(B1, 0, 1); PG8_SCHED; PG8_LDA(At, 0, 0); PG8_STAGE(PG8_SA(1, 1), a1 + hstep, voffA);
;             PG8_WAIT_VN(8 + Epi::NS); if (strict) PG8_WAIT_V(8); PG8_WAIT_L(0); PG8_BAR; PG8_MMA(0, 0, At, B0); PG8_MMA(0, 1, At, B1); PG8_BAR; PG8_SCHED;
;             PG8_LDA(At, 0, 1); PG8_STAGE(PG8_SB(0, 0), b2, voffB); PG8_STAGE(PG8_SB(0, 1), b2 + hstep, voffB); PG8_STAGE(PG8_SA(0, 0), a2, voffA);
;             PG8_WAIT_VN(8 + Epi::NS); if (strict) PG8_WAIT_V(8); PG8_WAIT_L(0); PG8_BAR; PG8_MMA(1, 0, At, B0); PG8_MMA(1, 1, At, B1); PG8_BAR; PG8_SCHED;
;             PG8_LDB(B0, 1, 0); PG8_LDB(B1, 1, 1); PG8_SCHED; PG8_LDA(At, 1, 0); PG8_STAGE(PG8_SA(0, 1), a2 + hstep, voffA);
;             PG8_WAIT_V(8); PG8_WAIT_L(0); PG8_BAR; PG8_MMA(0, 0, At, B0); PG8_MMA(0, 1, At, B1); PG8_BAR; PG8_SCHED;
;             PG8_LDA(At, 1, 1); PG8_STAGE(PG8_SB(1, 0), b3, voffB); PG8_STAGE(PG8_SB(1, 1), b3 + hstep, voffB); PG8_STAGE(PG8_SA(1, 0), a3, voffA);
;             PG8_WAIT_V(8); PG8_WAIT_L(0); PG8_BAR; PG8_MMA(1, 0, At, B0); PG8_MMA(1, 1, At, B1); PG8_BAR; PG8_SCHED;
.Lthird_wait_relaxed_5:
	s_waitcnt lgkmcnt(0)
	s_setprio 1
	s_barrier
	v_mfma_f32_16x16x32_bf16 v[126:129], v[130:133], v[162:165], v[126:129]
	v_mfma_f32_16x16x32_bf16 v[122:125], v[138:141], v[162:165], v[122:125]
	v_mfma_f32_16x16x32_bf16 v[110:113], v[130:133], v[170:173], v[110:113]
	v_mfma_f32_16x16x32_bf16 v[106:109], v[138:141], v[170:173], v[106:109]
	v_mfma_f32_16x16x32_bf16 v[94:97], v[130:133], v[178:181], v[94:97]
	v_mfma_f32_16x16x32_bf16 v[90:93], v[138:141], v[178:181], v[90:93]
	v_mfma_f32_16x16x32_bf16 v[78:81], v[130:133], v[186:189], v[78:81]
	v_mfma_f32_16x16x32_bf16 v[74:77], v[138:141], v[186:189], v[74:77]
	v_mfma_f32_16x16x32_bf16 v[126:129], v[134:137], v[166:169], v[126:129]
	v_mfma_f32_16x16x32_bf16 v[122:125], v[142:145], v[166:169], v[122:125]
	v_mfma_f32_16x16x32_bf16 v[110:113], v[134:137], v[174:177], v[110:113]
	v_mfma_f32_16x16x32_bf16 v[106:109], v[142:145], v[174:177], v[106:109]
	v_mfma_f32_16x16x32_bf16 v[94:97], v[134:137], v[182:185], v[94:97]
	v_mfma_f32_16x16x32_bf16 v[90:93], v[142:145], v[182:185], v[90:93]
	v_mfma_f32_16x16x32_bf16 v[78:81], v[134:137], v[190:193], v[78:81]
	v_mfma_f32_16x16x32_bf16 v[74:77], v[142:145], v[190:193], v[74:77]
	s_setprio 0
	s_setprio 1
	v_mfma_f32_16x16x32_bf16 v[118:121], v[146:149], v[162:165], v[118:121]
	v_mfma_f32_16x16x32_bf16 v[114:117], v[154:157], v[162:165], v[114:117]
	v_mfma_f32_16x16x32_bf16 v[102:105], v[146:149], v[170:173], v[102:105]
	v_mfma_f32_16x16x32_bf16 v[98:101], v[154:157], v[170:173], v[98:101]
	v_mfma_f32_16x16x32_bf16 v[86:89], v[146:149], v[178:181], v[86:89]
	v_mfma_f32_16x16x32_bf16 v[82:85], v[154:157], v[178:181], v[82:85]
	v_mfma_f32_16x16x32_bf16 v[70:73], v[146:149], v[186:189], v[70:73]
	v_mfma_f32_16x16x32_bf16 v[66:69], v[154:157], v[186:189], v[66:69]
	v_mfma_f32_16x16x32_bf16 v[118:121], v[150:153], v[166:169], v[118:121]
	v_mfma_f32_16x16x32_bf16 v[114:117], v[158:161], v[166:169], v[114:117]
	v_mfma_f32_16x16x32_bf16 v[102:105], v[150:153], v[174:177], v[102:105]
	v_mfma_f32_16x16x32_bf16 v[98:101], v[158:161], v[174:177], v[98:101]
	v_mfma_f32_16x16x32_bf16 v[86:89], v[150:153], v[182:185], v[86:89]
	v_mfma_f32_16x16x32_bf16 v[82:85], v[158:161], v[182:185], v[82:85]
	v_mfma_f32_16x16x32_bf16 v[70:73], v[150:153], v[190:193], v[70:73]
	v_mfma_f32_16x16x32_bf16 v[66:69], v[158:161], v[190:193], v[66:69]
	s_barrier
	s_setprio 0
	s_add_i32 s18, s20, s30
	v_lshl_add_u64 v[194:195], v[232:233], 0, s[64:65]
	s_mov_b32 m0, s18
	ds_read_b128 v[162:165], v247 offset:49152
	ds_read_b128 v[166:169], v247 offset:50176
	ds_read_b128 v[170:173], v247 offset:51200
	ds_read_b128 v[174:177], v247 offset:52224
	ds_read_b128 v[178:181], v247 offset:53248
	ds_read_b128 v[182:185], v247 offset:54272
	ds_read_b128 v[186:189], v247 offset:55296
	ds_read_b128 v[190:193], v247 offset:56320
	global_load_lds_dwordx4 v[194:195], off
	s_add_i32 m0, s18, 0x2000
	s_add_u32 s16, s16, 0xb0080
	v_lshl_add_u64 v[194:195], v[230:231], 0, s[64:65]
	s_addc_u32 s17, s17, 0
	s_add_i32 s18, s21, s30
	global_load_lds_dwordx4 v[194:195], off
	v_lshl_add_u64 v[194:195], s[16:17], 0, v[212:213]
	s_mov_b32 m0, s18
	s_nop 0
	global_load_lds_dwordx4 v[194:195], off
	v_lshl_add_u64 v[194:195], s[16:17], 0, v[216:217]
	s_add_i32 m0, s18, 0x2000
	s_nop 0
	global_load_lds_dwordx4 v[194:195], off
	v_lshl_add_u64 v[194:195], v[226:227], 0, s[64:65]
	s_mov_b32 m0, s42
	s_nop 0
	global_load_lds_dwordx4 v[194:195], off
	v_lshl_add_u64 v[194:195], v[228:229], 0, s[64:65]
	s_mov_b32 m0, s43
	s_nop 0
	global_load_lds_dwordx4 v[194:195], off
	s_waitcnt vmcnt(8)
	s_waitcnt lgkmcnt(0)
	s_setprio 1
	s_barrier
	v_mfma_f32_16x16x32_bf16 v[62:65], v[130:133], v[162:165], v[62:65]
	v_mfma_f32_16x16x32_bf16 v[58:61], v[138:141], v[162:165], v[58:61]
	v_mfma_f32_16x16x32_bf16 v[46:49], v[130:133], v[170:173], v[46:49]
	v_mfma_f32_16x16x32_bf16 v[42:45], v[138:141], v[170:173], v[42:45]
	v_mfma_f32_16x16x32_bf16 v[30:33], v[130:133], v[178:181], v[30:33]
	v_mfma_f32_16x16x32_bf16 v[26:29], v[138:141], v[178:181], v[26:29]
	v_mfma_f32_16x16x32_bf16 v[14:17], v[130:133], v[186:189], v[14:17]
	v_mfma_f32_16x16x32_bf16 v[10:13], v[138:141], v[186:189], v[10:13]
	v_mfma_f32_16x16x32_bf16 v[62:65], v[134:137], v[166:169], v[62:65]
	v_mfma_f32_16x16x32_bf16 v[58:61], v[142:145], v[166:169], v[58:61]
	v_mfma_f32_16x16x32_bf16 v[46:49], v[134:137], v[174:177], v[46:49]
	v_mfma_f32_16x16x32_bf16 v[42:45], v[142:145], v[174:177], v[42:45]
	v_mfma_f32_16x16x32_bf16 v[30:33], v[134:137], v[182:185], v[30:33]
	v_mfma_f32_16x16x32_bf16 v[26:29], v[142:145], v[182:185], v[26:29]
	v_mfma_f32_16x16x32_bf16 v[14:17], v[134:137], v[190:193], v[14:17]
	v_mfma_f32_16x16x32_bf16 v[10:13], v[142:145], v[190:193], v[10:13]
	s_setprio 0
	s_setprio 1
	v_mfma_f32_16x16x32_bf16 v[54:57], v[146:149], v[162:165], v[54:57]
	v_mfma_f32_16x16x32_bf16 v[50:53], v[154:157], v[162:165], v[50:53]
	v_mfma_f32_16x16x32_bf16 v[38:41], v[146:149], v[170:173], v[38:41]
	v_mfma_f32_16x16x32_bf16 v[34:37], v[154:157], v[170:173], v[34:37]
	v_mfma_f32_16x16x32_bf16 v[22:25], v[146:149], v[178:181], v[22:25]
	v_mfma_f32_16x16x32_bf16 v[18:21], v[154:157], v[178:181], v[18:21]
	v_mfma_f32_16x16x32_bf16 v[6:9], v[146:149], v[186:189], v[6:9]
	v_mfma_f32_16x16x32_bf16 v[2:5], v[154:157], v[186:189], v[2:5]
	v_mfma_f32_16x16x32_bf16 v[54:57], v[150:153], v[166:169], v[54:57]
	v_mfma_f32_16x16x32_bf16 v[50:53], v[158:161], v[166:169], v[50:53]
	v_mfma_f32_16x16x32_bf16 v[38:41], v[150:153], v[174:177], v[38:41]
	v_mfma_f32_16x16x32_bf16 v[34:37], v[158:161], v[174:177], v[34:37]
	v_mfma_f32_16x16x32_bf16 v[22:25], v[150:153], v[182:185], v[22:25]
	v_mfma_f32_16x16x32_bf16 v[18:21], v[158:161], v[182:185], v[18:21]
	v_mfma_f32_16x16x32_bf16 v[6:9], v[150:153], v[190:193], v[6:9]
	v_mfma_f32_16x16x32_bf16 v[2:5], v[158:161], v[190:193], v[2:5]
	s_barrier
	s_setprio 0
	s_add_i32 s63, s63, 2
	s_add_u32 s14, s14, 0x100
	s_addc_u32 s15, s15, 0
	s_cmp_gt_u32 s63, 41
	s_cbranch_scc1 .LBB0_240

; #define PG8_STAGE(bufoff, gbase, voff) do { _Pragma("unroll") for (int _i = 0; _i < 2; ++_i) \
;         __builtin_amdgcn_global_load_lds((const unsigned*)((const char*)(gbase) + (voff)[_i]), (PG8_LAS unsigned*)(lds + (bufoff) + ldsw + _i * 8192), 16, 0, 0); } while (0)
; #define PG8_LDA(dst, b, h) do { _Pragma("unroll") for (int m = 0; m < 4; ++m) _Pragma("unroll") for (int k = 0; k < 2; ++k) dst[m][k] = *(const PG8_LAS bf16x8*)(lds + PG8_SA(b, h) + aoff + m * 2048 + k * 1024); } while (0)
; #define PG8_LDB(dst, b, h) do { _Pragma("unroll") for (int n = 0; n < 2; ++n) _Pragma("unroll") for (int k = 0; k < 2; ++k) dst[n][k] = *(const PG8_LAS bf16x8*)(lds + PG8_SB(b, h) + boff + n * 2048 + k * 1024); } while (0)
; #define PG8_WAIT_V(n) asm volatile("s_waitcnt vmcnt(" #n ")" ::: "memory")
; #define PG8_WAIT_VN(n) asm volatile("s_waitcnt vmcnt(%0)" :: "n"(n) : "memory")
; #define PG8_WAIT_L(n) asm volatile("s_waitcnt lgkmcnt(" #n ")" ::: "memory")
; template <class Epi, class Sched, bool ALIGN_EPI = false, bool SP2 = false>
; __device__ __forceinline__ void gemm_phase(PG8_LAS unsigned char* lds, const Gemm g, const Sched& S, const Epi& E, const int wave_id) {
;     ...
;         for (int t = 0; t < nt; t += 2) {
;             const bool last = (t == nt - 2);
;             const char* a1 = cA + (size_t)(t + 1) * kstep;
;             const char* a2 = last ? nA : cA + (size_t)(t + 2) * kstep; const char* b2 = last ? nB : cB + (size_t)(t + 2) * kstep;
;             const char* a3 = a2 + kstep; const char* b3 = b2 + kstep;
;             if (last && has_next) S.a_ready(nxt);
;             if constexpr (SP2) {
;             int tz_ = __builtin_amdgcn_readfirstlane(t | (ui > 0 ? 0 : 1)); asm volatile("" : "+s"(tz_));
;             const bool strict = !(Epi::NS > 0 && tz_ == 0);
;             PG8_LDB(B0, 0, 0); PG8_LDB(B1, 0, 1); PG8_SCHED; PG8_LDA(At, 0, 0); PG8_STAGE(PG8_SA(1, 1), a1 + hstep, voffA);
;             PG8_WAIT_VN(8 + Epi::NS); if (strict) PG8_WAIT_V(8); PG8_WAIT_L(0); PG8_BAR; PG8_MMA(0, 0, At, B0); PG8_MMA(0, 1, At, B1); PG8_BAR; PG8_SCHED;
;             PG8_LDA(At, 0, 1); PG8_STAGE(PG8_SB(0, 0), b2, voffB); PG8_STAGE(PG8_SB(0, 1), b2 + hstep, voffB); PG8_STAGE(PG8_SA(0, 0), a2, voffA);
;             PG8_WAIT_VN(8 + Epi::NS); if (strict) PG8_WAIT_V(8); PG8_WAIT_L(0); PG8_BAR; PG8_MMA(1, 0, At, B0); PG8_MMA(1, 1, At, B1); PG8_BAR; PG8_SCHED;
.LBB0_238:
	s_add_u32 s16, s12, s14
	s_addc_u32 s17, s13, s15
	s_add_u32 s16, s16, 0x100
	s_addc_u32 s17, s17, 0
	s_add_u32 s53, s57, s14
	s_addc_u32 s67, s62, s15
	s_cmpk_eq_i32 s14, 0x1500
	s_cselect_b32 s19, s7, s17
	s_cselect_b32 s18, s6, s16
	s_cselect_b32 s17, s11, s67
	s_cselect_b32 s16, s10, s53
	s_waitcnt lgkmcnt(0)
	s_setprio 1
	s_barrier
	v_mfma_f32_16x16x32_bf16 v[126:129], v[146:149], v[186:189], v[126:129]
	v_mfma_f32_16x16x32_bf16 v[122:125], v[154:157], v[186:189], v[122:125]
	v_mfma_f32_16x16x32_bf16 v[110:113], v[146:149], v[178:181], v[110:113]
	v_mfma_f32_16x16x32_bf16 v[106:109], v[154:157], v[178:181], v[106:109]
	v_mfma_f32_16x16x32_bf16 v[94:97], v[146:149], v[170:173], v[94:97]
	v_mfma_f32_16x16x32_bf16 v[90:93], v[154:157], v[170:173], v[90:93]
	v_mfma_f32_16x16x32_bf16 v[78:81], v[146:149], v[162:165], v[78:81]
	v_mfma_f32_16x16x32_bf16 v[74:77], v[154:157], v[162:165], v[74:77]
	v_mfma_f32_16x16x32_bf16 v[126:129], v[150:153], v[190:193], v[126:129]
	v_mfma_f32_16x16x32_bf16 v[122:125], v[158:161], v[190:193], v[122:125]
	v_mfma_f32_16x16x32_bf16 v[110:113], v[150:153], v[182:185], v[110:113]
	v_mfma_f32_16x16x32_bf16 v[106:109], v[158:161], v[182:185], v[106:109]
	v_mfma_f32_16x16x32_bf16 v[94:97], v[150:153], v[174:177], v[94:97]
	v_mfma_f32_16x16x32_bf16 v[90:93], v[158:161], v[174:177], v[90:93]
	v_mfma_f32_16x16x32_bf16 v[78:81], v[150:153], v[166:169], v[78:81]
	v_mfma_f32_16x16x32_bf16 v[74:77], v[158:161], v[166:169], v[74:77]
	s_setprio 0
	s_setprio 1
	v_mfma_f32_16x16x32_bf16 v[118:121], v[130:133], v[186:189], v[118:121]
	v_mfma_f32_16x16x32_bf16 v[114:117], v[138:141], v[186:189], v[114:117]
	v_mfma_f32_16x16x32_bf16 v[102:105], v[130:133], v[178:181], v[102:105]
	v_mfma_f32_16x16x32_bf16 v[98:101], v[138:141], v[178:181], v[98:101]
	v_mfma_f32_16x16x32_bf16 v[86:89], v[130:133], v[170:173], v[86:89]
	v_mfma_f32_16x16x32_bf16 v[82:85], v[138:141], v[170:173], v[82:85]
	v_mfma_f32_16x16x32_bf16 v[70:73], v[130:133], v[162:165], v[70:73]
	v_mfma_f32_16x16x32_bf16 v[66:69], v[138:141], v[162:165], v[66:69]
	v_mfma_f32_16x16x32_bf16 v[118:121], v[134:137], v[190:193], v[118:121]
	v_mfma_f32_16x16x32_bf16 v[114:117], v[142:145], v[190:193], v[114:117]
	v_mfma_f32_16x16x32_bf16 v[102:105], v[134:137], v[182:185], v[102:105]
	v_mfma_f32_16x16x32_bf16 v[98:101], v[142:145], v[182:185], v[98:101]
	v_mfma_f32_16x16x32_bf16 v[86:89], v[134:137], v[174:177], v[86:89]
	v_mfma_f32_16x16x32_bf16 v[82:85], v[142:145], v[174:177], v[82:85]
	v_mfma_f32_16x16x32_bf16 v[70:73], v[134:137], v[166:169], v[70:73]
	v_mfma_f32_16x16x32_bf16 v[66:69], v[142:145], v[166:169], v[66:69]
	s_barrier
	s_setprio 0
	s_mov_b32 m0, s34
	v_lshl_add_u64 v[232:233], s[16:17], 0, v[212:213]
	s_add_u32 s68, s16, 0xb0000
	ds_read_b128 v[186:189], v247 offset:16384
	ds_read_b128 v[190:193], v247 offset:17408
	ds_read_b128 v[178:181], v247 offset:18432
	ds_read_b128 v[182:185], v247 offset:19456
	ds_read_b128 v[170:173], v247 offset:20480
	ds_read_b128 v[174:177], v247 offset:21504
	ds_read_b128 v[162:165], v247 offset:22528
	ds_read_b128 v[166:169], v247 offset:23552
	global_load_lds_dwordx4 v[232:233], off
	v_lshl_add_u64 v[230:231], s[16:17], 0, v[216:217]
	s_mov_b32 m0, s35
	s_addc_u32 s69, s17, 0
	global_load_lds_dwordx4 v[230:231], off
	v_lshl_add_u64 v[194:195], s[68:69], 0, v[212:213]
	s_mov_b32 m0, s36
	v_lshl_add_u64 v[226:227], s[18:19], 0, v[210:211]
	global_load_lds_dwordx4 v[194:195], off
	v_lshl_add_u64 v[194:195], s[68:69], 0, v[216:217]
	s_mov_b32 m0, s37
	v_lshl_add_u64 v[228:229], s[18:19], 0, v[214:215]
	global_load_lds_dwordx4 v[194:195], off
	s_mov_b32 m0, s31
	s_andn2_b64 vcc, exec, s[20:21]
	global_load_lds_dwordx4 v[226:227], off
	s_mov_b32 m0, s38
	s_nop 0
	global_load_lds_dwordx4 v[228:229], off
	s_waitcnt vmcnt(24)
	s_cbranch_vccnz .LBB0_235
	s_waitcnt vmcnt(8)
	s_branch .LBB0_235

; #define PG8_STAGE(bufoff, gbase, voff) do { _Pragma("unroll") for (int _i = 0; _i < 2; ++_i) \
;         __builtin_amdgcn_global_load_lds((const unsigned*)((const char*)(gbase) + (voff)[_i]), (PG8_LAS unsigned*)(lds + (bufoff) + ldsw + _i * 8192), 16, 0, 0); } while (0)
; #define PG8_LDA(dst, b, h) do { _Pragma("unroll") for (int m = 0; m < 4; ++m) _Pragma("unroll") for (int k = 0; k < 2; ++k) dst[m][k] = *(const PG8_LAS bf16x8*)(lds + PG8_SA(b, h) + aoff + m * 2048 + k * 1024); } while (0)
; #define PG8_LDB(dst, b, h) do { _Pragma("unroll") for (int n = 0; n < 2; ++n) _Pragma("unroll") for (int k = 0; k < 2; ++k) dst[n][k] = *(const PG8_LAS bf16x8*)(lds + PG8_SB(b, h) + boff + n * 2048 + k * 1024); } while (0)
; #define PG8_MMA(ai, bj, At, Bt) do { __builtin_amdgcn_s_setprio(1); _Pragma("unroll") for (int m = 0; m < 4; ++m) _Pragma("unroll") for (int n = 0; n < 2; ++n) _Pragma("unroll") for (int k = 0; k < 2; ++k) \
;         acc[ai][bj][m][n] = __builtin_amdgcn_mfma_f32_16x16x32_bf16(Bt[n][k], At[m][k], acc[ai][bj][m][n], 0, 0, 0); __builtin_amdgcn_s_setprio(0); } while (0)
; #define PG8_WAIT_V(n) asm volatile("s_waitcnt vmcnt(" #n ")" ::: "memory")
; #define PG8_WAIT_VN(n) asm volatile("s_waitcnt vmcnt(%0)" :: "n"(n) : "memory")
; #define PG8_WAIT_L(n) asm volatile("s_waitcnt lgkmcnt(" #n ")" ::: "memory")
; #define PG8_BAR __builtin_amdgcn_s_barrier()
; #define PG8_SCHED __builtin_amdgcn_sched_barrier(0)
; template <class Epi, class Sched, bool ALIGN_EPI = false, bool SP2 = false>
; __device__ __forceinline__ void gemm_phase(PG8_LAS unsigned char* lds, const Gemm g, const Sched& S, const Epi& E, const int wave_id) {
;     ...
;             PG8_WAIT_VN(8 + Epi::NS); if (strict) PG8_WAIT_V(8); PG8_WAIT_L(0); PG8_BAR; PG8_MMA(0, 0, At, B0); PG8_MMA(0, 1, At, B1); PG8_BAR; PG8_SCHED;
;             PG8_LDA(At, 0, 1); PG8_STAGE(PG8_SB(0, 0), b2, voffB); PG8_STAGE(PG8_SB(0, 1), b2 + hstep, voffB); PG8_STAGE(PG8_SA(0, 0), a2, voffA);
;             PG8_WAIT_VN(8 + Epi::NS); if (strict) PG8_WAIT_V(8); PG8_WAIT_L(0); PG8_BAR; PG8_MMA(1, 0, At, B0); PG8_MMA(1, 1, At, B1); PG8_BAR; PG8_SCHED;
;             PG8_LDB(B0, 1, 0); PG8_LDB(B1, 1, 1); PG8_SCHED; PG8_LDA(At, 1, 0); PG8_STAGE(PG8_SA(0, 1), a2 + hstep, voffA);
;             PG8_WAIT_V(8); PG8_WAIT_L(0); PG8_BAR; PG8_MMA(0, 0, At, B0); PG8_MMA(0, 1, At, B1); PG8_BAR; PG8_SCHED;
.LBB0_304:
	s_waitcnt lgkmcnt(0)
	s_setprio 1
	s_barrier
	v_mfma_f32_16x16x32_bf16 v[62:65], v[146:149], v[186:189], v[62:65]
	v_mfma_f32_16x16x32_bf16 v[58:61], v[154:157], v[186:189], v[58:61]
	v_mfma_f32_16x16x32_bf16 v[54:57], v[146:149], v[178:181], v[54:57]
	v_mfma_f32_16x16x32_bf16 v[50:53], v[154:157], v[178:181], v[50:53]
	v_mfma_f32_16x16x32_bf16 v[42:45], v[146:149], v[170:173], v[42:45]
	v_mfma_f32_16x16x32_bf16 v[34:37], v[154:157], v[170:173], v[34:37]
	v_mfma_f32_16x16x32_bf16 v[26:29], v[146:149], v[162:165], v[26:29]
	v_mfma_f32_16x16x32_bf16 v[18:21], v[154:157], v[162:165], v[18:21]
	v_mfma_f32_16x16x32_bf16 v[62:65], v[150:153], v[190:193], v[62:65]
	v_mfma_f32_16x16x32_bf16 v[58:61], v[158:161], v[190:193], v[58:61]
	v_mfma_f32_16x16x32_bf16 v[54:57], v[150:153], v[182:185], v[54:57]
	v_mfma_f32_16x16x32_bf16 v[50:53], v[158:161], v[182:185], v[50:53]
	v_mfma_f32_16x16x32_bf16 v[42:45], v[150:153], v[174:177], v[42:45]
	v_mfma_f32_16x16x32_bf16 v[34:37], v[158:161], v[174:177], v[34:37]
	v_mfma_f32_16x16x32_bf16 v[26:29], v[150:153], v[166:169], v[26:29]
	v_mfma_f32_16x16x32_bf16 v[18:21], v[158:161], v[166:169], v[18:21]
	s_setprio 0
	s_setprio 1
	v_mfma_f32_16x16x32_bf16 v[46:49], v[130:133], v[186:189], v[46:49]
	v_mfma_f32_16x16x32_bf16 v[38:41], v[138:141], v[186:189], v[38:41]
	v_mfma_f32_16x16x32_bf16 v[30:33], v[130:133], v[178:181], v[30:33]
	v_mfma_f32_16x16x32_bf16 v[22:25], v[138:141], v[178:181], v[22:25]
	v_mfma_f32_16x16x32_bf16 v[14:17], v[130:133], v[170:173], v[14:17]
	v_mfma_f32_16x16x32_bf16 v[10:13], v[138:141], v[170:173], v[10:13]
	v_mfma_f32_16x16x32_bf16 v[6:9], v[130:133], v[162:165], v[6:9]
	v_mfma_f32_16x16x32_bf16 v[2:5], v[138:141], v[162:165], v[2:5]
	v_mfma_f32_16x16x32_bf16 v[46:49], v[134:137], v[190:193], v[46:49]
	v_mfma_f32_16x16x32_bf16 v[38:41], v[142:145], v[190:193], v[38:41]
	v_mfma_f32_16x16x32_bf16 v[30:33], v[134:137], v[182:185], v[30:33]
	v_mfma_f32_16x16x32_bf16 v[22:25], v[142:145], v[182:185], v[22:25]
	v_mfma_f32_16x16x32_bf16 v[14:17], v[134:137], v[174:177], v[14:17]
	v_mfma_f32_16x16x32_bf16 v[10:13], v[142:145], v[174:177], v[10:13]
	v_mfma_f32_16x16x32_bf16 v[6:9], v[134:137], v[166:169], v[6:9]
	v_mfma_f32_16x16x32_bf16 v[2:5], v[142:145], v[166:169], v[2:5]
	s_barrier
	s_setprio 0
	s_add_i32 s16, 0, 0x18000
	s_add_i32 s17, 0, 0x1c000
	v_add_u32_e32 v142, s16, v231
	v_add_u32_e32 v158, s17, v231
	ds_read_b128 v[130:133], v142
	ds_read_b128 v[134:137], v142 offset:1024
	ds_read_b128 v[138:141], v142 offset:2048
	ds_read_b128 v[142:145], v142 offset:3072
	ds_read_b128 v[146:149], v158
	ds_read_b128 v[150:153], v158 offset:1024
	ds_read_b128 v[154:157], v158 offset:2048
	ds_read_b128 v[158:161], v158 offset:3072
	s_add_u32 s14, s14, 0xb0000
	s_addc_u32 s15, s15, 0
	s_mov_b32 m0, s29
	v_lshl_add_u64 v[194:195], s[14:15], 0, v[216:217]
	ds_read_b128 v[162:165], v232 offset:32768
	ds_read_b128 v[166:169], v232 offset:33792
	ds_read_b128 v[170:173], v232 offset:34816
	ds_read_b128 v[174:177], v232 offset:35840
	ds_read_b128 v[178:181], v232 offset:36864
	ds_read_b128 v[182:185], v232 offset:37888
	ds_read_b128 v[186:189], v232 offset:38912
	ds_read_b128 v[190:193], v232 offset:39936
	global_load_lds_dwordx4 v[194:195], off
	v_lshl_add_u64 v[194:195], s[14:15], 0, v[212:213]
	s_mov_b32 m0, s30
	s_nop 0
	global_load_lds_dwordx4 v[194:195], off
	s_waitcnt vmcnt(8)
	s_waitcnt lgkmcnt(0)
	s_setprio 1
	s_barrier
	v_mfma_f32_16x16x32_bf16 v[126:129], v[130:133], v[162:165], v[126:129]
	v_mfma_f32_16x16x32_bf16 v[122:125], v[138:141], v[162:165], v[122:125]
	v_mfma_f32_16x16x32_bf16 v[118:121], v[130:133], v[170:173], v[118:121]
	v_mfma_f32_16x16x32_bf16 v[114:117], v[138:141], v[170:173], v[114:117]
	v_mfma_f32_16x16x32_bf16 v[110:113], v[130:133], v[178:181], v[110:113]
	v_mfma_f32_16x16x32_bf16 v[102:105], v[138:141], v[178:181], v[102:105]
	v_mfma_f32_16x16x32_bf16 v[94:97], v[130:133], v[186:189], v[94:97]
	v_mfma_f32_16x16x32_bf16 v[86:89], v[138:141], v[186:189], v[86:89]
	v_mfma_f32_16x16x32_bf16 v[126:129], v[134:137], v[166:169], v[126:129]
	v_mfma_f32_16x16x32_bf16 v[122:125], v[142:145], v[166:169], v[122:125]
	v_mfma_f32_16x16x32_bf16 v[118:121], v[134:137], v[174:177], v[118:121]
	v_mfma_f32_16x16x32_bf16 v[114:117], v[142:145], v[174:177], v[114:117]
	v_mfma_f32_16x16x32_bf16 v[110:113], v[134:137], v[182:185], v[110:113]
	v_mfma_f32_16x16x32_bf16 v[102:105], v[142:145], v[182:185], v[102:105]
	v_mfma_f32_16x16x32_bf16 v[94:97], v[134:137], v[190:193], v[94:97]
	v_mfma_f32_16x16x32_bf16 v[86:89], v[142:145], v[190:193], v[86:89]
	s_setprio 0
	s_setprio 1
	v_mfma_f32_16x16x32_bf16 v[106:109], v[146:149], v[162:165], v[106:109]
	v_mfma_f32_16x16x32_bf16 v[98:101], v[154:157], v[162:165], v[98:101]
	v_mfma_f32_16x16x32_bf16 v[90:93], v[146:149], v[170:173], v[90:93]
	v_mfma_f32_16x16x32_bf16 v[82:85], v[154:157], v[170:173], v[82:85]
	v_mfma_f32_16x16x32_bf16 v[78:81], v[146:149], v[178:181], v[78:81]
	v_mfma_f32_16x16x32_bf16 v[74:77], v[154:157], v[178:181], v[74:77]
	v_mfma_f32_16x16x32_bf16 v[70:73], v[146:149], v[186:189], v[70:73]
	v_mfma_f32_16x16x32_bf16 v[66:69], v[154:157], v[186:189], v[66:69]
	v_mfma_f32_16x16x32_bf16 v[106:109], v[150:153], v[166:169], v[106:109]
	v_mfma_f32_16x16x32_bf16 v[98:101], v[158:161], v[166:169], v[98:101]
	v_mfma_f32_16x16x32_bf16 v[90:93], v[150:153], v[174:177], v[90:93]
	v_mfma_f32_16x16x32_bf16 v[82:85], v[158:161], v[174:177], v[82:85]
	v_mfma_f32_16x16x32_bf16 v[78:81], v[150:153], v[182:185], v[78:81]
	v_mfma_f32_16x16x32_bf16 v[74:77], v[158:161], v[182:185], v[74:77]
	v_mfma_f32_16x16x32_bf16 v[70:73], v[150:153], v[190:193], v[70:73]
	v_mfma_f32_16x16x32_bf16 v[66:69], v[158:161], v[190:193], v[66:69]
	s_barrier
; #define PG8_STAGE(bufoff, gbase, voff) do { _Pragma("unroll") for (int _i = 0; _i < 2; ++_i) \
;         __builtin_amdgcn_global_load_lds((const unsigned*)((const char*)(gbase) + (voff)[_i]), (PG8_LAS unsigned*)(lds + (bufoff) + ldsw + _i * 8192), 16, 0, 0); } while (0)
; #define PG8_LDA(dst, b, h) do { _Pragma("unroll") for (int m = 0; m < 4; ++m) _Pragma("unroll") for (int k = 0; k < 2; ++k) dst[m][k] = *(const PG8_LAS bf16x8*)(lds + PG8_SA(b, h) + aoff + m * 2048 + k * 1024); } while (0)
; #define PG8_MMA(ai, bj, At, Bt) do { __builtin_amdgcn_s_setprio(1); _Pragma("unroll") for (int m = 0; m < 4; ++m) _Pragma("unroll") for (int n = 0; n < 2; ++n) _Pragma("unroll") for (int k = 0; k < 2; ++k) \
;         acc[ai][bj][m][n] = __builtin_amdgcn_mfma_f32_16x16x32_bf16(Bt[n][k], At[m][k], acc[ai][bj][m][n], 0, 0, 0); __builtin_amdgcn_s_setprio(0); } while (0)
; #define PG8_WAIT_V(n) asm volatile("s_waitcnt vmcnt(" #n ")" ::: "memory")
; #define PG8_WAIT_L(n) asm volatile("s_waitcnt lgkmcnt(" #n ")" ::: "memory")
; #define PG8_BAR __builtin_amdgcn_s_barrier()
; #define PG8_SCHED __builtin_amdgcn_sched_barrier(0)
; template <class Epi, class Sched, bool ALIGN_EPI = false, bool SP2 = false>
; __device__ __forceinline__ void gemm_phase(PG8_LAS unsigned char* lds, const Gemm g, const Sched& S, const Epi& E, const int wave_id) {
;     ...
;         for (int t = 0; t < nt; t += 2) {
;     ...
;             PG8_LDA(At, 1, 1); PG8_STAGE(PG8_SB(1, 0), b3, voffB); PG8_STAGE(PG8_SB(1, 1), b3 + hstep, voffB); PG8_STAGE(PG8_SA(1, 0), a3, voffA);
;             PG8_WAIT_V(8); PG8_WAIT_L(0); PG8_BAR; PG8_MMA(1, 0, At, B0); PG8_MMA(1, 1, At, B1); PG8_BAR; PG8_SCHED;
	s_setprio 0
	s_add_i32 s14, s16, s21
	v_lshl_add_u64 v[194:195], v[228:229], 0, s[64:65]
	s_mov_b32 m0, s14
	ds_read_b128 v[162:165], v232 offset:49152
	ds_read_b128 v[166:169], v232 offset:50176
	ds_read_b128 v[170:173], v232 offset:51200
	ds_read_b128 v[174:177], v232 offset:52224
	ds_read_b128 v[178:181], v232 offset:53248
	ds_read_b128 v[182:185], v232 offset:54272
	ds_read_b128 v[186:189], v232 offset:55296
	ds_read_b128 v[190:193], v232 offset:56320
	global_load_lds_dwordx4 v[194:195], off
	s_add_i32 m0, s14, 0x2000
	s_add_u32 s12, s12, 0xb0080
	v_lshl_add_u64 v[194:195], v[226:227], 0, s[64:65]
	s_addc_u32 s13, s13, 0
	s_add_i32 s14, s17, s21
	global_load_lds_dwordx4 v[194:195], off
	v_lshl_add_u64 v[194:195], s[12:13], 0, v[214:215]
	s_mov_b32 m0, s14
	s_nop 0
	global_load_lds_dwordx4 v[194:195], off
	v_lshl_add_u64 v[194:195], s[12:13], 0, v[210:211]
	s_add_i32 m0, s14, 0x2000
	s_nop 0
	global_load_lds_dwordx4 v[194:195], off
	v_lshl_add_u64 v[194:195], v[222:223], 0, s[64:65]
	s_mov_b32 m0, s31
	s_nop 0
	global_load_lds_dwordx4 v[194:195], off
	v_lshl_add_u64 v[194:195], v[224:225], 0, s[64:65]
	s_mov_b32 m0, s34
	s_nop 0
	global_load_lds_dwordx4 v[194:195], off
	s_waitcnt vmcnt(8)
	s_waitcnt lgkmcnt(0)
	s_setprio 1
	s_barrier
	v_mfma_f32_16x16x32_bf16 v[62:65], v[130:133], v[162:165], v[62:65]
	v_mfma_f32_16x16x32_bf16 v[58:61], v[138:141], v[162:165], v[58:61]
	v_mfma_f32_16x16x32_bf16 v[54:57], v[130:133], v[170:173], v[54:57]
	v_mfma_f32_16x16x32_bf16 v[50:53], v[138:141], v[170:173], v[50:53]
	v_mfma_f32_16x16x32_bf16 v[42:45], v[130:133], v[178:181], v[42:45]
	v_mfma_f32_16x16x32_bf16 v[34:37], v[138:141], v[178:181], v[34:37]
	v_mfma_f32_16x16x32_bf16 v[26:29], v[130:133], v[186:189], v[26:29]
	v_mfma_f32_16x16x32_bf16 v[18:21], v[138:141], v[186:189], v[18:21]
	v_mfma_f32_16x16x32_bf16 v[62:65], v[134:137], v[166:169], v[62:65]
	v_mfma_f32_16x16x32_bf16 v[58:61], v[142:145], v[166:169], v[58:61]
	v_mfma_f32_16x16x32_bf16 v[54:57], v[134:137], v[174:177], v[54:57]
	v_mfma_f32_16x16x32_bf16 v[50:53], v[142:145], v[174:177], v[50:53]
	v_mfma_f32_16x16x32_bf16 v[42:45], v[134:137], v[182:185], v[42:45]
	v_mfma_f32_16x16x32_bf16 v[34:37], v[142:145], v[182:185], v[34:37]
	v_mfma_f32_16x16x32_bf16 v[26:29], v[134:137], v[190:193], v[26:29]
	v_mfma_f32_16x16x32_bf16 v[18:21], v[142:145], v[190:193], v[18:21]
	s_setprio 0
	s_setprio 1
	v_mfma_f32_16x16x32_bf16 v[46:49], v[146:149], v[162:165], v[46:49]
	v_mfma_f32_16x16x32_bf16 v[38:41], v[154:157], v[162:165], v[38:41]
	v_mfma_f32_16x16x32_bf16 v[30:33], v[146:149], v[170:173], v[30:33]
	v_mfma_f32_16x16x32_bf16 v[22:25], v[154:157], v[170:173], v[22:25]
	v_mfma_f32_16x16x32_bf16 v[14:17], v[146:149], v[178:181], v[14:17]
	v_mfma_f32_16x16x32_bf16 v[10:13], v[154:157], v[178:181], v[10:13]
	v_mfma_f32_16x16x32_bf16 v[6:9], v[146:149], v[186:189], v[6:9]
	v_mfma_f32_16x16x32_bf16 v[2:5], v[154:157], v[186:189], v[2:5]
	v_mfma_f32_16x16x32_bf16 v[46:49], v[150:153], v[166:169], v[46:49]
	v_mfma_f32_16x16x32_bf16 v[38:41], v[158:161], v[166:169], v[38:41]
	v_mfma_f32_16x16x32_bf16 v[30:33], v[150:153], v[174:177], v[30:33]
	v_mfma_f32_16x16x32_bf16 v[22:25], v[158:161], v[174:177], v[22:25]
	v_mfma_f32_16x16x32_bf16 v[14:17], v[150:153], v[182:185], v[14:17]
	v_mfma_f32_16x16x32_bf16 v[10:13], v[158:161], v[182:185], v[10:13]
	v_mfma_f32_16x16x32_bf16 v[6:9], v[150:153], v[190:193], v[6:9]
	v_mfma_f32_16x16x32_bf16 v[2:5], v[158:161], v[190:193], v[2:5]
	s_barrier
	s_setprio 0
	s_add_u32 s10, s10, 0x100
	s_addc_u32 s11, s11, 0
	s_cmp_gt_u32 s39, 19
	v_readlane_b32 s40, v254, 55
	s_cbranch_scc1 .LBB0_309

; #define PG8_STAGE(bufoff, gbase, voff) do { _Pragma("unroll") for (int _i = 0; _i < 2; ++_i) \
;         __builtin_amdgcn_global_load_lds((const unsigned*)((const char*)(gbase) + (voff)[_i]), (PG8_LAS unsigned*)(lds + (bufoff) + ldsw + _i * 8192), 16, 0, 0); } while (0)
; #define PG8_LDA(dst, b, h) do { _Pragma("unroll") for (int m = 0; m < 4; ++m) _Pragma("unroll") for (int k = 0; k < 2; ++k) dst[m][k] = *(const PG8_LAS bf16x8*)(lds + PG8_SA(b, h) + aoff + m * 2048 + k * 1024); } while (0)
; #define PG8_LDB(dst, b, h) do { _Pragma("unroll") for (int n = 0; n < 2; ++n) _Pragma("unroll") for (int k = 0; k < 2; ++k) dst[n][k] = *(const PG8_LAS bf16x8*)(lds + PG8_SB(b, h) + boff + n * 2048 + k * 1024); } while (0)
; #define PG8_WAIT_V(n) asm volatile("s_waitcnt vmcnt(" #n ")" ::: "memory")
; #define PG8_WAIT_VN(n) asm volatile("s_waitcnt vmcnt(%0)" :: "n"(n) : "memory")
; #define PG8_WAIT_L(n) asm volatile("s_waitcnt lgkmcnt(" #n ")" ::: "memory")
; template <class Epi, class Sched, bool ALIGN_EPI = false, bool SP2 = false>
; __device__ __forceinline__ void gemm_phase(PG8_LAS unsigned char* lds, const Gemm g, const Sched& S, const Epi& E, const int wave_id) {
;     ...
;         for (int t = 0; t < nt; t += 2) {
;             const bool last = (t == nt - 2);
;             const char* a1 = cA + (size_t)(t + 1) * kstep;
;             const char* a2 = last ? nA : cA + (size_t)(t + 2) * kstep; const char* b2 = last ? nB : cB + (size_t)(t + 2) * kstep;
;             const char* a3 = a2 + kstep; const char* b3 = b2 + kstep;
;             if (last && has_next) S.a_ready(nxt);
;             if constexpr (SP2) {
;             int tz_ = __builtin_amdgcn_readfirstlane(t | (ui > 0 ? 0 : 1)); asm volatile("" : "+s"(tz_));
;             const bool strict = !(Epi::NS > 0 && tz_ == 0);
;             PG8_LDB(B0, 0, 0); PG8_LDB(B1, 0, 1); PG8_SCHED; PG8_LDA(At, 0, 0); PG8_STAGE(PG8_SA(1, 1), a1 + hstep, voffA);
;             PG8_WAIT_VN(8 + Epi::NS); if (strict) PG8_WAIT_V(8); PG8_WAIT_L(0); PG8_BAR; PG8_MMA(0, 0, At, B0); PG8_MMA(0, 1, At, B1); PG8_BAR; PG8_SCHED;
;             PG8_LDA(At, 0, 1); PG8_STAGE(PG8_SB(0, 0), b2, voffB); PG8_STAGE(PG8_SB(0, 1), b2 + hstep, voffB); PG8_STAGE(PG8_SA(0, 0), a2, voffA);
;             PG8_WAIT_VN(8 + Epi::NS); if (strict) PG8_WAIT_V(8); PG8_WAIT_L(0); PG8_BAR; PG8_MMA(1, 0, At, B0); PG8_MMA(1, 1, At, B1); PG8_BAR; PG8_SCHED;
.LBB0_307:
	s_add_u32 s12, s37, s10
	s_addc_u32 s13, s38, s11
	s_add_u32 s12, s12, 0x26300100
	s_addc_u32 s13, s13, 0
	s_add_u32 s40, s35, s10
	s_addc_u32 s41, s36, s11
	s_cmpk_eq_i32 s10, 0xa00
	s_cselect_b32 s15, s9, s13
	s_cselect_b32 s14, s8, s12
	s_cselect_b32 s13, s7, s41
	s_cselect_b32 s12, s6, s40
	s_waitcnt lgkmcnt(0)
	s_setprio 1
	s_barrier
	v_mfma_f32_16x16x32_bf16 v[126:129], v[146:149], v[186:189], v[126:129]
	v_mfma_f32_16x16x32_bf16 v[122:125], v[154:157], v[186:189], v[122:125]
	v_mfma_f32_16x16x32_bf16 v[118:121], v[146:149], v[178:181], v[118:121]
	v_mfma_f32_16x16x32_bf16 v[114:117], v[154:157], v[178:181], v[114:117]
	v_mfma_f32_16x16x32_bf16 v[110:113], v[146:149], v[170:173], v[110:113]
	v_mfma_f32_16x16x32_bf16 v[102:105], v[154:157], v[170:173], v[102:105]
	v_mfma_f32_16x16x32_bf16 v[94:97], v[146:149], v[162:165], v[94:97]
	v_mfma_f32_16x16x32_bf16 v[86:89], v[154:157], v[162:165], v[86:89]
	v_mfma_f32_16x16x32_bf16 v[126:129], v[150:153], v[190:193], v[126:129]
	v_mfma_f32_16x16x32_bf16 v[122:125], v[158:161], v[190:193], v[122:125]
	v_mfma_f32_16x16x32_bf16 v[118:121], v[150:153], v[182:185], v[118:121]
	v_mfma_f32_16x16x32_bf16 v[114:117], v[158:161], v[182:185], v[114:117]
	v_mfma_f32_16x16x32_bf16 v[110:113], v[150:153], v[174:177], v[110:113]
	v_mfma_f32_16x16x32_bf16 v[102:105], v[158:161], v[174:177], v[102:105]
	v_mfma_f32_16x16x32_bf16 v[94:97], v[150:153], v[166:169], v[94:97]
	v_mfma_f32_16x16x32_bf16 v[86:89], v[158:161], v[166:169], v[86:89]
	s_setprio 0
	s_setprio 1
	v_mfma_f32_16x16x32_bf16 v[106:109], v[130:133], v[186:189], v[106:109]
	v_mfma_f32_16x16x32_bf16 v[98:101], v[138:141], v[186:189], v[98:101]
	v_mfma_f32_16x16x32_bf16 v[90:93], v[130:133], v[178:181], v[90:93]
	v_mfma_f32_16x16x32_bf16 v[82:85], v[138:141], v[178:181], v[82:85]
	v_mfma_f32_16x16x32_bf16 v[78:81], v[130:133], v[170:173], v[78:81]
	v_mfma_f32_16x16x32_bf16 v[74:77], v[138:141], v[170:173], v[74:77]
	v_mfma_f32_16x16x32_bf16 v[70:73], v[130:133], v[162:165], v[70:73]
	v_mfma_f32_16x16x32_bf16 v[66:69], v[138:141], v[162:165], v[66:69]
	v_mfma_f32_16x16x32_bf16 v[106:109], v[134:137], v[190:193], v[106:109]
	v_mfma_f32_16x16x32_bf16 v[98:101], v[142:145], v[190:193], v[98:101]
	v_mfma_f32_16x16x32_bf16 v[90:93], v[134:137], v[182:185], v[90:93]
	v_mfma_f32_16x16x32_bf16 v[82:85], v[142:145], v[182:185], v[82:85]
	v_mfma_f32_16x16x32_bf16 v[78:81], v[134:137], v[174:177], v[78:81]
	v_mfma_f32_16x16x32_bf16 v[74:77], v[142:145], v[174:177], v[74:77]
	v_mfma_f32_16x16x32_bf16 v[70:73], v[134:137], v[166:169], v[70:73]
	v_mfma_f32_16x16x32_bf16 v[66:69], v[142:145], v[166:169], v[66:69]
	s_barrier
	s_setprio 0
	s_mov_b32 m0, s23
	v_lshl_add_u64 v[228:229], s[12:13], 0, v[214:215]
	s_add_u32 s40, s12, 0xb0000
	ds_read_b128 v[186:189], v232 offset:16384
	ds_read_b128 v[190:193], v232 offset:17408
	ds_read_b128 v[178:181], v232 offset:18432
	ds_read_b128 v[182:185], v232 offset:19456
	ds_read_b128 v[170:173], v232 offset:20480
	ds_read_b128 v[174:177], v232 offset:21504
	ds_read_b128 v[162:165], v232 offset:22528
	ds_read_b128 v[166:169], v232 offset:23552
	global_load_lds_dwordx4 v[228:229], off
	v_lshl_add_u64 v[226:227], s[12:13], 0, v[210:211]
	s_mov_b32 m0, s24
	s_addc_u32 s41, s13, 0
	global_load_lds_dwordx4 v[226:227], off
	v_lshl_add_u64 v[194:195], s[40:41], 0, v[214:215]
	s_mov_b32 m0, s25
	v_lshl_add_u64 v[222:223], s[14:15], 0, v[216:217]
	global_load_lds_dwordx4 v[194:195], off
	v_lshl_add_u64 v[194:195], s[40:41], 0, v[210:211]
	s_mov_b32 m0, s26
	v_lshl_add_u64 v[224:225], s[14:15], 0, v[212:213]
	global_load_lds_dwordx4 v[194:195], off
	s_mov_b32 m0, s22
	s_andn2_b64 vcc, exec, s[16:17]
	global_load_lds_dwordx4 v[222:223], off
	s_mov_b32 m0, s28
	s_nop 0
	global_load_lds_dwordx4 v[224:225], off
	s_waitcnt vmcnt(24)
	s_cbranch_vccnz .LBB0_304
	s_waitcnt vmcnt(8)
	s_branch .LBB0_304

; #define PG8_STAGE(bufoff, gbase, voff) do { _Pragma("unroll") for (int _i = 0; _i < 2; ++_i) \
;         __builtin_amdgcn_global_load_lds((const unsigned*)((const char*)(gbase) + (voff)[_i]), (PG8_LAS unsigned*)(lds + (bufoff) + ldsw + _i * 8192), 16, 0, 0); } while (0)
; #define PG8_LDA(dst, b, h) do { _Pragma("unroll") for (int m = 0; m < 4; ++m) _Pragma("unroll") for (int k = 0; k < 2; ++k) dst[m][k] = *(const PG8_LAS bf16x8*)(lds + PG8_SA(b, h) + aoff + m * 2048 + k * 1024); } while (0)
; #define PG8_LDB(dst, b, h) do { _Pragma("unroll") for (int n = 0; n < 2; ++n) _Pragma("unroll") for (int k = 0; k < 2; ++k) dst[n][k] = *(const PG8_LAS bf16x8*)(lds + PG8_SB(b, h) + boff + n * 2048 + k * 1024); } while (0)
; #define PG8_MMA(ai, bj, At, Bt) do { __builtin_amdgcn_s_setprio(1); _Pragma("unroll") for (int m = 0; m < 4; ++m) _Pragma("unroll") for (int n = 0; n < 2; ++n) _Pragma("unroll") for (int k = 0; k < 2; ++k) \
;         acc[ai][bj][m][n] = __builtin_amdgcn_mfma_f32_16x16x32_bf16(Bt[n][k], At[m][k], acc[ai][bj][m][n], 0, 0, 0); __builtin_amdgcn_s_setprio(0); } while (0)
; #define PG8_WAIT_V(n) asm volatile("s_waitcnt vmcnt(" #n ")" ::: "memory")
; #define PG8_WAIT_VN(n) asm volatile("s_waitcnt vmcnt(%0)" :: "n"(n) : "memory")
; #define PG8_WAIT_L(n) asm volatile("s_waitcnt lgkmcnt(" #n ")" ::: "memory")
; template <class Epi, class Sched, bool ALIGN_EPI = false, bool SP2 = false>
; __device__ __forceinline__ void gemm_phase(PG8_LAS unsigned char* lds, const Gemm g, const Sched& S, const Epi& E, const int wave_id) {
;     ...
;             PG8_LDB(B0, 0, 0); PG8_LDB(B1, 0, 1); PG8_SCHED; PG8_LDA(At, 0, 0); PG8_STAGE(PG8_SA(1, 1), a1 + hstep, voffA);
;             PG8_WAIT_VN(8 + Epi::NS); if (strict) PG8_WAIT_V(8); PG8_WAIT_L(0); PG8_BAR; PG8_MMA(0, 0, At, B0); PG8_MMA(0, 1, At, B1); PG8_BAR; PG8_SCHED;
;             PG8_LDA(At, 0, 1); PG8_STAGE(PG8_SB(0, 0), b2, voffB); PG8_STAGE(PG8_SB(0, 1), b2 + hstep, voffB); PG8_STAGE(PG8_SA(0, 0), a2, voffA);
;             PG8_WAIT_VN(8 + Epi::NS); if (strict) PG8_WAIT_V(8); PG8_WAIT_L(0); PG8_BAR; PG8_MMA(1, 0, At, B0); PG8_MMA(1, 1, At, B1); PG8_BAR; PG8_SCHED;
;             PG8_LDB(B0, 1, 0); PG8_LDB(B1, 1, 1); PG8_SCHED; PG8_LDA(At, 1, 0); PG8_STAGE(PG8_SA(0, 1), a2 + hstep, voffA);
;             PG8_WAIT_V(8); PG8_WAIT_L(0); PG8_BAR; PG8_MMA(0, 0, At, B0); PG8_MMA(0, 1, At, B1); PG8_BAR; PG8_SCHED;
.LBB0_420:
	s_waitcnt lgkmcnt(0)
	s_setprio 1
	s_barrier
	v_mfma_f32_16x16x32_bf16 v[62:65], v[146:149], v[186:189], v[62:65]
	v_mfma_f32_16x16x32_bf16 v[58:61], v[154:157], v[186:189], v[58:61]
	v_mfma_f32_16x16x32_bf16 v[46:49], v[146:149], v[178:181], v[46:49]
	v_mfma_f32_16x16x32_bf16 v[42:45], v[154:157], v[178:181], v[42:45]
	v_mfma_f32_16x16x32_bf16 v[30:33], v[146:149], v[170:173], v[30:33]
	v_mfma_f32_16x16x32_bf16 v[26:29], v[154:157], v[170:173], v[26:29]
	v_mfma_f32_16x16x32_bf16 v[14:17], v[146:149], v[162:165], v[14:17]
	v_mfma_f32_16x16x32_bf16 v[10:13], v[154:157], v[162:165], v[10:13]
	v_mfma_f32_16x16x32_bf16 v[62:65], v[150:153], v[190:193], v[62:65]
	v_mfma_f32_16x16x32_bf16 v[58:61], v[158:161], v[190:193], v[58:61]
	v_mfma_f32_16x16x32_bf16 v[46:49], v[150:153], v[182:185], v[46:49]
	v_mfma_f32_16x16x32_bf16 v[42:45], v[158:161], v[182:185], v[42:45]
	v_mfma_f32_16x16x32_bf16 v[30:33], v[150:153], v[174:177], v[30:33]
	v_mfma_f32_16x16x32_bf16 v[26:29], v[158:161], v[174:177], v[26:29]
	v_mfma_f32_16x16x32_bf16 v[14:17], v[150:153], v[166:169], v[14:17]
	v_mfma_f32_16x16x32_bf16 v[10:13], v[158:161], v[166:169], v[10:13]
	s_setprio 0
	s_setprio 1
	v_mfma_f32_16x16x32_bf16 v[54:57], v[130:133], v[186:189], v[54:57]
	v_mfma_f32_16x16x32_bf16 v[50:53], v[138:141], v[186:189], v[50:53]
	v_mfma_f32_16x16x32_bf16 v[38:41], v[130:133], v[178:181], v[38:41]
	v_mfma_f32_16x16x32_bf16 v[34:37], v[138:141], v[178:181], v[34:37]
	v_mfma_f32_16x16x32_bf16 v[22:25], v[130:133], v[170:173], v[22:25]
	v_mfma_f32_16x16x32_bf16 v[18:21], v[138:141], v[170:173], v[18:21]
	v_mfma_f32_16x16x32_bf16 v[6:9], v[130:133], v[162:165], v[6:9]
	v_mfma_f32_16x16x32_bf16 v[2:5], v[138:141], v[162:165], v[2:5]
	v_mfma_f32_16x16x32_bf16 v[54:57], v[134:137], v[190:193], v[54:57]
	v_mfma_f32_16x16x32_bf16 v[50:53], v[142:145], v[190:193], v[50:53]
	v_mfma_f32_16x16x32_bf16 v[38:41], v[134:137], v[182:185], v[38:41]
	v_mfma_f32_16x16x32_bf16 v[34:37], v[142:145], v[182:185], v[34:37]
	v_mfma_f32_16x16x32_bf16 v[22:25], v[134:137], v[174:177], v[22:25]
	v_mfma_f32_16x16x32_bf16 v[18:21], v[142:145], v[174:177], v[18:21]
	v_mfma_f32_16x16x32_bf16 v[6:9], v[134:137], v[166:169], v[6:9]
	v_mfma_f32_16x16x32_bf16 v[2:5], v[142:145], v[166:169], v[2:5]
	s_barrier
	s_setprio 0
	s_add_i32 s34, 0, 0x18000
	s_add_i32 s35, 0, 0x1c000
	v_add_u32_e32 v142, s34, v246
	v_add_u32_e32 v158, s35, v246
	ds_read_b128 v[130:133], v142
	ds_read_b128 v[134:137], v142 offset:1024
	ds_read_b128 v[138:141], v142 offset:2048
	ds_read_b128 v[142:145], v142 offset:3072
	ds_read_b128 v[146:149], v158
	ds_read_b128 v[150:153], v158 offset:1024
	ds_read_b128 v[154:157], v158 offset:2048
	ds_read_b128 v[158:161], v158 offset:3072
	s_add_u32 s14, s14, 0x40000
	s_addc_u32 s15, s15, 0
	s_mov_b32 m0, s3
	v_lshl_add_u64 v[194:195], s[14:15], 0, v[210:211]
	ds_read_b128 v[162:165], v247 offset:32768
	ds_read_b128 v[166:169], v247 offset:33792
	ds_read_b128 v[170:173], v247 offset:34816
	ds_read_b128 v[174:177], v247 offset:35840
	ds_read_b128 v[178:181], v247 offset:36864
	ds_read_b128 v[182:185], v247 offset:37888
	ds_read_b128 v[186:189], v247 offset:38912
	ds_read_b128 v[190:193], v247 offset:39936
	global_load_lds_dwordx4 v[194:195], off
	v_lshl_add_u64 v[194:195], s[14:15], 0, v[214:215]
	s_mov_b32 m0, s4
	s_nop 0
	global_load_lds_dwordx4 v[194:195], off
	s_waitcnt vmcnt(26)
	s_cmp_eq_u32 s100, 0
	s_cbranch_scc1 .Lthird_wait_relaxed_4
	s_waitcnt vmcnt(8)
; #define PG8_STAGE(bufoff, gbase, voff) do { _Pragma("unroll") for (int _i = 0; _i < 2; ++_i) \
;         __builtin_amdgcn_global_load_lds((const unsigned*)((const char*)(gbase) + (voff)[_i]), (PG8_LAS unsigned*)(lds + (bufoff) + ldsw + _i * 8192), 16, 0, 0); } while (0)
; #define PG8_WAIT_V(n) asm volatile("s_waitcnt vmcnt(" #n ")" ::: "memory")
; #define PG8_WAIT_VN(n) asm volatile("s_waitcnt vmcnt(%0)" :: "n"(n) : "memory")
; template <class Epi, class Sched, bool ALIGN_EPI = false, bool SP2 = false>
; __device__ __forceinline__ void gemm_phase(PG8_LAS unsigned char* lds, const Gemm g, const Sched& S, const Epi& E, const int wave_id) {
;     ...
;         for (int t = 0; t < nt; t += 2) {
;             const bool last = (t == nt - 2);
;             const char* a1 = cA + (size_t)(t + 1) * kstep;
;             const char* a2 = last ? nA : cA + (size_t)(t + 2) * kstep; const char* b2 = last ? nB : cB + (size_t)(t + 2) * kstep;
;             const char* a3 = a2 + kstep; const char* b3 = b2 + kstep;
;             if (last && has_next) S.a_ready(nxt);
;             if constexpr (SP2) {
;             int tz_ = __builtin_amdgcn_readfirstlane(t | (ui > 0 ? 0 : 1)); asm volatile("" : "+s"(tz_));
;             const bool strict = !(Epi::NS > 0 && tz_ == 0);
;             PG8_LDB(B0, 0, 0); PG8_LDB(B1, 0, 1); PG8_SCHED; PG8_LDA(At, 0, 0); PG8_STAGE(PG8_SA(1, 1), a1 + hstep, voffA);
;             PG8_WAIT_VN(8 + Epi::NS); if (strict) PG8_WAIT_V(8); PG8_WAIT_L(0); PG8_BAR; PG8_MMA(0, 0, At, B0); PG8_MMA(0, 1, At, B1); PG8_BAR; PG8_SCHED;
;             PG8_LDA(At, 0, 1); PG8_STAGE(PG8_SB(0, 0), b2, voffB); PG8_STAGE(PG8_SB(0, 1), b2 + hstep, voffB); PG8_STAGE(PG8_SA(0, 0), a2, voffA);
;             PG8_WAIT_VN(8 + Epi::NS); if (strict) PG8_WAIT_V(8); PG8_WAIT_L(0); PG8_BAR; PG8_MMA(1, 0, At, B0); PG8_MMA(1, 1, At, B1); PG8_BAR; PG8_SCHED;
;             PG8_LDB(B0, 1, 0); PG8_LDB(B1, 1, 1); PG8_SCHED; PG8_LDA(At, 1, 0); PG8_STAGE(PG8_SA(0, 1), a2 + hstep, voffA);
;             PG8_WAIT_V(8); PG8_WAIT_L(0); PG8_BAR; PG8_MMA(0, 0, At, B0); PG8_MMA(0, 1, At, B1); PG8_BAR; PG8_SCHED;
;             PG8_LDA(At, 1, 1); PG8_STAGE(PG8_SB(1, 0), b3, voffB); PG8_STAGE(PG8_SB(1, 1), b3 + hstep, voffB); PG8_STAGE(PG8_SA(1, 0), a3, voffA);
;             PG8_WAIT_V(8); PG8_WAIT_L(0); PG8_BAR; PG8_MMA(1, 0, At, B0); PG8_MMA(1, 1, At, B1); PG8_BAR; PG8_SCHED;
.Lthird_wait_relaxed_4:
	s_waitcnt lgkmcnt(0)
	s_setprio 1
	s_barrier
	v_mfma_f32_16x16x32_bf16 v[126:129], v[130:133], v[162:165], v[126:129]
	v_mfma_f32_16x16x32_bf16 v[122:125], v[138:141], v[162:165], v[122:125]
	v_mfma_f32_16x16x32_bf16 v[110:113], v[130:133], v[170:173], v[110:113]
	v_mfma_f32_16x16x32_bf16 v[106:109], v[138:141], v[170:173], v[106:109]
	v_mfma_f32_16x16x32_bf16 v[94:97], v[130:133], v[178:181], v[94:97]
	v_mfma_f32_16x16x32_bf16 v[90:93], v[138:141], v[178:181], v[90:93]
	v_mfma_f32_16x16x32_bf16 v[78:81], v[130:133], v[186:189], v[78:81]
	v_mfma_f32_16x16x32_bf16 v[74:77], v[138:141], v[186:189], v[74:77]
	v_mfma_f32_16x16x32_bf16 v[126:129], v[134:137], v[166:169], v[126:129]
	v_mfma_f32_16x16x32_bf16 v[122:125], v[142:145], v[166:169], v[122:125]
	v_mfma_f32_16x16x32_bf16 v[110:113], v[134:137], v[174:177], v[110:113]
	v_mfma_f32_16x16x32_bf16 v[106:109], v[142:145], v[174:177], v[106:109]
	v_mfma_f32_16x16x32_bf16 v[94:97], v[134:137], v[182:185], v[94:97]
	v_mfma_f32_16x16x32_bf16 v[90:93], v[142:145], v[182:185], v[90:93]
	v_mfma_f32_16x16x32_bf16 v[78:81], v[134:137], v[190:193], v[78:81]
	v_mfma_f32_16x16x32_bf16 v[74:77], v[142:145], v[190:193], v[74:77]
	s_setprio 0
	s_setprio 1
	v_mfma_f32_16x16x32_bf16 v[118:121], v[146:149], v[162:165], v[118:121]
	v_mfma_f32_16x16x32_bf16 v[114:117], v[154:157], v[162:165], v[114:117]
	v_mfma_f32_16x16x32_bf16 v[102:105], v[146:149], v[170:173], v[102:105]
	v_mfma_f32_16x16x32_bf16 v[98:101], v[154:157], v[170:173], v[98:101]
	v_mfma_f32_16x16x32_bf16 v[86:89], v[146:149], v[178:181], v[86:89]
	v_mfma_f32_16x16x32_bf16 v[82:85], v[154:157], v[178:181], v[82:85]
	v_mfma_f32_16x16x32_bf16 v[70:73], v[146:149], v[186:189], v[70:73]
	v_mfma_f32_16x16x32_bf16 v[66:69], v[154:157], v[186:189], v[66:69]
	v_mfma_f32_16x16x32_bf16 v[118:121], v[150:153], v[166:169], v[118:121]
	v_mfma_f32_16x16x32_bf16 v[114:117], v[158:161], v[166:169], v[114:117]
	v_mfma_f32_16x16x32_bf16 v[102:105], v[150:153], v[174:177], v[102:105]
	v_mfma_f32_16x16x32_bf16 v[98:101], v[158:161], v[174:177], v[98:101]
	v_mfma_f32_16x16x32_bf16 v[86:89], v[150:153], v[182:185], v[86:89]
	v_mfma_f32_16x16x32_bf16 v[82:85], v[158:161], v[182:185], v[82:85]
	v_mfma_f32_16x16x32_bf16 v[70:73], v[150:153], v[190:193], v[70:73]
	v_mfma_f32_16x16x32_bf16 v[66:69], v[158:161], v[190:193], v[66:69]
	s_barrier
	s_setprio 0
	s_add_i32 s14, s34, s90
	v_lshl_add_u64 v[194:195], v[232:233], 0, s[64:65]
	s_mov_b32 m0, s14
	ds_read_b128 v[162:165], v247 offset:49152
	ds_read_b128 v[166:169], v247 offset:50176
	ds_read_b128 v[170:173], v247 offset:51200
	ds_read_b128 v[174:177], v247 offset:52224
	ds_read_b128 v[178:181], v247 offset:53248
	ds_read_b128 v[182:185], v247 offset:54272
	ds_read_b128 v[186:189], v247 offset:55296
	ds_read_b128 v[190:193], v247 offset:56320
	global_load_lds_dwordx4 v[194:195], off
	s_add_i32 m0, s14, 0x2000
	s_add_u32 s12, s12, 0x40080
	v_lshl_add_u64 v[194:195], v[230:231], 0, s[64:65]
	s_addc_u32 s13, s13, 0
	s_add_i32 s14, s35, s90
	global_load_lds_dwordx4 v[194:195], off
	v_lshl_add_u64 v[194:195], s[12:13], 0, v[212:213]
	s_mov_b32 m0, s14
	s_nop 0
	global_load_lds_dwordx4 v[194:195], off
	v_lshl_add_u64 v[194:195], s[12:13], 0, v[216:217]
	s_add_i32 m0, s14, 0x2000
	s_nop 0
	global_load_lds_dwordx4 v[194:195], off
	v_lshl_add_u64 v[194:195], v[226:227], 0, s[64:65]
	s_mov_b32 m0, s63
	s_nop 0
	global_load_lds_dwordx4 v[194:195], off
	v_lshl_add_u64 v[194:195], v[228:229], 0, s[64:65]
	s_mov_b32 m0, s68
	s_nop 0
	global_load_lds_dwordx4 v[194:195], off
	s_waitcnt vmcnt(8)
	s_waitcnt lgkmcnt(0)
	s_setprio 1
	s_barrier
	v_mfma_f32_16x16x32_bf16 v[62:65], v[130:133], v[162:165], v[62:65]
	v_mfma_f32_16x16x32_bf16 v[58:61], v[138:141], v[162:165], v[58:61]
	v_mfma_f32_16x16x32_bf16 v[46:49], v[130:133], v[170:173], v[46:49]
	v_mfma_f32_16x16x32_bf16 v[42:45], v[138:141], v[170:173], v[42:45]
	v_mfma_f32_16x16x32_bf16 v[30:33], v[130:133], v[178:181], v[30:33]
	v_mfma_f32_16x16x32_bf16 v[26:29], v[138:141], v[178:181], v[26:29]
	v_mfma_f32_16x16x32_bf16 v[14:17], v[130:133], v[186:189], v[14:17]
	v_mfma_f32_16x16x32_bf16 v[10:13], v[138:141], v[186:189], v[10:13]
	v_mfma_f32_16x16x32_bf16 v[62:65], v[134:137], v[166:169], v[62:65]
	v_mfma_f32_16x16x32_bf16 v[58:61], v[142:145], v[166:169], v[58:61]
	v_mfma_f32_16x16x32_bf16 v[46:49], v[134:137], v[174:177], v[46:49]
	v_mfma_f32_16x16x32_bf16 v[42:45], v[142:145], v[174:177], v[42:45]
	v_mfma_f32_16x16x32_bf16 v[30:33], v[134:137], v[182:185], v[30:33]
	v_mfma_f32_16x16x32_bf16 v[26:29], v[142:145], v[182:185], v[26:29]
	v_mfma_f32_16x16x32_bf16 v[14:17], v[134:137], v[190:193], v[14:17]
	v_mfma_f32_16x16x32_bf16 v[10:13], v[142:145], v[190:193], v[10:13]
	s_setprio 0
	s_setprio 1
	v_mfma_f32_16x16x32_bf16 v[54:57], v[146:149], v[162:165], v[54:57]
	v_mfma_f32_16x16x32_bf16 v[50:53], v[154:157], v[162:165], v[50:53]
	v_mfma_f32_16x16x32_bf16 v[38:41], v[146:149], v[170:173], v[38:41]
	v_mfma_f32_16x16x32_bf16 v[34:37], v[154:157], v[170:173], v[34:37]
	v_mfma_f32_16x16x32_bf16 v[22:25], v[146:149], v[178:181], v[22:25]
	v_mfma_f32_16x16x32_bf16 v[18:21], v[154:157], v[178:181], v[18:21]
	v_mfma_f32_16x16x32_bf16 v[6:9], v[146:149], v[186:189], v[6:9]
	v_mfma_f32_16x16x32_bf16 v[2:5], v[154:157], v[186:189], v[2:5]
	v_mfma_f32_16x16x32_bf16 v[54:57], v[150:153], v[166:169], v[54:57]
	v_mfma_f32_16x16x32_bf16 v[50:53], v[158:161], v[166:169], v[50:53]
	v_mfma_f32_16x16x32_bf16 v[38:41], v[150:153], v[174:177], v[38:41]
	v_mfma_f32_16x16x32_bf16 v[34:37], v[158:161], v[174:177], v[34:37]
	v_mfma_f32_16x16x32_bf16 v[22:25], v[150:153], v[182:185], v[22:25]
	v_mfma_f32_16x16x32_bf16 v[18:21], v[158:161], v[182:185], v[18:21]
	v_mfma_f32_16x16x32_bf16 v[6:9], v[150:153], v[190:193], v[6:9]
	v_mfma_f32_16x16x32_bf16 v[2:5], v[158:161], v[190:193], v[2:5]
	s_barrier
	s_setprio 0
	s_add_i32 s40, s40, 2
	s_add_u32 s10, s10, 0x100
	s_addc_u32 s11, s11, 0
	s_cmp_gt_u32 s40, 13
	s_cbranch_scc1 .LBB0_425

; #define PG8_STAGE(bufoff, gbase, voff) do { _Pragma("unroll") for (int _i = 0; _i < 2; ++_i) \
;         __builtin_amdgcn_global_load_lds((const unsigned*)((const char*)(gbase) + (voff)[_i]), (PG8_LAS unsigned*)(lds + (bufoff) + ldsw + _i * 8192), 16, 0, 0); } while (0)
; #define PG8_LDA(dst, b, h) do { _Pragma("unroll") for (int m = 0; m < 4; ++m) _Pragma("unroll") for (int k = 0; k < 2; ++k) dst[m][k] = *(const PG8_LAS bf16x8*)(lds + PG8_SA(b, h) + aoff + m * 2048 + k * 1024); } while (0)
; #define PG8_LDB(dst, b, h) do { _Pragma("unroll") for (int n = 0; n < 2; ++n) _Pragma("unroll") for (int k = 0; k < 2; ++k) dst[n][k] = *(const PG8_LAS bf16x8*)(lds + PG8_SB(b, h) + boff + n * 2048 + k * 1024); } while (0)
; #define PG8_WAIT_V(n) asm volatile("s_waitcnt vmcnt(" #n ")" ::: "memory")
; #define PG8_WAIT_VN(n) asm volatile("s_waitcnt vmcnt(%0)" :: "n"(n) : "memory")
; #define PG8_WAIT_L(n) asm volatile("s_waitcnt lgkmcnt(" #n ")" ::: "memory")
; template <class Epi, class Sched, bool ALIGN_EPI = false, bool SP2 = false>
; __device__ __forceinline__ void gemm_phase(PG8_LAS unsigned char* lds, const Gemm g, const Sched& S, const Epi& E, const int wave_id) {
;     ...
;         for (int t = 0; t < nt; t += 2) {
;             const bool last = (t == nt - 2);
;             const char* a1 = cA + (size_t)(t + 1) * kstep;
;             const char* a2 = last ? nA : cA + (size_t)(t + 2) * kstep; const char* b2 = last ? nB : cB + (size_t)(t + 2) * kstep;
;             const char* a3 = a2 + kstep; const char* b3 = b2 + kstep;
;             if (last && has_next) S.a_ready(nxt);
;             if constexpr (SP2) {
;             int tz_ = __builtin_amdgcn_readfirstlane(t | (ui > 0 ? 0 : 1)); asm volatile("" : "+s"(tz_));
;             const bool strict = !(Epi::NS > 0 && tz_ == 0);
;             PG8_LDB(B0, 0, 0); PG8_LDB(B1, 0, 1); PG8_SCHED; PG8_LDA(At, 0, 0); PG8_STAGE(PG8_SA(1, 1), a1 + hstep, voffA);
;             PG8_WAIT_VN(8 + Epi::NS); if (strict) PG8_WAIT_V(8); PG8_WAIT_L(0); PG8_BAR; PG8_MMA(0, 0, At, B0); PG8_MMA(0, 1, At, B1); PG8_BAR; PG8_SCHED;
;             PG8_LDA(At, 0, 1); PG8_STAGE(PG8_SB(0, 0), b2, voffB); PG8_STAGE(PG8_SB(0, 1), b2 + hstep, voffB); PG8_STAGE(PG8_SA(0, 0), a2, voffA);
;             PG8_WAIT_VN(8 + Epi::NS); if (strict) PG8_WAIT_V(8); PG8_WAIT_L(0); PG8_BAR; PG8_MMA(1, 0, At, B0); PG8_MMA(1, 1, At, B1); PG8_BAR; PG8_SCHED;
.LBB0_423:
	s_add_u32 s12, s8, s10
	s_addc_u32 s13, s9, s11
	s_add_u32 s12, s12, 0x100
	s_addc_u32 s13, s13, 0
	s_add_u32 s41, s36, s10
	s_addc_u32 s42, s37, s11
	s_cmpk_eq_i32 s10, 0x700
	s_cselect_b32 s15, s23, s13
	s_cselect_b32 s14, s29, s12
	s_cselect_b32 s13, s21, s42
	s_cselect_b32 s12, s31, s41
	s_waitcnt lgkmcnt(0)
	s_setprio 1
	s_barrier
	v_mfma_f32_16x16x32_bf16 v[126:129], v[146:149], v[186:189], v[126:129]
	v_mfma_f32_16x16x32_bf16 v[122:125], v[154:157], v[186:189], v[122:125]
	v_mfma_f32_16x16x32_bf16 v[110:113], v[146:149], v[178:181], v[110:113]
	v_mfma_f32_16x16x32_bf16 v[106:109], v[154:157], v[178:181], v[106:109]
	v_mfma_f32_16x16x32_bf16 v[94:97], v[146:149], v[170:173], v[94:97]
	v_mfma_f32_16x16x32_bf16 v[90:93], v[154:157], v[170:173], v[90:93]
	v_mfma_f32_16x16x32_bf16 v[78:81], v[146:149], v[162:165], v[78:81]
	v_mfma_f32_16x16x32_bf16 v[74:77], v[154:157], v[162:165], v[74:77]
	v_mfma_f32_16x16x32_bf16 v[126:129], v[150:153], v[190:193], v[126:129]
	v_mfma_f32_16x16x32_bf16 v[122:125], v[158:161], v[190:193], v[122:125]
	v_mfma_f32_16x16x32_bf16 v[110:113], v[150:153], v[182:185], v[110:113]
	v_mfma_f32_16x16x32_bf16 v[106:109], v[158:161], v[182:185], v[106:109]
	v_mfma_f32_16x16x32_bf16 v[94:97], v[150:153], v[174:177], v[94:97]
	v_mfma_f32_16x16x32_bf16 v[90:93], v[158:161], v[174:177], v[90:93]
	v_mfma_f32_16x16x32_bf16 v[78:81], v[150:153], v[166:169], v[78:81]
	v_mfma_f32_16x16x32_bf16 v[74:77], v[158:161], v[166:169], v[74:77]
	s_setprio 0
	s_setprio 1
	v_mfma_f32_16x16x32_bf16 v[118:121], v[130:133], v[186:189], v[118:121]
	v_mfma_f32_16x16x32_bf16 v[114:117], v[138:141], v[186:189], v[114:117]
	v_mfma_f32_16x16x32_bf16 v[102:105], v[130:133], v[178:181], v[102:105]
	v_mfma_f32_16x16x32_bf16 v[98:101], v[138:141], v[178:181], v[98:101]
	v_mfma_f32_16x16x32_bf16 v[86:89], v[130:133], v[170:173], v[86:89]
	v_mfma_f32_16x16x32_bf16 v[82:85], v[138:141], v[170:173], v[82:85]
	v_mfma_f32_16x16x32_bf16 v[70:73], v[130:133], v[162:165], v[70:73]
	v_mfma_f32_16x16x32_bf16 v[66:69], v[138:141], v[162:165], v[66:69]
	v_mfma_f32_16x16x32_bf16 v[118:121], v[134:137], v[190:193], v[118:121]
	v_mfma_f32_16x16x32_bf16 v[114:117], v[142:145], v[190:193], v[114:117]
	v_mfma_f32_16x16x32_bf16 v[102:105], v[134:137], v[182:185], v[102:105]
	v_mfma_f32_16x16x32_bf16 v[98:101], v[142:145], v[182:185], v[98:101]
	v_mfma_f32_16x16x32_bf16 v[86:89], v[134:137], v[174:177], v[86:89]
	v_mfma_f32_16x16x32_bf16 v[82:85], v[142:145], v[174:177], v[82:85]
	v_mfma_f32_16x16x32_bf16 v[70:73], v[134:137], v[166:169], v[70:73]
	v_mfma_f32_16x16x32_bf16 v[66:69], v[142:145], v[166:169], v[66:69]
	s_barrier
	s_setprio 0
	s_mov_b32 m0, s94
	v_lshl_add_u64 v[232:233], s[12:13], 0, v[212:213]
	s_add_u32 s42, s12, 0x40000
	ds_read_b128 v[186:189], v247 offset:16384
	ds_read_b128 v[190:193], v247 offset:17408
	ds_read_b128 v[178:181], v247 offset:18432
	ds_read_b128 v[182:185], v247 offset:19456
	ds_read_b128 v[170:173], v247 offset:20480
	ds_read_b128 v[174:177], v247 offset:21504
	ds_read_b128 v[162:165], v247 offset:22528
	ds_read_b128 v[166:169], v247 offset:23552
	global_load_lds_dwordx4 v[232:233], off
	v_lshl_add_u64 v[230:231], s[12:13], 0, v[216:217]
	s_mov_b32 m0, s95
	s_addc_u32 s43, s13, 0
	global_load_lds_dwordx4 v[230:231], off
	v_lshl_add_u64 v[194:195], s[42:43], 0, v[212:213]
	s_mov_b32 m0, s38
	v_lshl_add_u64 v[226:227], s[14:15], 0, v[210:211]
	global_load_lds_dwordx4 v[194:195], off
	v_lshl_add_u64 v[194:195], s[42:43], 0, v[216:217]
	s_mov_b32 m0, s39
	v_lshl_add_u64 v[228:229], s[14:15], 0, v[214:215]
	global_load_lds_dwordx4 v[194:195], off
	s_mov_b32 m0, s91
	s_andn2_b64 vcc, exec, s[34:35]
	global_load_lds_dwordx4 v[226:227], off
	s_mov_b32 m0, s2
	s_nop 0
	global_load_lds_dwordx4 v[228:229], off
	s_waitcnt vmcnt(24)
	s_cbranch_vccnz .LBB0_420
	s_waitcnt vmcnt(8)
	s_branch .LBB0_420

; #define PG8_STAGE(bufoff, gbase, voff) do { _Pragma("unroll") for (int _i = 0; _i < 2; ++_i) \
;         __builtin_amdgcn_global_load_lds((const unsigned*)((const char*)(gbase) + (voff)[_i]), (PG8_LAS unsigned*)(lds + (bufoff) + ldsw + _i * 8192), 16, 0, 0); } while (0)
; #define PG8_LDA(dst, b, h) do { _Pragma("unroll") for (int m = 0; m < 4; ++m) _Pragma("unroll") for (int k = 0; k < 2; ++k) dst[m][k] = *(const PG8_LAS bf16x8*)(lds + PG8_SA(b, h) + aoff + m * 2048 + k * 1024); } while (0)
; #define PG8_LDB(dst, b, h) do { _Pragma("unroll") for (int n = 0; n < 2; ++n) _Pragma("unroll") for (int k = 0; k < 2; ++k) dst[n][k] = *(const PG8_LAS bf16x8*)(lds + PG8_SB(b, h) + boff + n * 2048 + k * 1024); } while (0)
; #define PG8_MMA(ai, bj, At, Bt) do { __builtin_amdgcn_s_setprio(1); _Pragma("unroll") for (int m = 0; m < 4; ++m) _Pragma("unroll") for (int n = 0; n < 2; ++n) _Pragma("unroll") for (int k = 0; k < 2; ++k) \
;         acc[ai][bj][m][n] = __builtin_amdgcn_mfma_f32_16x16x32_bf16(Bt[n][k], At[m][k], acc[ai][bj][m][n], 0, 0, 0); __builtin_amdgcn_s_setprio(0); } while (0)
; #define PG8_WAIT_V(n) asm volatile("s_waitcnt vmcnt(" #n ")" ::: "memory")
; #define PG8_WAIT_VN(n) asm volatile("s_waitcnt vmcnt(%0)" :: "n"(n) : "memory")
; #define PG8_WAIT_L(n) asm volatile("s_waitcnt lgkmcnt(" #n ")" ::: "memory")
; #define PG8_BAR __builtin_amdgcn_s_barrier()
; #define PG8_SCHED __builtin_amdgcn_sched_barrier(0)
; template <class Epi, class Sched, bool ALIGN_EPI = false, bool SP2 = false>
; __device__ __forceinline__ void gemm_phase(PG8_LAS unsigned char* lds, const Gemm g, const Sched& S, const Epi& E, const int wave_id) {
;     ...
;             PG8_WAIT_VN(8 + Epi::NS); if (strict) PG8_WAIT_V(8); PG8_WAIT_L(0); PG8_BAR; PG8_MMA(0, 0, At, B0); PG8_MMA(0, 1, At, B1); PG8_BAR; PG8_SCHED;
;             PG8_LDA(At, 0, 1); PG8_STAGE(PG8_SB(0, 0), b2, voffB); PG8_STAGE(PG8_SB(0, 1), b2 + hstep, voffB); PG8_STAGE(PG8_SA(0, 0), a2, voffA);
;             PG8_WAIT_VN(8 + Epi::NS); if (strict) PG8_WAIT_V(8); PG8_WAIT_L(0); PG8_BAR; PG8_MMA(1, 0, At, B0); PG8_MMA(1, 1, At, B1); PG8_BAR; PG8_SCHED;
;             PG8_LDB(B0, 1, 0); PG8_LDB(B1, 1, 1); PG8_SCHED; PG8_LDA(At, 1, 0); PG8_STAGE(PG8_SA(0, 1), a2 + hstep, voffA);
;             PG8_WAIT_V(8); PG8_WAIT_L(0); PG8_BAR; PG8_MMA(0, 0, At, B0); PG8_MMA(0, 1, At, B1); PG8_BAR; PG8_SCHED;
.LBB0_1504:
	s_waitcnt lgkmcnt(0)
	s_setprio 1
	s_barrier
	v_mfma_f32_16x16x32_bf16 v[62:65], v[146:149], v[186:189], v[62:65]
	v_mfma_f32_16x16x32_bf16 v[58:61], v[154:157], v[186:189], v[58:61]
	v_mfma_f32_16x16x32_bf16 v[46:49], v[146:149], v[178:181], v[46:49]
	v_mfma_f32_16x16x32_bf16 v[42:45], v[154:157], v[178:181], v[42:45]
	v_mfma_f32_16x16x32_bf16 v[30:33], v[146:149], v[170:173], v[30:33]
	v_mfma_f32_16x16x32_bf16 v[26:29], v[154:157], v[170:173], v[26:29]
	v_mfma_f32_16x16x32_bf16 v[14:17], v[146:149], v[162:165], v[14:17]
	v_mfma_f32_16x16x32_bf16 v[10:13], v[154:157], v[162:165], v[10:13]
	v_mfma_f32_16x16x32_bf16 v[62:65], v[150:153], v[190:193], v[62:65]
	v_mfma_f32_16x16x32_bf16 v[58:61], v[158:161], v[190:193], v[58:61]
	v_mfma_f32_16x16x32_bf16 v[46:49], v[150:153], v[182:185], v[46:49]
	v_mfma_f32_16x16x32_bf16 v[42:45], v[158:161], v[182:185], v[42:45]
	v_mfma_f32_16x16x32_bf16 v[30:33], v[150:153], v[174:177], v[30:33]
	v_mfma_f32_16x16x32_bf16 v[26:29], v[158:161], v[174:177], v[26:29]
	v_mfma_f32_16x16x32_bf16 v[14:17], v[150:153], v[166:169], v[14:17]
	v_mfma_f32_16x16x32_bf16 v[10:13], v[158:161], v[166:169], v[10:13]
	s_setprio 0
	s_setprio 1
	v_mfma_f32_16x16x32_bf16 v[54:57], v[130:133], v[186:189], v[54:57]
	v_mfma_f32_16x16x32_bf16 v[50:53], v[138:141], v[186:189], v[50:53]
	v_mfma_f32_16x16x32_bf16 v[38:41], v[130:133], v[178:181], v[38:41]
	v_mfma_f32_16x16x32_bf16 v[34:37], v[138:141], v[178:181], v[34:37]
	v_mfma_f32_16x16x32_bf16 v[22:25], v[130:133], v[170:173], v[22:25]
	v_mfma_f32_16x16x32_bf16 v[18:21], v[138:141], v[170:173], v[18:21]
	v_mfma_f32_16x16x32_bf16 v[6:9], v[130:133], v[162:165], v[6:9]
	v_mfma_f32_16x16x32_bf16 v[2:5], v[138:141], v[162:165], v[2:5]
	v_mfma_f32_16x16x32_bf16 v[54:57], v[134:137], v[190:193], v[54:57]
	v_mfma_f32_16x16x32_bf16 v[50:53], v[142:145], v[190:193], v[50:53]
	v_mfma_f32_16x16x32_bf16 v[38:41], v[134:137], v[182:185], v[38:41]
	v_mfma_f32_16x16x32_bf16 v[34:37], v[142:145], v[182:185], v[34:37]
	v_mfma_f32_16x16x32_bf16 v[22:25], v[134:137], v[174:177], v[22:25]
	v_mfma_f32_16x16x32_bf16 v[18:21], v[142:145], v[174:177], v[18:21]
	v_mfma_f32_16x16x32_bf16 v[6:9], v[134:137], v[166:169], v[6:9]
	v_mfma_f32_16x16x32_bf16 v[2:5], v[142:145], v[166:169], v[2:5]
	s_barrier
	s_setprio 0
	s_add_i32 s20, 0, 0x18000
	s_add_i32 s21, 0, 0x1c000
	v_add_u32_e32 v142, s20, v1
	v_add_u32_e32 v158, s21, v1
	ds_read_b128 v[130:133], v142
	ds_read_b128 v[134:137], v142 offset:1024
	ds_read_b128 v[138:141], v142 offset:2048
	ds_read_b128 v[142:145], v142 offset:3072
	ds_read_b128 v[146:149], v158
	ds_read_b128 v[150:153], v158 offset:1024
	ds_read_b128 v[154:157], v158 offset:2048
	ds_read_b128 v[158:161], v158 offset:3072
	s_add_u32 s18, s18, 0x40000
	s_addc_u32 s19, s19, 0
	s_mov_b32 m0, s35
	v_lshl_add_u64 v[194:195], s[18:19], 0, v[216:217]
	ds_read_b128 v[162:165], v232 offset:32768
	ds_read_b128 v[166:169], v232 offset:33792
	ds_read_b128 v[170:173], v232 offset:34816
	ds_read_b128 v[174:177], v232 offset:35840
	ds_read_b128 v[178:181], v232 offset:36864
	ds_read_b128 v[182:185], v232 offset:37888
	ds_read_b128 v[186:189], v232 offset:38912
	ds_read_b128 v[190:193], v232 offset:39936
	global_load_lds_dwordx4 v[194:195], off
	v_lshl_add_u64 v[194:195], s[18:19], 0, v[212:213]
	s_mov_b32 m0, s36
	s_nop 0
	global_load_lds_dwordx4 v[194:195], off
	s_waitcnt vmcnt(8)
	s_waitcnt lgkmcnt(0)
	s_setprio 1
	s_barrier
	v_mfma_f32_16x16x32_bf16 v[126:129], v[130:133], v[162:165], v[126:129]
	v_mfma_f32_16x16x32_bf16 v[122:125], v[138:141], v[162:165], v[122:125]
	v_mfma_f32_16x16x32_bf16 v[110:113], v[130:133], v[170:173], v[110:113]
	v_mfma_f32_16x16x32_bf16 v[106:109], v[138:141], v[170:173], v[106:109]
	v_mfma_f32_16x16x32_bf16 v[94:97], v[130:133], v[178:181], v[94:97]
	v_mfma_f32_16x16x32_bf16 v[90:93], v[138:141], v[178:181], v[90:93]
	v_mfma_f32_16x16x32_bf16 v[78:81], v[130:133], v[186:189], v[78:81]
	v_mfma_f32_16x16x32_bf16 v[74:77], v[138:141], v[186:189], v[74:77]
	v_mfma_f32_16x16x32_bf16 v[126:129], v[134:137], v[166:169], v[126:129]
	v_mfma_f32_16x16x32_bf16 v[122:125], v[142:145], v[166:169], v[122:125]
	v_mfma_f32_16x16x32_bf16 v[110:113], v[134:137], v[174:177], v[110:113]
	v_mfma_f32_16x16x32_bf16 v[106:109], v[142:145], v[174:177], v[106:109]
	v_mfma_f32_16x16x32_bf16 v[94:97], v[134:137], v[182:185], v[94:97]
	v_mfma_f32_16x16x32_bf16 v[90:93], v[142:145], v[182:185], v[90:93]
	v_mfma_f32_16x16x32_bf16 v[78:81], v[134:137], v[190:193], v[78:81]
	v_mfma_f32_16x16x32_bf16 v[74:77], v[142:145], v[190:193], v[74:77]
	s_setprio 0
	s_setprio 1
	v_mfma_f32_16x16x32_bf16 v[118:121], v[146:149], v[162:165], v[118:121]
	v_mfma_f32_16x16x32_bf16 v[114:117], v[154:157], v[162:165], v[114:117]
	v_mfma_f32_16x16x32_bf16 v[102:105], v[146:149], v[170:173], v[102:105]
	v_mfma_f32_16x16x32_bf16 v[98:101], v[154:157], v[170:173], v[98:101]
	v_mfma_f32_16x16x32_bf16 v[86:89], v[146:149], v[178:181], v[86:89]
	v_mfma_f32_16x16x32_bf16 v[82:85], v[154:157], v[178:181], v[82:85]
	v_mfma_f32_16x16x32_bf16 v[70:73], v[146:149], v[186:189], v[70:73]
	v_mfma_f32_16x16x32_bf16 v[66:69], v[154:157], v[186:189], v[66:69]
	v_mfma_f32_16x16x32_bf16 v[118:121], v[150:153], v[166:169], v[118:121]
	v_mfma_f32_16x16x32_bf16 v[114:117], v[158:161], v[166:169], v[114:117]
	v_mfma_f32_16x16x32_bf16 v[102:105], v[150:153], v[174:177], v[102:105]
	v_mfma_f32_16x16x32_bf16 v[98:101], v[158:161], v[174:177], v[98:101]
	v_mfma_f32_16x16x32_bf16 v[86:89], v[150:153], v[182:185], v[86:89]
	v_mfma_f32_16x16x32_bf16 v[82:85], v[158:161], v[182:185], v[82:85]
	v_mfma_f32_16x16x32_bf16 v[70:73], v[150:153], v[190:193], v[70:73]
	v_mfma_f32_16x16x32_bf16 v[66:69], v[158:161], v[190:193], v[66:69]
	s_barrier
; #define PG8_STAGE(bufoff, gbase, voff) do { _Pragma("unroll") for (int _i = 0; _i < 2; ++_i) \
;         __builtin_amdgcn_global_load_lds((const unsigned*)((const char*)(gbase) + (voff)[_i]), (PG8_LAS unsigned*)(lds + (bufoff) + ldsw + _i * 8192), 16, 0, 0); } while (0)
; #define PG8_LDA(dst, b, h) do { _Pragma("unroll") for (int m = 0; m < 4; ++m) _Pragma("unroll") for (int k = 0; k < 2; ++k) dst[m][k] = *(const PG8_LAS bf16x8*)(lds + PG8_SA(b, h) + aoff + m * 2048 + k * 1024); } while (0)
; #define PG8_MMA(ai, bj, At, Bt) do { __builtin_amdgcn_s_setprio(1); _Pragma("unroll") for (int m = 0; m < 4; ++m) _Pragma("unroll") for (int n = 0; n < 2; ++n) _Pragma("unroll") for (int k = 0; k < 2; ++k) \
;         acc[ai][bj][m][n] = __builtin_amdgcn_mfma_f32_16x16x32_bf16(Bt[n][k], At[m][k], acc[ai][bj][m][n], 0, 0, 0); __builtin_amdgcn_s_setprio(0); } while (0)
; #define PG8_WAIT_V(n) asm volatile("s_waitcnt vmcnt(" #n ")" ::: "memory")
; #define PG8_WAIT_L(n) asm volatile("s_waitcnt lgkmcnt(" #n ")" ::: "memory")
; #define PG8_BAR __builtin_amdgcn_s_barrier()
; #define PG8_SCHED __builtin_amdgcn_sched_barrier(0)
; template <class Epi, class Sched, bool ALIGN_EPI = false, bool SP2 = false>
; __device__ __forceinline__ void gemm_phase(PG8_LAS unsigned char* lds, const Gemm g, const Sched& S, const Epi& E, const int wave_id) {
;     ...
;         for (int t = 0; t < nt; t += 2) {
;     ...
;             PG8_LDA(At, 1, 1); PG8_STAGE(PG8_SB(1, 0), b3, voffB); PG8_STAGE(PG8_SB(1, 1), b3 + hstep, voffB); PG8_STAGE(PG8_SA(1, 0), a3, voffA);
;             PG8_WAIT_V(8); PG8_WAIT_L(0); PG8_BAR; PG8_MMA(1, 0, At, B0); PG8_MMA(1, 1, At, B1); PG8_BAR; PG8_SCHED;
	s_setprio 0
	s_add_i32 s18, s20, s24
	v_lshl_add_u64 v[194:195], v[228:229], 0, s[64:65]
	s_mov_b32 m0, s18
	ds_read_b128 v[162:165], v232 offset:49152
	ds_read_b128 v[166:169], v232 offset:50176
	ds_read_b128 v[170:173], v232 offset:51200
	ds_read_b128 v[174:177], v232 offset:52224
	ds_read_b128 v[178:181], v232 offset:53248
	ds_read_b128 v[182:185], v232 offset:54272
	ds_read_b128 v[186:189], v232 offset:55296
	ds_read_b128 v[190:193], v232 offset:56320
	global_load_lds_dwordx4 v[194:195], off
	s_add_i32 m0, s18, 0x2000
	s_add_u32 s16, s16, 0x40080
	v_lshl_add_u64 v[194:195], v[226:227], 0, s[64:65]
	s_addc_u32 s17, s17, 0
	s_add_i32 s18, s21, s24
	global_load_lds_dwordx4 v[194:195], off
	v_lshl_add_u64 v[194:195], s[16:17], 0, v[214:215]
	s_mov_b32 m0, s18
	s_nop 0
	global_load_lds_dwordx4 v[194:195], off
	v_lshl_add_u64 v[194:195], s[16:17], 0, v[210:211]
	s_add_i32 m0, s18, 0x2000
	s_nop 0
	global_load_lds_dwordx4 v[194:195], off
	v_lshl_add_u64 v[194:195], v[222:223], 0, s[64:65]
	s_mov_b32 m0, s37
	s_nop 0
	global_load_lds_dwordx4 v[194:195], off
	v_lshl_add_u64 v[194:195], v[224:225], 0, s[64:65]
	s_mov_b32 m0, s38
	s_nop 0
	global_load_lds_dwordx4 v[194:195], off
	s_waitcnt vmcnt(8)
	s_waitcnt lgkmcnt(0)
	s_setprio 1
	s_barrier
	v_mfma_f32_16x16x32_bf16 v[62:65], v[130:133], v[162:165], v[62:65]
	v_mfma_f32_16x16x32_bf16 v[58:61], v[138:141], v[162:165], v[58:61]
	v_mfma_f32_16x16x32_bf16 v[46:49], v[130:133], v[170:173], v[46:49]
	v_mfma_f32_16x16x32_bf16 v[42:45], v[138:141], v[170:173], v[42:45]
	v_mfma_f32_16x16x32_bf16 v[30:33], v[130:133], v[178:181], v[30:33]
	v_mfma_f32_16x16x32_bf16 v[26:29], v[138:141], v[178:181], v[26:29]
	v_mfma_f32_16x16x32_bf16 v[14:17], v[130:133], v[186:189], v[14:17]
	v_mfma_f32_16x16x32_bf16 v[10:13], v[138:141], v[186:189], v[10:13]
	v_mfma_f32_16x16x32_bf16 v[62:65], v[134:137], v[166:169], v[62:65]
	v_mfma_f32_16x16x32_bf16 v[58:61], v[142:145], v[166:169], v[58:61]
	v_mfma_f32_16x16x32_bf16 v[46:49], v[134:137], v[174:177], v[46:49]
	v_mfma_f32_16x16x32_bf16 v[42:45], v[142:145], v[174:177], v[42:45]
	v_mfma_f32_16x16x32_bf16 v[30:33], v[134:137], v[182:185], v[30:33]
	v_mfma_f32_16x16x32_bf16 v[26:29], v[142:145], v[182:185], v[26:29]
	v_mfma_f32_16x16x32_bf16 v[14:17], v[134:137], v[190:193], v[14:17]
	v_mfma_f32_16x16x32_bf16 v[10:13], v[142:145], v[190:193], v[10:13]
	s_setprio 0
	s_setprio 1
	v_mfma_f32_16x16x32_bf16 v[54:57], v[146:149], v[162:165], v[54:57]
	v_mfma_f32_16x16x32_bf16 v[50:53], v[154:157], v[162:165], v[50:53]
	v_mfma_f32_16x16x32_bf16 v[38:41], v[146:149], v[170:173], v[38:41]
	v_mfma_f32_16x16x32_bf16 v[34:37], v[154:157], v[170:173], v[34:37]
	v_mfma_f32_16x16x32_bf16 v[22:25], v[146:149], v[178:181], v[22:25]
	v_mfma_f32_16x16x32_bf16 v[18:21], v[154:157], v[178:181], v[18:21]
	v_mfma_f32_16x16x32_bf16 v[6:9], v[146:149], v[186:189], v[6:9]
	v_mfma_f32_16x16x32_bf16 v[2:5], v[154:157], v[186:189], v[2:5]
	v_mfma_f32_16x16x32_bf16 v[54:57], v[150:153], v[166:169], v[54:57]
	v_mfma_f32_16x16x32_bf16 v[50:53], v[158:161], v[166:169], v[50:53]
	v_mfma_f32_16x16x32_bf16 v[38:41], v[150:153], v[174:177], v[38:41]
	v_mfma_f32_16x16x32_bf16 v[34:37], v[158:161], v[174:177], v[34:37]
	v_mfma_f32_16x16x32_bf16 v[22:25], v[150:153], v[182:185], v[22:25]
	v_mfma_f32_16x16x32_bf16 v[18:21], v[158:161], v[182:185], v[18:21]
	v_mfma_f32_16x16x32_bf16 v[6:9], v[150:153], v[190:193], v[6:9]
	v_mfma_f32_16x16x32_bf16 v[2:5], v[158:161], v[190:193], v[2:5]
	s_barrier
	s_setprio 0
	s_add_u32 s12, s12, 0x100
	s_addc_u32 s13, s13, 0
	s_cmp_gt_u32 s43, 13
	s_cbranch_scc1 .LBB0_1526

; #define PG8_STAGE(bufoff, gbase, voff) do { _Pragma("unroll") for (int _i = 0; _i < 2; ++_i) \
;         __builtin_amdgcn_global_load_lds((const unsigned*)((const char*)(gbase) + (voff)[_i]), (PG8_LAS unsigned*)(lds + (bufoff) + ldsw + _i * 8192), 16, 0, 0); } while (0)
; #define PG8_LDA(dst, b, h) do { _Pragma("unroll") for (int m = 0; m < 4; ++m) _Pragma("unroll") for (int k = 0; k < 2; ++k) dst[m][k] = *(const PG8_LAS bf16x8*)(lds + PG8_SA(b, h) + aoff + m * 2048 + k * 1024); } while (0)
; #define PG8_LDB(dst, b, h) do { _Pragma("unroll") for (int n = 0; n < 2; ++n) _Pragma("unroll") for (int k = 0; k < 2; ++k) dst[n][k] = *(const PG8_LAS bf16x8*)(lds + PG8_SB(b, h) + boff + n * 2048 + k * 1024); } while (0)
; #define PG8_WAIT_V(n) asm volatile("s_waitcnt vmcnt(" #n ")" ::: "memory")
; #define PG8_WAIT_VN(n) asm volatile("s_waitcnt vmcnt(%0)" :: "n"(n) : "memory")
; #define PG8_WAIT_L(n) asm volatile("s_waitcnt lgkmcnt(" #n ")" ::: "memory")
; template <class Epi, class Sched, bool ALIGN_EPI = false, bool SP2 = false>
; __device__ __forceinline__ void gemm_phase(PG8_LAS unsigned char* lds, const Gemm g, const Sched& S, const Epi& E, const int wave_id) {
;     ...
;         for (int t = 0; t < nt; t += 2) {
;             const bool last = (t == nt - 2);
;             const char* a1 = cA + (size_t)(t + 1) * kstep;
;             const char* a2 = last ? nA : cA + (size_t)(t + 2) * kstep; const char* b2 = last ? nB : cB + (size_t)(t + 2) * kstep;
;             const char* a3 = a2 + kstep; const char* b3 = b2 + kstep;
;             if (last && has_next) S.a_ready(nxt);
;             if constexpr (SP2) {
;             int tz_ = __builtin_amdgcn_readfirstlane(t | (ui > 0 ? 0 : 1)); asm volatile("" : "+s"(tz_));
;             const bool strict = !(Epi::NS > 0 && tz_ == 0);
;             PG8_LDB(B0, 0, 0); PG8_LDB(B1, 0, 1); PG8_SCHED; PG8_LDA(At, 0, 0); PG8_STAGE(PG8_SA(1, 1), a1 + hstep, voffA);
;             PG8_WAIT_VN(8 + Epi::NS); if (strict) PG8_WAIT_V(8); PG8_WAIT_L(0); PG8_BAR; PG8_MMA(0, 0, At, B0); PG8_MMA(0, 1, At, B1); PG8_BAR; PG8_SCHED;
;             PG8_LDA(At, 0, 1); PG8_STAGE(PG8_SB(0, 0), b2, voffB); PG8_STAGE(PG8_SB(0, 1), b2 + hstep, voffB); PG8_STAGE(PG8_SA(0, 0), a2, voffA);
;             PG8_WAIT_VN(8 + Epi::NS); if (strict) PG8_WAIT_V(8); PG8_WAIT_L(0); PG8_BAR; PG8_MMA(1, 0, At, B0); PG8_MMA(1, 1, At, B1); PG8_BAR; PG8_SCHED;
.LBB0_1507:
	s_add_u32 s16, s41, s12
	s_addc_u32 s17, s42, s13
	s_add_u32 s16, s16, 0x8f2c0100
	s_addc_u32 s17, s17, 0
	s_add_u32 s49, s39, s12
	s_addc_u32 s50, s40, s13
	s_cmpk_eq_i32 s12, 0x700
	s_cselect_b32 s19, s11, s17
	s_cselect_b32 s18, s10, s16
	s_cselect_b32 s17, s9, s50
	s_cselect_b32 s16, s8, s49
	s_waitcnt lgkmcnt(0)
	s_setprio 1
	s_barrier
	v_mfma_f32_16x16x32_bf16 v[126:129], v[146:149], v[186:189], v[126:129]
	v_mfma_f32_16x16x32_bf16 v[122:125], v[154:157], v[186:189], v[122:125]
	v_mfma_f32_16x16x32_bf16 v[110:113], v[146:149], v[178:181], v[110:113]
	v_mfma_f32_16x16x32_bf16 v[106:109], v[154:157], v[178:181], v[106:109]
	v_mfma_f32_16x16x32_bf16 v[94:97], v[146:149], v[170:173], v[94:97]
	v_mfma_f32_16x16x32_bf16 v[90:93], v[154:157], v[170:173], v[90:93]
	v_mfma_f32_16x16x32_bf16 v[78:81], v[146:149], v[162:165], v[78:81]
	v_mfma_f32_16x16x32_bf16 v[74:77], v[154:157], v[162:165], v[74:77]
	v_mfma_f32_16x16x32_bf16 v[126:129], v[150:153], v[190:193], v[126:129]
	v_mfma_f32_16x16x32_bf16 v[122:125], v[158:161], v[190:193], v[122:125]
	v_mfma_f32_16x16x32_bf16 v[110:113], v[150:153], v[182:185], v[110:113]
	v_mfma_f32_16x16x32_bf16 v[106:109], v[158:161], v[182:185], v[106:109]
	v_mfma_f32_16x16x32_bf16 v[94:97], v[150:153], v[174:177], v[94:97]
	v_mfma_f32_16x16x32_bf16 v[90:93], v[158:161], v[174:177], v[90:93]
	v_mfma_f32_16x16x32_bf16 v[78:81], v[150:153], v[166:169], v[78:81]
	v_mfma_f32_16x16x32_bf16 v[74:77], v[158:161], v[166:169], v[74:77]
	s_setprio 0
	s_setprio 1
	v_mfma_f32_16x16x32_bf16 v[118:121], v[130:133], v[186:189], v[118:121]
	v_mfma_f32_16x16x32_bf16 v[114:117], v[138:141], v[186:189], v[114:117]
	v_mfma_f32_16x16x32_bf16 v[102:105], v[130:133], v[178:181], v[102:105]
	v_mfma_f32_16x16x32_bf16 v[98:101], v[138:141], v[178:181], v[98:101]
	v_mfma_f32_16x16x32_bf16 v[86:89], v[130:133], v[170:173], v[86:89]
	v_mfma_f32_16x16x32_bf16 v[82:85], v[138:141], v[170:173], v[82:85]
	v_mfma_f32_16x16x32_bf16 v[70:73], v[130:133], v[162:165], v[70:73]
	v_mfma_f32_16x16x32_bf16 v[66:69], v[138:141], v[162:165], v[66:69]
	v_mfma_f32_16x16x32_bf16 v[118:121], v[134:137], v[190:193], v[118:121]
	v_mfma_f32_16x16x32_bf16 v[114:117], v[142:145], v[190:193], v[114:117]
	v_mfma_f32_16x16x32_bf16 v[102:105], v[134:137], v[182:185], v[102:105]
	v_mfma_f32_16x16x32_bf16 v[98:101], v[142:145], v[182:185], v[98:101]
	v_mfma_f32_16x16x32_bf16 v[86:89], v[134:137], v[174:177], v[86:89]
	v_mfma_f32_16x16x32_bf16 v[82:85], v[142:145], v[174:177], v[82:85]
	v_mfma_f32_16x16x32_bf16 v[70:73], v[134:137], v[166:169], v[70:73]
	v_mfma_f32_16x16x32_bf16 v[66:69], v[142:145], v[166:169], v[66:69]
	s_barrier
	s_setprio 0
	s_mov_b32 m0, s26
	v_lshl_add_u64 v[228:229], s[16:17], 0, v[214:215]
	s_add_u32 s50, s16, 0x40000
	ds_read_b128 v[186:189], v232 offset:16384
	ds_read_b128 v[190:193], v232 offset:17408
	ds_read_b128 v[178:181], v232 offset:18432
	ds_read_b128 v[182:185], v232 offset:19456
	ds_read_b128 v[170:173], v232 offset:20480
	ds_read_b128 v[174:177], v232 offset:21504
	ds_read_b128 v[162:165], v232 offset:22528
	ds_read_b128 v[166:169], v232 offset:23552
	global_load_lds_dwordx4 v[228:229], off
	v_lshl_add_u64 v[226:227], s[16:17], 0, v[210:211]
	s_mov_b32 m0, s27
	s_addc_u32 s51, s17, 0
	global_load_lds_dwordx4 v[226:227], off
	v_lshl_add_u64 v[194:195], s[50:51], 0, v[214:215]
	s_mov_b32 m0, s29
	v_lshl_add_u64 v[222:223], s[18:19], 0, v[216:217]
	global_load_lds_dwordx4 v[194:195], off
	v_lshl_add_u64 v[194:195], s[50:51], 0, v[210:211]
	s_mov_b32 m0, s30
	v_lshl_add_u64 v[224:225], s[18:19], 0, v[212:213]
	global_load_lds_dwordx4 v[194:195], off
	s_mov_b32 m0, s25
	s_andn2_b64 vcc, exec, s[20:21]
	global_load_lds_dwordx4 v[222:223], off
	s_mov_b32 m0, s34
	s_nop 0
	global_load_lds_dwordx4 v[224:225], off
	s_waitcnt vmcnt(24)
	s_cbranch_vccnz .LBB0_1504
	s_waitcnt vmcnt(8)
	s_branch .LBB0_1504

; #define PG8_STAGE(bufoff, gbase, voff) do { _Pragma("unroll") for (int _i = 0; _i < 2; ++_i) \
;         __builtin_amdgcn_global_load_lds((const unsigned*)((const char*)(gbase) + (voff)[_i]), (PG8_LAS unsigned*)(lds + (bufoff) + ldsw + _i * 8192), 16, 0, 0); } while (0)
; #define PG8_LDA(dst, b, h) do { _Pragma("unroll") for (int m = 0; m < 4; ++m) _Pragma("unroll") for (int k = 0; k < 2; ++k) dst[m][k] = *(const PG8_LAS bf16x8*)(lds + PG8_SA(b, h) + aoff + m * 2048 + k * 1024); } while (0)
; #define PG8_LDB(dst, b, h) do { _Pragma("unroll") for (int n = 0; n < 2; ++n) _Pragma("unroll") for (int k = 0; k < 2; ++k) dst[n][k] = *(const PG8_LAS bf16x8*)(lds + PG8_SB(b, h) + boff + n * 2048 + k * 1024); } while (0)
; template <class Epi, class Sched, bool ALIGN_EPI = false, bool SP2 = false>
; __device__ __forceinline__ void gemm_phase(PG8_LAS unsigned char* lds, const Gemm g, const Sched& S, const Epi& E, const int wave_id) {
;     ...
;         for (int t = 0; t < nt; t += 2) {
;             const bool last = (t == nt - 2);
;             const char* a1 = cA + (size_t)(t + 1) * kstep;
;             const char* a2 = last ? nA : cA + (size_t)(t + 2) * kstep; const char* b2 = last ? nB : cB + (size_t)(t + 2) * kstep;
;             const char* a3 = a2 + kstep; const char* b3 = b2 + kstep;
;             if (last && has_next) S.a_ready(nxt);
;             if constexpr (SP2) {
;             int tz_ = __builtin_amdgcn_readfirstlane(t | (ui > 0 ? 0 : 1)); asm volatile("" : "+s"(tz_));
;             const bool strict = !(Epi::NS > 0 && tz_ == 0);
;             PG8_LDB(B0, 0, 0); PG8_LDB(B1, 0, 1); PG8_SCHED; PG8_LDA(At, 0, 0); PG8_STAGE(PG8_SA(1, 1), a1 + hstep, voffA);
;             PG8_WAIT_VN(8 + Epi::NS); if (strict) PG8_WAIT_V(8); PG8_WAIT_L(0); PG8_BAR; PG8_MMA(0, 0, At, B0); PG8_MMA(0, 1, At, B1); PG8_BAR; PG8_SCHED;
;             PG8_LDA(At, 0, 1); PG8_STAGE(PG8_SB(0, 0), b2, voffB); PG8_STAGE(PG8_SB(0, 1), b2 + hstep, voffB); PG8_STAGE(PG8_SA(0, 0), a2, voffA);
;             PG8_WAIT_VN(8 + Epi::NS); if (strict) PG8_WAIT_V(8); PG8_WAIT_L(0); PG8_BAR; PG8_MMA(1, 0, At, B0); PG8_MMA(1, 1, At, B1); PG8_BAR; PG8_SCHED;
;             PG8_LDB(B0, 1, 0); PG8_LDB(B1, 1, 1); PG8_SCHED; PG8_LDA(At, 1, 0); PG8_STAGE(PG8_SA(0, 1), a2 + hstep, voffA);
;             PG8_WAIT_V(8); PG8_WAIT_L(0); PG8_BAR; PG8_MMA(0, 0, At, B0); PG8_MMA(0, 1, At, B1); PG8_BAR; PG8_SCHED;
.LBB0_1537:
	s_add_u32 s12, s8, s10
	s_addc_u32 s13, s9, s11
	s_add_u32 s12, s12, 0x100
	s_addc_u32 s13, s13, 0
	s_add_u32 s53, s67, s10
	s_addc_u32 s76, s68, s11
	s_add_i32 s69, s69, 2
	s_add_i32 s78, 0, 0x10000
	v_add_u32_e32 v147, s69, v146
	s_cmpk_eq_i32 s10, 0x700
	s_cselect_b32 s26, s57, s12
	v_readfirstlane_b32 s12, v147
	s_cselect_b32 s27, s56, s13
	v_add_u32_e32 v147, s78, v163
	s_cselect_b32 s13, s62, s76
	s_cselect_b32 s12, s63, s53
	s_add_i32 s53, 0, 0x14000
	ds_read_b128 v[148:151], v147
	ds_read_b128 v[152:155], v147 offset:1024
	ds_read_b128 v[156:159], v147 offset:2048
	ds_read_b128 v[166:169], v147 offset:3072
	v_add_u32_e32 v147, s53, v163
	ds_read_b128 v[170:173], v147
	ds_read_b128 v[174:177], v147 offset:1024
	ds_read_b128 v[178:181], v147 offset:2048
	ds_read_b128 v[182:185], v147 offset:3072
	v_lshl_add_u64 v[160:161], v[144:145], 0, s[10:11]
	s_add_i32 m0, s17, 0xc000
	ds_read_b128 v[186:189], v164
	ds_read_b128 v[190:193], v164 offset:1024
	ds_read_b128 v[194:197], v164 offset:2048
	ds_read_b128 v[198:201], v164 offset:3072
	ds_read_b128 v[202:205], v164 offset:4096
	ds_read_b128 v[206:209], v164 offset:5120
	ds_read_b128 v[210:213], v164 offset:6144
	ds_read_b128 v[214:217], v164 offset:7168
	global_load_lds_dwordx4 v[160:161], off
	v_lshl_add_u64 v[160:161], v[142:143], 0, s[10:11]
	s_add_i32 m0, s17, 0xe000
	s_nop 0
	global_load_lds_dwordx4 v[160:161], off
	s_waitcnt vmcnt(8)
	s_waitcnt vmcnt(8)
	s_waitcnt lgkmcnt(0)
	s_setprio 1
	s_barrier
	v_mfma_f32_16x16x32_bf16 v[126:129], v[148:151], v[186:189], v[126:129]
	v_mfma_f32_16x16x32_bf16 v[122:125], v[156:159], v[186:189], v[122:125]
	v_mfma_f32_16x16x32_bf16 v[118:121], v[148:151], v[194:197], v[118:121]
	v_mfma_f32_16x16x32_bf16 v[114:117], v[156:159], v[194:197], v[114:117]
	v_mfma_f32_16x16x32_bf16 v[110:113], v[148:151], v[202:205], v[110:113]
	v_mfma_f32_16x16x32_bf16 v[106:109], v[156:159], v[202:205], v[106:109]
	v_mfma_f32_16x16x32_bf16 v[102:105], v[148:151], v[210:213], v[102:105]
	v_mfma_f32_16x16x32_bf16 v[98:101], v[156:159], v[210:213], v[98:101]
	v_mfma_f32_16x16x32_bf16 v[126:129], v[152:155], v[190:193], v[126:129]
	v_mfma_f32_16x16x32_bf16 v[122:125], v[166:169], v[190:193], v[122:125]
	v_mfma_f32_16x16x32_bf16 v[118:121], v[152:155], v[198:201], v[118:121]
	v_mfma_f32_16x16x32_bf16 v[114:117], v[166:169], v[198:201], v[114:117]
	v_mfma_f32_16x16x32_bf16 v[110:113], v[152:155], v[206:209], v[110:113]
	v_mfma_f32_16x16x32_bf16 v[106:109], v[166:169], v[206:209], v[106:109]
	v_mfma_f32_16x16x32_bf16 v[102:105], v[152:155], v[214:217], v[102:105]
	v_mfma_f32_16x16x32_bf16 v[98:101], v[166:169], v[214:217], v[98:101]
	s_setprio 0
	s_setprio 1
	v_mfma_f32_16x16x32_bf16 v[94:97], v[170:173], v[186:189], v[94:97]
	v_mfma_f32_16x16x32_bf16 v[90:93], v[178:181], v[186:189], v[90:93]
	v_mfma_f32_16x16x32_bf16 v[86:89], v[170:173], v[194:197], v[86:89]
	v_mfma_f32_16x16x32_bf16 v[82:85], v[178:181], v[194:197], v[82:85]
	v_mfma_f32_16x16x32_bf16 v[78:81], v[170:173], v[202:205], v[78:81]
	v_mfma_f32_16x16x32_bf16 v[74:77], v[178:181], v[202:205], v[74:77]
	v_mfma_f32_16x16x32_bf16 v[70:73], v[170:173], v[210:213], v[70:73]
	v_mfma_f32_16x16x32_bf16 v[66:69], v[178:181], v[210:213], v[66:69]
	v_mfma_f32_16x16x32_bf16 v[94:97], v[174:177], v[190:193], v[94:97]
	v_mfma_f32_16x16x32_bf16 v[90:93], v[182:185], v[190:193], v[90:93]
	v_mfma_f32_16x16x32_bf16 v[86:89], v[174:177], v[198:201], v[86:89]
	v_mfma_f32_16x16x32_bf16 v[82:85], v[182:185], v[198:201], v[82:85]
	v_mfma_f32_16x16x32_bf16 v[78:81], v[174:177], v[206:209], v[78:81]
	v_mfma_f32_16x16x32_bf16 v[74:77], v[182:185], v[206:209], v[74:77]
	v_mfma_f32_16x16x32_bf16 v[70:73], v[174:177], v[214:217], v[70:73]
	v_mfma_f32_16x16x32_bf16 v[66:69], v[182:185], v[214:217], v[66:69]
	s_barrier
	s_setprio 0
	s_add_i32 s76, s78, s35
	v_lshl_add_u64 v[160:161], s[12:13], 0, v[132:133]
	s_mov_b32 m0, s76
	ds_read_b128 v[186:189], v164 offset:16384
	ds_read_b128 v[190:193], v164 offset:17408
	ds_read_b128 v[194:197], v164 offset:18432
	ds_read_b128 v[198:201], v164 offset:19456
	ds_read_b128 v[202:205], v164 offset:20480
	ds_read_b128 v[206:209], v164 offset:21504
	ds_read_b128 v[210:213], v164 offset:22528
	ds_read_b128 v[214:217], v164 offset:23552
	global_load_lds_dwordx4 v[160:161], off
	s_add_i32 m0, s76, 0x2000
	s_add_u32 s90, s12, 0x40000
	v_lshl_add_u64 v[218:219], s[12:13], 0, v[136:137]
	s_addc_u32 s91, s13, 0
	s_add_i32 s53, s53, s35
	global_load_lds_dwordx4 v[218:219], off
	v_lshl_add_u64 v[220:221], s[90:91], 0, v[132:133]
	s_mov_b32 m0, s53
	v_lshl_add_u64 v[222:223], s[26:27], 0, v[134:135]
	global_load_lds_dwordx4 v[220:221], off
	v_lshl_add_u64 v[220:221], s[90:91], 0, v[136:137]
	s_add_i32 m0, s53, 0x2000
	s_nop 0
	global_load_lds_dwordx4 v[220:221], off
	v_lshl_add_u64 v[220:221], s[26:27], 0, v[130:131]
	s_mov_b32 m0, s17
	s_nop 0
	global_load_lds_dwordx4 v[220:221], off
	s_mov_b32 m0, s37
	s_nop 0
	global_load_lds_dwordx4 v[222:223], off
	s_waitcnt vmcnt(8)
	s_waitcnt vmcnt(8)
	s_waitcnt lgkmcnt(0)
	s_setprio 1
	s_barrier
; #define PG8_STAGE(bufoff, gbase, voff) do { _Pragma("unroll") for (int _i = 0; _i < 2; ++_i) \
;         __builtin_amdgcn_global_load_lds((const unsigned*)((const char*)(gbase) + (voff)[_i]), (PG8_LAS unsigned*)(lds + (bufoff) + ldsw + _i * 8192), 16, 0, 0); } while (0)
; #define PG8_LDA(dst, b, h) do { _Pragma("unroll") for (int m = 0; m < 4; ++m) _Pragma("unroll") for (int k = 0; k < 2; ++k) dst[m][k] = *(const PG8_LAS bf16x8*)(lds + PG8_SA(b, h) + aoff + m * 2048 + k * 1024); } while (0)
; #define PG8_LDB(dst, b, h) do { _Pragma("unroll") for (int n = 0; n < 2; ++n) _Pragma("unroll") for (int k = 0; k < 2; ++k) dst[n][k] = *(const PG8_LAS bf16x8*)(lds + PG8_SB(b, h) + boff + n * 2048 + k * 1024); } while (0)
; #define PG8_MMA(ai, bj, At, Bt) do { __builtin_amdgcn_s_setprio(1); _Pragma("unroll") for (int m = 0; m < 4; ++m) _Pragma("unroll") for (int n = 0; n < 2; ++n) _Pragma("unroll") for (int k = 0; k < 2; ++k) \
;         acc[ai][bj][m][n] = __builtin_amdgcn_mfma_f32_16x16x32_bf16(Bt[n][k], At[m][k], acc[ai][bj][m][n], 0, 0, 0); __builtin_amdgcn_s_setprio(0); } while (0)
; #define PG8_WAIT_V(n) asm volatile("s_waitcnt vmcnt(" #n ")" ::: "memory")
; #define PG8_WAIT_VN(n) asm volatile("s_waitcnt vmcnt(%0)" :: "n"(n) : "memory")
; #define PG8_WAIT_L(n) asm volatile("s_waitcnt lgkmcnt(" #n ")" ::: "memory")
; #define PG8_BAR __builtin_amdgcn_s_barrier()
; #define PG8_SCHED __builtin_amdgcn_sched_barrier(0)
; template <class Epi, class Sched, bool ALIGN_EPI = false, bool SP2 = false>
; __device__ __forceinline__ void gemm_phase(PG8_LAS unsigned char* lds, const Gemm g, const Sched& S, const Epi& E, const int wave_id) {
;     ...
;             PG8_WAIT_VN(8 + Epi::NS); if (strict) PG8_WAIT_V(8); PG8_WAIT_L(0); PG8_BAR; PG8_MMA(0, 0, At, B0); PG8_MMA(0, 1, At, B1); PG8_BAR; PG8_SCHED;
;             PG8_LDA(At, 0, 1); PG8_STAGE(PG8_SB(0, 0), b2, voffB); PG8_STAGE(PG8_SB(0, 1), b2 + hstep, voffB); PG8_STAGE(PG8_SA(0, 0), a2, voffA);
;             PG8_WAIT_VN(8 + Epi::NS); if (strict) PG8_WAIT_V(8); PG8_WAIT_L(0); PG8_BAR; PG8_MMA(1, 0, At, B0); PG8_MMA(1, 1, At, B1); PG8_BAR; PG8_SCHED;
;             PG8_LDB(B0, 1, 0); PG8_LDB(B1, 1, 1); PG8_SCHED; PG8_LDA(At, 1, 0); PG8_STAGE(PG8_SA(0, 1), a2 + hstep, voffA);
;             PG8_WAIT_V(8); PG8_WAIT_L(0); PG8_BAR; PG8_MMA(0, 0, At, B0); PG8_MMA(0, 1, At, B1); PG8_BAR; PG8_SCHED;
	v_mfma_f32_16x16x32_bf16 v[62:65], v[148:151], v[186:189], v[62:65]
	v_mfma_f32_16x16x32_bf16 v[58:61], v[156:159], v[186:189], v[58:61]
	v_mfma_f32_16x16x32_bf16 v[54:57], v[148:151], v[194:197], v[54:57]
	v_mfma_f32_16x16x32_bf16 v[50:53], v[156:159], v[194:197], v[50:53]
	v_mfma_f32_16x16x32_bf16 v[46:49], v[148:151], v[202:205], v[46:49]
	v_mfma_f32_16x16x32_bf16 v[42:45], v[156:159], v[202:205], v[42:45]
	v_mfma_f32_16x16x32_bf16 v[38:41], v[148:151], v[210:213], v[38:41]
	v_mfma_f32_16x16x32_bf16 v[34:37], v[156:159], v[210:213], v[34:37]
	v_mfma_f32_16x16x32_bf16 v[62:65], v[152:155], v[190:193], v[62:65]
	v_mfma_f32_16x16x32_bf16 v[58:61], v[166:169], v[190:193], v[58:61]
	v_mfma_f32_16x16x32_bf16 v[54:57], v[152:155], v[198:201], v[54:57]
	v_mfma_f32_16x16x32_bf16 v[50:53], v[166:169], v[198:201], v[50:53]
	v_mfma_f32_16x16x32_bf16 v[46:49], v[152:155], v[206:209], v[46:49]
	v_mfma_f32_16x16x32_bf16 v[42:45], v[166:169], v[206:209], v[42:45]
	v_mfma_f32_16x16x32_bf16 v[38:41], v[152:155], v[214:217], v[38:41]
	v_mfma_f32_16x16x32_bf16 v[34:37], v[166:169], v[214:217], v[34:37]
	s_setprio 0
	s_setprio 1
	v_mfma_f32_16x16x32_bf16 v[30:33], v[170:173], v[186:189], v[30:33]
	v_mfma_f32_16x16x32_bf16 v[26:29], v[178:181], v[186:189], v[26:29]
	v_mfma_f32_16x16x32_bf16 v[22:25], v[170:173], v[194:197], v[22:25]
	v_mfma_f32_16x16x32_bf16 v[18:21], v[178:181], v[194:197], v[18:21]
	v_mfma_f32_16x16x32_bf16 v[14:17], v[170:173], v[202:205], v[14:17]
	v_mfma_f32_16x16x32_bf16 v[10:13], v[178:181], v[202:205], v[10:13]
	v_mfma_f32_16x16x32_bf16 v[6:9], v[170:173], v[210:213], v[6:9]
	v_mfma_f32_16x16x32_bf16 v[2:5], v[178:181], v[210:213], v[2:5]
	v_mfma_f32_16x16x32_bf16 v[30:33], v[174:177], v[190:193], v[30:33]
	v_mfma_f32_16x16x32_bf16 v[26:29], v[182:185], v[190:193], v[26:29]
	v_mfma_f32_16x16x32_bf16 v[22:25], v[174:177], v[198:201], v[22:25]
	v_mfma_f32_16x16x32_bf16 v[18:21], v[182:185], v[198:201], v[18:21]
	v_mfma_f32_16x16x32_bf16 v[14:17], v[174:177], v[206:209], v[14:17]
	v_mfma_f32_16x16x32_bf16 v[10:13], v[182:185], v[206:209], v[10:13]
	v_mfma_f32_16x16x32_bf16 v[6:9], v[174:177], v[214:217], v[6:9]
	v_mfma_f32_16x16x32_bf16 v[2:5], v[182:185], v[214:217], v[2:5]
	s_barrier
	s_setprio 0
	s_add_i32 s53, 0, 0x18000
	v_add_u32_e32 v147, s53, v163
	s_add_i32 s76, 0, 0x1c000
	ds_read_b128 v[148:151], v147
	ds_read_b128 v[152:155], v147 offset:1024
	ds_read_b128 v[156:159], v147 offset:2048
	ds_read_b128 v[166:169], v147 offset:3072
	v_add_u32_e32 v147, s76, v163
	ds_read_b128 v[170:173], v147
	ds_read_b128 v[174:177], v147 offset:1024
	ds_read_b128 v[178:181], v147 offset:2048
	ds_read_b128 v[182:185], v147 offset:3072
	s_add_u32 s26, s26, 0x40000
	s_addc_u32 s27, s27, 0
	s_mov_b32 m0, s38
	v_lshl_add_u64 v[224:225], s[26:27], 0, v[130:131]
	ds_read_b128 v[186:189], v164 offset:32768
	ds_read_b128 v[190:193], v164 offset:33792
	ds_read_b128 v[194:197], v164 offset:34816
	ds_read_b128 v[198:201], v164 offset:35840
	ds_read_b128 v[202:205], v164 offset:36864
	ds_read_b128 v[206:209], v164 offset:37888
	ds_read_b128 v[210:213], v164 offset:38912
	ds_read_b128 v[214:217], v164 offset:39936
	global_load_lds_dwordx4 v[224:225], off
	v_lshl_add_u64 v[224:225], s[26:27], 0, v[134:135]
	s_mov_b32 m0, s39
	s_nop 0
	global_load_lds_dwordx4 v[224:225], off
	s_waitcnt vmcnt(8)
	s_waitcnt lgkmcnt(0)
	s_setprio 1
	s_barrier
	v_mfma_f32_16x16x32_bf16 v[126:129], v[148:151], v[186:189], v[126:129]
	v_mfma_f32_16x16x32_bf16 v[122:125], v[156:159], v[186:189], v[122:125]
	v_mfma_f32_16x16x32_bf16 v[118:121], v[148:151], v[194:197], v[118:121]
	v_mfma_f32_16x16x32_bf16 v[114:117], v[156:159], v[194:197], v[114:117]
	v_mfma_f32_16x16x32_bf16 v[110:113], v[148:151], v[202:205], v[110:113]
	v_mfma_f32_16x16x32_bf16 v[106:109], v[156:159], v[202:205], v[106:109]
	v_mfma_f32_16x16x32_bf16 v[102:105], v[148:151], v[210:213], v[102:105]
	v_mfma_f32_16x16x32_bf16 v[98:101], v[156:159], v[210:213], v[98:101]
	v_mfma_f32_16x16x32_bf16 v[126:129], v[152:155], v[190:193], v[126:129]
	v_mfma_f32_16x16x32_bf16 v[122:125], v[166:169], v[190:193], v[122:125]
	v_mfma_f32_16x16x32_bf16 v[118:121], v[152:155], v[198:201], v[118:121]
	v_mfma_f32_16x16x32_bf16 v[114:117], v[166:169], v[198:201], v[114:117]
	v_mfma_f32_16x16x32_bf16 v[110:113], v[152:155], v[206:209], v[110:113]
	v_mfma_f32_16x16x32_bf16 v[106:109], v[166:169], v[206:209], v[106:109]
	v_mfma_f32_16x16x32_bf16 v[102:105], v[152:155], v[214:217], v[102:105]
	v_mfma_f32_16x16x32_bf16 v[98:101], v[166:169], v[214:217], v[98:101]
	s_setprio 0
	s_setprio 1
	v_mfma_f32_16x16x32_bf16 v[94:97], v[170:173], v[186:189], v[94:97]
	v_mfma_f32_16x16x32_bf16 v[90:93], v[178:181], v[186:189], v[90:93]
	v_mfma_f32_16x16x32_bf16 v[86:89], v[170:173], v[194:197], v[86:89]
	v_mfma_f32_16x16x32_bf16 v[82:85], v[178:181], v[194:197], v[82:85]
	v_mfma_f32_16x16x32_bf16 v[78:81], v[170:173], v[202:205], v[78:81]
	v_mfma_f32_16x16x32_bf16 v[74:77], v[178:181], v[202:205], v[74:77]
	v_mfma_f32_16x16x32_bf16 v[70:73], v[170:173], v[210:213], v[70:73]
	v_mfma_f32_16x16x32_bf16 v[66:69], v[178:181], v[210:213], v[66:69]
	v_mfma_f32_16x16x32_bf16 v[94:97], v[174:177], v[190:193], v[94:97]
	v_mfma_f32_16x16x32_bf16 v[90:93], v[182:185], v[190:193], v[90:93]
	v_mfma_f32_16x16x32_bf16 v[86:89], v[174:177], v[198:201], v[86:89]
	v_mfma_f32_16x16x32_bf16 v[82:85], v[182:185], v[198:201], v[82:85]
	v_mfma_f32_16x16x32_bf16 v[78:81], v[174:177], v[206:209], v[78:81]
	v_mfma_f32_16x16x32_bf16 v[74:77], v[182:185], v[206:209], v[74:77]
	v_mfma_f32_16x16x32_bf16 v[70:73], v[174:177], v[214:217], v[70:73]
	v_mfma_f32_16x16x32_bf16 v[66:69], v[182:185], v[214:217], v[66:69]
	s_barrier
; #define PG8_STAGE(bufoff, gbase, voff) do { _Pragma("unroll") for (int _i = 0; _i < 2; ++_i) \
;         __builtin_amdgcn_global_load_lds((const unsigned*)((const char*)(gbase) + (voff)[_i]), (PG8_LAS unsigned*)(lds + (bufoff) + ldsw + _i * 8192), 16, 0, 0); } while (0)
; #define PG8_LDA(dst, b, h) do { _Pragma("unroll") for (int m = 0; m < 4; ++m) _Pragma("unroll") for (int k = 0; k < 2; ++k) dst[m][k] = *(const PG8_LAS bf16x8*)(lds + PG8_SA(b, h) + aoff + m * 2048 + k * 1024); } while (0)
; #define PG8_MMA(ai, bj, At, Bt) do { __builtin_amdgcn_s_setprio(1); _Pragma("unroll") for (int m = 0; m < 4; ++m) _Pragma("unroll") for (int n = 0; n < 2; ++n) _Pragma("unroll") for (int k = 0; k < 2; ++k) \
;         acc[ai][bj][m][n] = __builtin_amdgcn_mfma_f32_16x16x32_bf16(Bt[n][k], At[m][k], acc[ai][bj][m][n], 0, 0, 0); __builtin_amdgcn_s_setprio(0); } while (0)
; #define PG8_WAIT_V(n) asm volatile("s_waitcnt vmcnt(" #n ")" ::: "memory")
; #define PG8_WAIT_L(n) asm volatile("s_waitcnt lgkmcnt(" #n ")" ::: "memory")
; #define PG8_BAR __builtin_amdgcn_s_barrier()
; #define PG8_SCHED __builtin_amdgcn_sched_barrier(0)
; template <class Epi, class Sched, bool ALIGN_EPI = false, bool SP2 = false>
; __device__ __forceinline__ void gemm_phase(PG8_LAS unsigned char* lds, const Gemm g, const Sched& S, const Epi& E, const int wave_id) {
;     ...
;         for (int t = 0; t < nt; t += 2) {
;     ...
;             PG8_LDA(At, 1, 1); PG8_STAGE(PG8_SB(1, 0), b3, voffB); PG8_STAGE(PG8_SB(1, 1), b3 + hstep, voffB); PG8_STAGE(PG8_SA(1, 0), a3, voffA);
;             PG8_WAIT_V(8); PG8_WAIT_L(0); PG8_BAR; PG8_MMA(1, 0, At, B0); PG8_MMA(1, 1, At, B1); PG8_BAR; PG8_SCHED;
;     ...
;         if constexpr (ALIGN_EPI) { if (wr == 0) PG8_BAR; }
	s_setprio 0
	s_add_i32 s26, s53, s35
	v_lshl_add_u64 v[160:161], v[160:161], 0, s[64:65]
	s_mov_b32 m0, s26
	ds_read_b128 v[186:189], v164 offset:49152
	ds_read_b128 v[190:193], v164 offset:50176
	ds_read_b128 v[194:197], v164 offset:51200
	ds_read_b128 v[198:201], v164 offset:52224
	ds_read_b128 v[202:205], v164 offset:53248
	ds_read_b128 v[206:209], v164 offset:54272
	ds_read_b128 v[210:213], v164 offset:55296
	ds_read_b128 v[214:217], v164 offset:56320
	global_load_lds_dwordx4 v[160:161], off
	s_add_i32 m0, s26, 0x2000
	s_add_u32 s12, s12, 0x40080
	v_lshl_add_u64 v[160:161], v[218:219], 0, s[64:65]
	s_addc_u32 s13, s13, 0
	s_add_i32 s26, s76, s35
	global_load_lds_dwordx4 v[160:161], off
	v_lshl_add_u64 v[160:161], s[12:13], 0, v[132:133]
	s_mov_b32 m0, s26
	s_nop 0
	global_load_lds_dwordx4 v[160:161], off
	v_lshl_add_u64 v[160:161], s[12:13], 0, v[136:137]
	s_add_i32 m0, s26, 0x2000
	s_nop 0
	global_load_lds_dwordx4 v[160:161], off
	v_lshl_add_u64 v[160:161], v[220:221], 0, s[64:65]
	s_mov_b32 m0, s41
	s_nop 0
	global_load_lds_dwordx4 v[160:161], off
	v_lshl_add_u64 v[160:161], v[222:223], 0, s[64:65]
	s_mov_b32 m0, s42
	s_nop 0
	global_load_lds_dwordx4 v[160:161], off
	s_waitcnt vmcnt(8)
	s_waitcnt lgkmcnt(0)
	s_setprio 1
	s_barrier
	v_mfma_f32_16x16x32_bf16 v[62:65], v[148:151], v[186:189], v[62:65]
	v_mfma_f32_16x16x32_bf16 v[58:61], v[156:159], v[186:189], v[58:61]
	v_mfma_f32_16x16x32_bf16 v[54:57], v[148:151], v[194:197], v[54:57]
	v_mfma_f32_16x16x32_bf16 v[50:53], v[156:159], v[194:197], v[50:53]
	v_mfma_f32_16x16x32_bf16 v[46:49], v[148:151], v[202:205], v[46:49]
	v_mfma_f32_16x16x32_bf16 v[42:45], v[156:159], v[202:205], v[42:45]
	v_mfma_f32_16x16x32_bf16 v[38:41], v[148:151], v[210:213], v[38:41]
	v_mfma_f32_16x16x32_bf16 v[34:37], v[156:159], v[210:213], v[34:37]
	v_mfma_f32_16x16x32_bf16 v[62:65], v[152:155], v[190:193], v[62:65]
	v_mfma_f32_16x16x32_bf16 v[58:61], v[166:169], v[190:193], v[58:61]
	v_mfma_f32_16x16x32_bf16 v[54:57], v[152:155], v[198:201], v[54:57]
	v_mfma_f32_16x16x32_bf16 v[50:53], v[166:169], v[198:201], v[50:53]
	v_mfma_f32_16x16x32_bf16 v[46:49], v[152:155], v[206:209], v[46:49]
	v_mfma_f32_16x16x32_bf16 v[42:45], v[166:169], v[206:209], v[42:45]
	v_mfma_f32_16x16x32_bf16 v[38:41], v[152:155], v[214:217], v[38:41]
	v_mfma_f32_16x16x32_bf16 v[34:37], v[166:169], v[214:217], v[34:37]
	s_setprio 0
	s_setprio 1
	v_mfma_f32_16x16x32_bf16 v[30:33], v[170:173], v[186:189], v[30:33]
	v_mfma_f32_16x16x32_bf16 v[26:29], v[178:181], v[186:189], v[26:29]
	v_mfma_f32_16x16x32_bf16 v[22:25], v[170:173], v[194:197], v[22:25]
	v_mfma_f32_16x16x32_bf16 v[18:21], v[178:181], v[194:197], v[18:21]
	v_mfma_f32_16x16x32_bf16 v[14:17], v[170:173], v[202:205], v[14:17]
	v_mfma_f32_16x16x32_bf16 v[10:13], v[178:181], v[202:205], v[10:13]
	v_mfma_f32_16x16x32_bf16 v[6:9], v[170:173], v[210:213], v[6:9]
	v_mfma_f32_16x16x32_bf16 v[2:5], v[178:181], v[210:213], v[2:5]
	v_mfma_f32_16x16x32_bf16 v[30:33], v[174:177], v[190:193], v[30:33]
	v_mfma_f32_16x16x32_bf16 v[26:29], v[182:185], v[190:193], v[26:29]
	v_mfma_f32_16x16x32_bf16 v[22:25], v[174:177], v[198:201], v[22:25]
	v_mfma_f32_16x16x32_bf16 v[18:21], v[182:185], v[198:201], v[18:21]
	v_mfma_f32_16x16x32_bf16 v[14:17], v[174:177], v[206:209], v[14:17]
	v_mfma_f32_16x16x32_bf16 v[10:13], v[182:185], v[206:209], v[10:13]
	v_mfma_f32_16x16x32_bf16 v[6:9], v[174:177], v[214:217], v[6:9]
	v_mfma_f32_16x16x32_bf16 v[2:5], v[182:185], v[214:217], v[2:5]
	s_barrier
	s_setprio 0
	s_add_u32 s10, s10, 0x100
	s_addc_u32 s11, s11, 0
	s_cmp_gt_u32 s69, 13
	s_cbranch_scc0 .LBB0_1537
	s_and_b64 vcc, exec, s[24:25]
	s_cbranch_vccz .LBB0_1540
	s_barrier

; #define PG8_STAGE(bufoff, gbase, voff) do { _Pragma("unroll") for (int _i = 0; _i < 2; ++_i) \
;         __builtin_amdgcn_global_load_lds((const unsigned*)((const char*)(gbase) + (voff)[_i]), (PG8_LAS unsigned*)(lds + (bufoff) + ldsw + _i * 8192), 16, 0, 0); } while (0)
; #define PG8_LDA(dst, b, h) do { _Pragma("unroll") for (int m = 0; m < 4; ++m) _Pragma("unroll") for (int k = 0; k < 2; ++k) dst[m][k] = *(const PG8_LAS bf16x8*)(lds + PG8_SA(b, h) + aoff + m * 2048 + k * 1024); } while (0)
; #define PG8_LDB(dst, b, h) do { _Pragma("unroll") for (int n = 0; n < 2; ++n) _Pragma("unroll") for (int k = 0; k < 2; ++k) dst[n][k] = *(const PG8_LAS bf16x8*)(lds + PG8_SB(b, h) + boff + n * 2048 + k * 1024); } while (0)
; template <class Epi, class Sched, bool ALIGN_EPI = false, bool SP2 = false>
; __device__ __forceinline__ void gemm_phase(PG8_LAS unsigned char* lds, const Gemm g, const Sched& S, const Epi& E, const int wave_id) {
;     ...
;         for (int t = 0; t < nt; t += 2) {
;             const bool last = (t == nt - 2);
;             const char* a1 = cA + (size_t)(t + 1) * kstep;
;             const char* a2 = last ? nA : cA + (size_t)(t + 2) * kstep; const char* b2 = last ? nB : cB + (size_t)(t + 2) * kstep;
;             const char* a3 = a2 + kstep; const char* b3 = b2 + kstep;
;             if (last && has_next) S.a_ready(nxt);
;             if constexpr (SP2) {
;             int tz_ = __builtin_amdgcn_readfirstlane(t | (ui > 0 ? 0 : 1)); asm volatile("" : "+s"(tz_));
;             const bool strict = !(Epi::NS > 0 && tz_ == 0);
;             PG8_LDB(B0, 0, 0); PG8_LDB(B1, 0, 1); PG8_SCHED; PG8_LDA(At, 0, 0); PG8_STAGE(PG8_SA(1, 1), a1 + hstep, voffA);
;             PG8_WAIT_VN(8 + Epi::NS); if (strict) PG8_WAIT_V(8); PG8_WAIT_L(0); PG8_BAR; PG8_MMA(0, 0, At, B0); PG8_MMA(0, 1, At, B1); PG8_BAR; PG8_SCHED;
;             PG8_LDA(At, 0, 1); PG8_STAGE(PG8_SB(0, 0), b2, voffB); PG8_STAGE(PG8_SB(0, 1), b2 + hstep, voffB); PG8_STAGE(PG8_SA(0, 0), a2, voffA);
;             PG8_WAIT_VN(8 + Epi::NS); if (strict) PG8_WAIT_V(8); PG8_WAIT_L(0); PG8_BAR; PG8_MMA(1, 0, At, B0); PG8_MMA(1, 1, At, B1); PG8_BAR; PG8_SCHED;
;             PG8_LDB(B0, 1, 0); PG8_LDB(B1, 1, 1); PG8_SCHED; PG8_LDA(At, 1, 0); PG8_STAGE(PG8_SA(0, 1), a2 + hstep, voffA);
;             PG8_WAIT_V(8); PG8_WAIT_L(0); PG8_BAR; PG8_MMA(0, 0, At, B0); PG8_MMA(0, 1, At, B1); PG8_BAR; PG8_SCHED;
.LBB0_1685:
	s_add_u32 s24, s20, s22
	s_addc_u32 s25, s21, s23
	s_add_u32 s24, s24, 0x100
	s_addc_u32 s25, s25, 0
	s_add_u32 s53, s52, s22
	s_addc_u32 s57, s54, s23
	s_add_i32 s56, s56, 2
	s_add_i32 s62, 0, 0x10000
	v_add_u32_e32 v147, s56, v146
	s_cmpk_eq_i32 s22, 0x700
	s_cselect_b32 s26, s11, s24
	v_readfirstlane_b32 s24, v147
	s_cselect_b32 s27, s9, s25
	v_add_u32_e32 v147, s62, v163
	s_cselect_b32 s25, s13, s57
	s_cselect_b32 s24, s15, s53
	s_add_i32 s53, 0, 0x14000
	ds_read_b128 v[148:151], v147
	ds_read_b128 v[152:155], v147 offset:1024
	ds_read_b128 v[156:159], v147 offset:2048
	ds_read_b128 v[166:169], v147 offset:3072
	v_add_u32_e32 v147, s53, v163
	ds_read_b128 v[170:173], v147
	ds_read_b128 v[174:177], v147 offset:1024
	ds_read_b128 v[178:181], v147 offset:2048
	ds_read_b128 v[182:185], v147 offset:3072
	v_lshl_add_u64 v[160:161], v[144:145], 0, s[22:23]
	s_add_i32 m0, s38, 0xc000
	ds_read_b128 v[186:189], v164
	ds_read_b128 v[190:193], v164 offset:1024
	ds_read_b128 v[194:197], v164 offset:2048
	ds_read_b128 v[198:201], v164 offset:3072
	ds_read_b128 v[202:205], v164 offset:4096
	ds_read_b128 v[206:209], v164 offset:5120
	ds_read_b128 v[210:213], v164 offset:6144
	ds_read_b128 v[214:217], v164 offset:7168
	global_load_lds_dwordx4 v[160:161], off
	v_lshl_add_u64 v[160:161], v[142:143], 0, s[22:23]
	s_add_i32 m0, s38, 0xe000
	s_nop 0
	global_load_lds_dwordx4 v[160:161], off
	s_waitcnt vmcnt(8)
	s_waitcnt vmcnt(8)
	s_waitcnt lgkmcnt(0)
	s_setprio 1
	s_barrier
	v_mfma_f32_16x16x32_bf16 v[126:129], v[148:151], v[186:189], v[126:129]
	v_mfma_f32_16x16x32_bf16 v[122:125], v[156:159], v[186:189], v[122:125]
	v_mfma_f32_16x16x32_bf16 v[118:121], v[148:151], v[194:197], v[118:121]
	v_mfma_f32_16x16x32_bf16 v[114:117], v[156:159], v[194:197], v[114:117]
	v_mfma_f32_16x16x32_bf16 v[110:113], v[148:151], v[202:205], v[110:113]
	v_mfma_f32_16x16x32_bf16 v[106:109], v[156:159], v[202:205], v[106:109]
	v_mfma_f32_16x16x32_bf16 v[102:105], v[148:151], v[210:213], v[102:105]
	v_mfma_f32_16x16x32_bf16 v[98:101], v[156:159], v[210:213], v[98:101]
	v_mfma_f32_16x16x32_bf16 v[126:129], v[152:155], v[190:193], v[126:129]
	v_mfma_f32_16x16x32_bf16 v[122:125], v[166:169], v[190:193], v[122:125]
	v_mfma_f32_16x16x32_bf16 v[118:121], v[152:155], v[198:201], v[118:121]
	v_mfma_f32_16x16x32_bf16 v[114:117], v[166:169], v[198:201], v[114:117]
	v_mfma_f32_16x16x32_bf16 v[110:113], v[152:155], v[206:209], v[110:113]
	v_mfma_f32_16x16x32_bf16 v[106:109], v[166:169], v[206:209], v[106:109]
	v_mfma_f32_16x16x32_bf16 v[102:105], v[152:155], v[214:217], v[102:105]
	v_mfma_f32_16x16x32_bf16 v[98:101], v[166:169], v[214:217], v[98:101]
	s_setprio 0
	s_setprio 1
	v_mfma_f32_16x16x32_bf16 v[94:97], v[170:173], v[186:189], v[94:97]
	v_mfma_f32_16x16x32_bf16 v[90:93], v[178:181], v[186:189], v[90:93]
	v_mfma_f32_16x16x32_bf16 v[86:89], v[170:173], v[194:197], v[86:89]
	v_mfma_f32_16x16x32_bf16 v[82:85], v[178:181], v[194:197], v[82:85]
	v_mfma_f32_16x16x32_bf16 v[78:81], v[170:173], v[202:205], v[78:81]
	v_mfma_f32_16x16x32_bf16 v[74:77], v[178:181], v[202:205], v[74:77]
	v_mfma_f32_16x16x32_bf16 v[70:73], v[170:173], v[210:213], v[70:73]
	v_mfma_f32_16x16x32_bf16 v[66:69], v[178:181], v[210:213], v[66:69]
	v_mfma_f32_16x16x32_bf16 v[94:97], v[174:177], v[190:193], v[94:97]
	v_mfma_f32_16x16x32_bf16 v[90:93], v[182:185], v[190:193], v[90:93]
	v_mfma_f32_16x16x32_bf16 v[86:89], v[174:177], v[198:201], v[86:89]
	v_mfma_f32_16x16x32_bf16 v[82:85], v[182:185], v[198:201], v[82:85]
	v_mfma_f32_16x16x32_bf16 v[78:81], v[174:177], v[206:209], v[78:81]
	v_mfma_f32_16x16x32_bf16 v[74:77], v[182:185], v[206:209], v[74:77]
	v_mfma_f32_16x16x32_bf16 v[70:73], v[174:177], v[214:217], v[70:73]
	v_mfma_f32_16x16x32_bf16 v[66:69], v[182:185], v[214:217], v[66:69]
	s_barrier
	s_setprio 0
	s_add_i32 s57, s62, s37
	v_lshl_add_u64 v[160:161], s[24:25], 0, v[132:133]
	s_mov_b32 m0, s57
	ds_read_b128 v[186:189], v164 offset:16384
	ds_read_b128 v[190:193], v164 offset:17408
	ds_read_b128 v[194:197], v164 offset:18432
	ds_read_b128 v[198:201], v164 offset:19456
	ds_read_b128 v[202:205], v164 offset:20480
	ds_read_b128 v[206:209], v164 offset:21504
	ds_read_b128 v[210:213], v164 offset:22528
	ds_read_b128 v[214:217], v164 offset:23552
	global_load_lds_dwordx4 v[160:161], off
	s_add_i32 m0, s57, 0x2000
	s_add_u32 s62, s24, 0x40000
	v_lshl_add_u64 v[218:219], s[24:25], 0, v[136:137]
	s_addc_u32 s63, s25, 0
	s_add_i32 s53, s53, s37
	global_load_lds_dwordx4 v[218:219], off
	v_lshl_add_u64 v[220:221], s[62:63], 0, v[132:133]
	s_mov_b32 m0, s53
	v_lshl_add_u64 v[222:223], s[26:27], 0, v[134:135]
	global_load_lds_dwordx4 v[220:221], off
	v_lshl_add_u64 v[220:221], s[62:63], 0, v[136:137]
	s_add_i32 m0, s53, 0x2000
	s_nop 0
	global_load_lds_dwordx4 v[220:221], off
	v_lshl_add_u64 v[220:221], s[26:27], 0, v[130:131]
	s_mov_b32 m0, s38
	s_nop 0
	global_load_lds_dwordx4 v[220:221], off
	s_mov_b32 m0, s39
	s_nop 0
	global_load_lds_dwordx4 v[222:223], off
	s_waitcnt vmcnt(8)
	s_waitcnt vmcnt(8)
	s_waitcnt lgkmcnt(0)
	s_setprio 1
	s_barrier
; #define PG8_STAGE(bufoff, gbase, voff) do { _Pragma("unroll") for (int _i = 0; _i < 2; ++_i) \
;         __builtin_amdgcn_global_load_lds((const unsigned*)((const char*)(gbase) + (voff)[_i]), (PG8_LAS unsigned*)(lds + (bufoff) + ldsw + _i * 8192), 16, 0, 0); } while (0)
; #define PG8_LDA(dst, b, h) do { _Pragma("unroll") for (int m = 0; m < 4; ++m) _Pragma("unroll") for (int k = 0; k < 2; ++k) dst[m][k] = *(const PG8_LAS bf16x8*)(lds + PG8_SA(b, h) + aoff + m * 2048 + k * 1024); } while (0)
; #define PG8_LDB(dst, b, h) do { _Pragma("unroll") for (int n = 0; n < 2; ++n) _Pragma("unroll") for (int k = 0; k < 2; ++k) dst[n][k] = *(const PG8_LAS bf16x8*)(lds + PG8_SB(b, h) + boff + n * 2048 + k * 1024); } while (0)
; #define PG8_MMA(ai, bj, At, Bt) do { __builtin_amdgcn_s_setprio(1); _Pragma("unroll") for (int m = 0; m < 4; ++m) _Pragma("unroll") for (int n = 0; n < 2; ++n) _Pragma("unroll") for (int k = 0; k < 2; ++k) \
;         acc[ai][bj][m][n] = __builtin_amdgcn_mfma_f32_16x16x32_bf16(Bt[n][k], At[m][k], acc[ai][bj][m][n], 0, 0, 0); __builtin_amdgcn_s_setprio(0); } while (0)
; #define PG8_WAIT_V(n) asm volatile("s_waitcnt vmcnt(" #n ")" ::: "memory")
; #define PG8_WAIT_VN(n) asm volatile("s_waitcnt vmcnt(%0)" :: "n"(n) : "memory")
; #define PG8_WAIT_L(n) asm volatile("s_waitcnt lgkmcnt(" #n ")" ::: "memory")
; #define PG8_BAR __builtin_amdgcn_s_barrier()
; #define PG8_SCHED __builtin_amdgcn_sched_barrier(0)
; template <class Epi, class Sched, bool ALIGN_EPI = false, bool SP2 = false>
; __device__ __forceinline__ void gemm_phase(PG8_LAS unsigned char* lds, const Gemm g, const Sched& S, const Epi& E, const int wave_id) {
;     ...
;             PG8_WAIT_VN(8 + Epi::NS); if (strict) PG8_WAIT_V(8); PG8_WAIT_L(0); PG8_BAR; PG8_MMA(0, 0, At, B0); PG8_MMA(0, 1, At, B1); PG8_BAR; PG8_SCHED;
;             PG8_LDA(At, 0, 1); PG8_STAGE(PG8_SB(0, 0), b2, voffB); PG8_STAGE(PG8_SB(0, 1), b2 + hstep, voffB); PG8_STAGE(PG8_SA(0, 0), a2, voffA);
;             PG8_WAIT_VN(8 + Epi::NS); if (strict) PG8_WAIT_V(8); PG8_WAIT_L(0); PG8_BAR; PG8_MMA(1, 0, At, B0); PG8_MMA(1, 1, At, B1); PG8_BAR; PG8_SCHED;
;             PG8_LDB(B0, 1, 0); PG8_LDB(B1, 1, 1); PG8_SCHED; PG8_LDA(At, 1, 0); PG8_STAGE(PG8_SA(0, 1), a2 + hstep, voffA);
;             PG8_WAIT_V(8); PG8_WAIT_L(0); PG8_BAR; PG8_MMA(0, 0, At, B0); PG8_MMA(0, 1, At, B1); PG8_BAR; PG8_SCHED;
	v_mfma_f32_16x16x32_bf16 v[62:65], v[148:151], v[186:189], v[62:65]
	v_mfma_f32_16x16x32_bf16 v[58:61], v[156:159], v[186:189], v[58:61]
	v_mfma_f32_16x16x32_bf16 v[54:57], v[148:151], v[194:197], v[54:57]
	v_mfma_f32_16x16x32_bf16 v[50:53], v[156:159], v[194:197], v[50:53]
	v_mfma_f32_16x16x32_bf16 v[46:49], v[148:151], v[202:205], v[46:49]
	v_mfma_f32_16x16x32_bf16 v[42:45], v[156:159], v[202:205], v[42:45]
	v_mfma_f32_16x16x32_bf16 v[38:41], v[148:151], v[210:213], v[38:41]
	v_mfma_f32_16x16x32_bf16 v[34:37], v[156:159], v[210:213], v[34:37]
	v_mfma_f32_16x16x32_bf16 v[62:65], v[152:155], v[190:193], v[62:65]
	v_mfma_f32_16x16x32_bf16 v[58:61], v[166:169], v[190:193], v[58:61]
	v_mfma_f32_16x16x32_bf16 v[54:57], v[152:155], v[198:201], v[54:57]
	v_mfma_f32_16x16x32_bf16 v[50:53], v[166:169], v[198:201], v[50:53]
	v_mfma_f32_16x16x32_bf16 v[46:49], v[152:155], v[206:209], v[46:49]
	v_mfma_f32_16x16x32_bf16 v[42:45], v[166:169], v[206:209], v[42:45]
	v_mfma_f32_16x16x32_bf16 v[38:41], v[152:155], v[214:217], v[38:41]
	v_mfma_f32_16x16x32_bf16 v[34:37], v[166:169], v[214:217], v[34:37]
	s_setprio 0
	s_setprio 1
	v_mfma_f32_16x16x32_bf16 v[30:33], v[170:173], v[186:189], v[30:33]
	v_mfma_f32_16x16x32_bf16 v[26:29], v[178:181], v[186:189], v[26:29]
	v_mfma_f32_16x16x32_bf16 v[22:25], v[170:173], v[194:197], v[22:25]
	v_mfma_f32_16x16x32_bf16 v[18:21], v[178:181], v[194:197], v[18:21]
	v_mfma_f32_16x16x32_bf16 v[14:17], v[170:173], v[202:205], v[14:17]
	v_mfma_f32_16x16x32_bf16 v[10:13], v[178:181], v[202:205], v[10:13]
	v_mfma_f32_16x16x32_bf16 v[6:9], v[170:173], v[210:213], v[6:9]
	v_mfma_f32_16x16x32_bf16 v[2:5], v[178:181], v[210:213], v[2:5]
	v_mfma_f32_16x16x32_bf16 v[30:33], v[174:177], v[190:193], v[30:33]
	v_mfma_f32_16x16x32_bf16 v[26:29], v[182:185], v[190:193], v[26:29]
	v_mfma_f32_16x16x32_bf16 v[22:25], v[174:177], v[198:201], v[22:25]
	v_mfma_f32_16x16x32_bf16 v[18:21], v[182:185], v[198:201], v[18:21]
	v_mfma_f32_16x16x32_bf16 v[14:17], v[174:177], v[206:209], v[14:17]
	v_mfma_f32_16x16x32_bf16 v[10:13], v[182:185], v[206:209], v[10:13]
	v_mfma_f32_16x16x32_bf16 v[6:9], v[174:177], v[214:217], v[6:9]
	v_mfma_f32_16x16x32_bf16 v[2:5], v[182:185], v[214:217], v[2:5]
	s_barrier
	s_setprio 0
	s_add_i32 s53, 0, 0x18000
	v_add_u32_e32 v147, s53, v163
	s_add_i32 s57, 0, 0x1c000
	ds_read_b128 v[148:151], v147
	ds_read_b128 v[152:155], v147 offset:1024
	ds_read_b128 v[156:159], v147 offset:2048
	ds_read_b128 v[166:169], v147 offset:3072
	v_add_u32_e32 v147, s57, v163
	ds_read_b128 v[170:173], v147
	ds_read_b128 v[174:177], v147 offset:1024
	ds_read_b128 v[178:181], v147 offset:2048
	ds_read_b128 v[182:185], v147 offset:3072
	s_add_u32 s26, s26, 0x40000
	s_addc_u32 s27, s27, 0
	s_mov_b32 m0, s40
	v_lshl_add_u64 v[224:225], s[26:27], 0, v[130:131]
	ds_read_b128 v[186:189], v164 offset:32768
	ds_read_b128 v[190:193], v164 offset:33792
	ds_read_b128 v[194:197], v164 offset:34816
	ds_read_b128 v[198:201], v164 offset:35840
	ds_read_b128 v[202:205], v164 offset:36864
	ds_read_b128 v[206:209], v164 offset:37888
	ds_read_b128 v[210:213], v164 offset:38912
	ds_read_b128 v[214:217], v164 offset:39936
	global_load_lds_dwordx4 v[224:225], off
	v_lshl_add_u64 v[224:225], s[26:27], 0, v[134:135]
	s_mov_b32 m0, s41
	s_nop 0
	global_load_lds_dwordx4 v[224:225], off
	s_waitcnt vmcnt(8)
	s_waitcnt lgkmcnt(0)
	s_setprio 1
	s_barrier
	v_mfma_f32_16x16x32_bf16 v[126:129], v[148:151], v[186:189], v[126:129]
	v_mfma_f32_16x16x32_bf16 v[122:125], v[156:159], v[186:189], v[122:125]
	v_mfma_f32_16x16x32_bf16 v[118:121], v[148:151], v[194:197], v[118:121]
	v_mfma_f32_16x16x32_bf16 v[114:117], v[156:159], v[194:197], v[114:117]
	v_mfma_f32_16x16x32_bf16 v[110:113], v[148:151], v[202:205], v[110:113]
	v_mfma_f32_16x16x32_bf16 v[106:109], v[156:159], v[202:205], v[106:109]
	v_mfma_f32_16x16x32_bf16 v[102:105], v[148:151], v[210:213], v[102:105]
	v_mfma_f32_16x16x32_bf16 v[98:101], v[156:159], v[210:213], v[98:101]
	v_mfma_f32_16x16x32_bf16 v[126:129], v[152:155], v[190:193], v[126:129]
	v_mfma_f32_16x16x32_bf16 v[122:125], v[166:169], v[190:193], v[122:125]
	v_mfma_f32_16x16x32_bf16 v[118:121], v[152:155], v[198:201], v[118:121]
	v_mfma_f32_16x16x32_bf16 v[114:117], v[166:169], v[198:201], v[114:117]
	v_mfma_f32_16x16x32_bf16 v[110:113], v[152:155], v[206:209], v[110:113]
	v_mfma_f32_16x16x32_bf16 v[106:109], v[166:169], v[206:209], v[106:109]
	v_mfma_f32_16x16x32_bf16 v[102:105], v[152:155], v[214:217], v[102:105]
	v_mfma_f32_16x16x32_bf16 v[98:101], v[166:169], v[214:217], v[98:101]
	s_setprio 0
	s_setprio 1
	v_mfma_f32_16x16x32_bf16 v[94:97], v[170:173], v[186:189], v[94:97]
	v_mfma_f32_16x16x32_bf16 v[90:93], v[178:181], v[186:189], v[90:93]
	v_mfma_f32_16x16x32_bf16 v[86:89], v[170:173], v[194:197], v[86:89]
	v_mfma_f32_16x16x32_bf16 v[82:85], v[178:181], v[194:197], v[82:85]
	v_mfma_f32_16x16x32_bf16 v[78:81], v[170:173], v[202:205], v[78:81]
	v_mfma_f32_16x16x32_bf16 v[74:77], v[178:181], v[202:205], v[74:77]
	v_mfma_f32_16x16x32_bf16 v[70:73], v[170:173], v[210:213], v[70:73]
	v_mfma_f32_16x16x32_bf16 v[66:69], v[178:181], v[210:213], v[66:69]
	v_mfma_f32_16x16x32_bf16 v[94:97], v[174:177], v[190:193], v[94:97]
	v_mfma_f32_16x16x32_bf16 v[90:93], v[182:185], v[190:193], v[90:93]
	v_mfma_f32_16x16x32_bf16 v[86:89], v[174:177], v[198:201], v[86:89]
	v_mfma_f32_16x16x32_bf16 v[82:85], v[182:185], v[198:201], v[82:85]
	v_mfma_f32_16x16x32_bf16 v[78:81], v[174:177], v[206:209], v[78:81]
	v_mfma_f32_16x16x32_bf16 v[74:77], v[182:185], v[206:209], v[74:77]
	v_mfma_f32_16x16x32_bf16 v[70:73], v[174:177], v[214:217], v[70:73]
	v_mfma_f32_16x16x32_bf16 v[66:69], v[182:185], v[214:217], v[66:69]
	s_barrier
; #define PG8_STAGE(bufoff, gbase, voff) do { _Pragma("unroll") for (int _i = 0; _i < 2; ++_i) \
;         __builtin_amdgcn_global_load_lds((const unsigned*)((const char*)(gbase) + (voff)[_i]), (PG8_LAS unsigned*)(lds + (bufoff) + ldsw + _i * 8192), 16, 0, 0); } while (0)
; #define PG8_LDA(dst, b, h) do { _Pragma("unroll") for (int m = 0; m < 4; ++m) _Pragma("unroll") for (int k = 0; k < 2; ++k) dst[m][k] = *(const PG8_LAS bf16x8*)(lds + PG8_SA(b, h) + aoff + m * 2048 + k * 1024); } while (0)
; #define PG8_MMA(ai, bj, At, Bt) do { __builtin_amdgcn_s_setprio(1); _Pragma("unroll") for (int m = 0; m < 4; ++m) _Pragma("unroll") for (int n = 0; n < 2; ++n) _Pragma("unroll") for (int k = 0; k < 2; ++k) \
;         acc[ai][bj][m][n] = __builtin_amdgcn_mfma_f32_16x16x32_bf16(Bt[n][k], At[m][k], acc[ai][bj][m][n], 0, 0, 0); __builtin_amdgcn_s_setprio(0); } while (0)
; #define PG8_WAIT_V(n) asm volatile("s_waitcnt vmcnt(" #n ")" ::: "memory")
; #define PG8_WAIT_L(n) asm volatile("s_waitcnt lgkmcnt(" #n ")" ::: "memory")
; #define PG8_BAR __builtin_amdgcn_s_barrier()
; #define PG8_SCHED __builtin_amdgcn_sched_barrier(0)
; template <class Epi, class Sched, bool ALIGN_EPI = false, bool SP2 = false>
; __device__ __forceinline__ void gemm_phase(PG8_LAS unsigned char* lds, const Gemm g, const Sched& S, const Epi& E, const int wave_id) {
;     ...
;         for (int t = 0; t < nt; t += 2) {
;     ...
;             PG8_LDA(At, 1, 1); PG8_STAGE(PG8_SB(1, 0), b3, voffB); PG8_STAGE(PG8_SB(1, 1), b3 + hstep, voffB); PG8_STAGE(PG8_SA(1, 0), a3, voffA);
;             PG8_WAIT_V(8); PG8_WAIT_L(0); PG8_BAR; PG8_MMA(1, 0, At, B0); PG8_MMA(1, 1, At, B1); PG8_BAR; PG8_SCHED;
;     ...
;         if constexpr (ALIGN_EPI) { if (wr == 0) PG8_BAR; }
	s_setprio 0
	s_add_i32 s26, s53, s37
	v_lshl_add_u64 v[160:161], v[160:161], 0, s[64:65]
	s_mov_b32 m0, s26
	ds_read_b128 v[186:189], v164 offset:49152
	ds_read_b128 v[190:193], v164 offset:50176
	ds_read_b128 v[194:197], v164 offset:51200
	ds_read_b128 v[198:201], v164 offset:52224
	ds_read_b128 v[202:205], v164 offset:53248
	ds_read_b128 v[206:209], v164 offset:54272
	ds_read_b128 v[210:213], v164 offset:55296
	ds_read_b128 v[214:217], v164 offset:56320
	global_load_lds_dwordx4 v[160:161], off
	s_add_i32 m0, s26, 0x2000
	s_add_u32 s24, s24, 0x40080
	v_lshl_add_u64 v[160:161], v[218:219], 0, s[64:65]
	s_addc_u32 s25, s25, 0
	s_add_i32 s26, s57, s37
	global_load_lds_dwordx4 v[160:161], off
	v_lshl_add_u64 v[160:161], s[24:25], 0, v[132:133]
	s_mov_b32 m0, s26
	s_nop 0
	global_load_lds_dwordx4 v[160:161], off
	v_lshl_add_u64 v[160:161], s[24:25], 0, v[136:137]
	s_add_i32 m0, s26, 0x2000
	s_nop 0
	global_load_lds_dwordx4 v[160:161], off
	v_lshl_add_u64 v[160:161], v[220:221], 0, s[64:65]
	s_mov_b32 m0, s43
	s_nop 0
	global_load_lds_dwordx4 v[160:161], off
	v_lshl_add_u64 v[160:161], v[222:223], 0, s[64:65]
	s_mov_b32 m0, s49
	s_nop 0
	global_load_lds_dwordx4 v[160:161], off
	s_waitcnt vmcnt(8)
	s_waitcnt lgkmcnt(0)
	s_setprio 1
	s_barrier
	v_mfma_f32_16x16x32_bf16 v[62:65], v[148:151], v[186:189], v[62:65]
	v_mfma_f32_16x16x32_bf16 v[58:61], v[156:159], v[186:189], v[58:61]
	v_mfma_f32_16x16x32_bf16 v[54:57], v[148:151], v[194:197], v[54:57]
	v_mfma_f32_16x16x32_bf16 v[50:53], v[156:159], v[194:197], v[50:53]
	v_mfma_f32_16x16x32_bf16 v[46:49], v[148:151], v[202:205], v[46:49]
	v_mfma_f32_16x16x32_bf16 v[42:45], v[156:159], v[202:205], v[42:45]
	v_mfma_f32_16x16x32_bf16 v[38:41], v[148:151], v[210:213], v[38:41]
	v_mfma_f32_16x16x32_bf16 v[34:37], v[156:159], v[210:213], v[34:37]
	v_mfma_f32_16x16x32_bf16 v[62:65], v[152:155], v[190:193], v[62:65]
	v_mfma_f32_16x16x32_bf16 v[58:61], v[166:169], v[190:193], v[58:61]
	v_mfma_f32_16x16x32_bf16 v[54:57], v[152:155], v[198:201], v[54:57]
	v_mfma_f32_16x16x32_bf16 v[50:53], v[166:169], v[198:201], v[50:53]
	v_mfma_f32_16x16x32_bf16 v[46:49], v[152:155], v[206:209], v[46:49]
	v_mfma_f32_16x16x32_bf16 v[42:45], v[166:169], v[206:209], v[42:45]
	v_mfma_f32_16x16x32_bf16 v[38:41], v[152:155], v[214:217], v[38:41]
	v_mfma_f32_16x16x32_bf16 v[34:37], v[166:169], v[214:217], v[34:37]
	s_setprio 0
	s_setprio 1
	v_mfma_f32_16x16x32_bf16 v[30:33], v[170:173], v[186:189], v[30:33]
	v_mfma_f32_16x16x32_bf16 v[26:29], v[178:181], v[186:189], v[26:29]
	v_mfma_f32_16x16x32_bf16 v[22:25], v[170:173], v[194:197], v[22:25]
	v_mfma_f32_16x16x32_bf16 v[18:21], v[178:181], v[194:197], v[18:21]
	v_mfma_f32_16x16x32_bf16 v[14:17], v[170:173], v[202:205], v[14:17]
	v_mfma_f32_16x16x32_bf16 v[10:13], v[178:181], v[202:205], v[10:13]
	v_mfma_f32_16x16x32_bf16 v[6:9], v[170:173], v[210:213], v[6:9]
	v_mfma_f32_16x16x32_bf16 v[2:5], v[178:181], v[210:213], v[2:5]
	v_mfma_f32_16x16x32_bf16 v[30:33], v[174:177], v[190:193], v[30:33]
	v_mfma_f32_16x16x32_bf16 v[26:29], v[182:185], v[190:193], v[26:29]
	v_mfma_f32_16x16x32_bf16 v[22:25], v[174:177], v[198:201], v[22:25]
	v_mfma_f32_16x16x32_bf16 v[18:21], v[182:185], v[198:201], v[18:21]
	v_mfma_f32_16x16x32_bf16 v[14:17], v[174:177], v[206:209], v[14:17]
	v_mfma_f32_16x16x32_bf16 v[10:13], v[182:185], v[206:209], v[10:13]
	v_mfma_f32_16x16x32_bf16 v[6:9], v[174:177], v[214:217], v[6:9]
	v_mfma_f32_16x16x32_bf16 v[2:5], v[182:185], v[214:217], v[2:5]
	s_barrier
	s_setprio 0
	s_add_u32 s22, s22, 0x100
	s_addc_u32 s23, s23, 0
	s_cmp_gt_u32 s56, 13
	s_cbranch_scc0 .LBB0_1685
	s_and_b64 vcc, exec, s[4:5]
	s_cbranch_vccz .LBB0_1688
	s_barrier

; #define PG8_STAGE(bufoff, gbase, voff) do { _Pragma("unroll") for (int _i = 0; _i < 2; ++_i) \
;         __builtin_amdgcn_global_load_lds((const unsigned*)((const char*)(gbase) + (voff)[_i]), (PG8_LAS unsigned*)(lds + (bufoff) + ldsw + _i * 8192), 16, 0, 0); } while (0)
; #define PG8_LDA(dst, b, h) do { _Pragma("unroll") for (int m = 0; m < 4; ++m) _Pragma("unroll") for (int k = 0; k < 2; ++k) dst[m][k] = *(const PG8_LAS bf16x8*)(lds + PG8_SA(b, h) + aoff + m * 2048 + k * 1024); } while (0)
; #define PG8_LDB(dst, b, h) do { _Pragma("unroll") for (int n = 0; n < 2; ++n) _Pragma("unroll") for (int k = 0; k < 2; ++k) dst[n][k] = *(const PG8_LAS bf16x8*)(lds + PG8_SB(b, h) + boff + n * 2048 + k * 1024); } while (0)
; #define PG8_MMA(ai, bj, At, Bt) do { __builtin_amdgcn_s_setprio(1); _Pragma("unroll") for (int m = 0; m < 4; ++m) _Pragma("unroll") for (int n = 0; n < 2; ++n) _Pragma("unroll") for (int k = 0; k < 2; ++k) \
;         acc[ai][bj][m][n] = __builtin_amdgcn_mfma_f32_16x16x32_bf16(Bt[n][k], At[m][k], acc[ai][bj][m][n], 0, 0, 0); __builtin_amdgcn_s_setprio(0); } while (0)
; #define PG8_WAIT_V(n) asm volatile("s_waitcnt vmcnt(" #n ")" ::: "memory")
; #define PG8_WAIT_VN(n) asm volatile("s_waitcnt vmcnt(%0)" :: "n"(n) : "memory")
; #define PG8_WAIT_L(n) asm volatile("s_waitcnt lgkmcnt(" #n ")" ::: "memory")
; template <class Epi, class Sched, bool ALIGN_EPI = false, bool SP2 = false>
; __device__ __forceinline__ void gemm_phase(PG8_LAS unsigned char* lds, const Gemm g, const Sched& S, const Epi& E, const int wave_id) {
;     ...
;             PG8_LDB(B0, 0, 0); PG8_LDB(B1, 0, 1); PG8_SCHED; PG8_LDA(At, 0, 0); PG8_STAGE(PG8_SA(1, 1), a1 + hstep, voffA);
;             PG8_WAIT_VN(8 + Epi::NS); if (strict) PG8_WAIT_V(8); PG8_WAIT_L(0); PG8_BAR; PG8_MMA(0, 0, At, B0); PG8_MMA(0, 1, At, B1); PG8_BAR; PG8_SCHED;
;             PG8_LDA(At, 0, 1); PG8_STAGE(PG8_SB(0, 0), b2, voffB); PG8_STAGE(PG8_SB(0, 1), b2 + hstep, voffB); PG8_STAGE(PG8_SA(0, 0), a2, voffA);
;             PG8_WAIT_VN(8 + Epi::NS); if (strict) PG8_WAIT_V(8); PG8_WAIT_L(0); PG8_BAR; PG8_MMA(1, 0, At, B0); PG8_MMA(1, 1, At, B1); PG8_BAR; PG8_SCHED;
;             PG8_LDB(B0, 1, 0); PG8_LDB(B1, 1, 1); PG8_SCHED; PG8_LDA(At, 1, 0); PG8_STAGE(PG8_SA(0, 1), a2 + hstep, voffA);
;             PG8_WAIT_V(8); PG8_WAIT_L(0); PG8_BAR; PG8_MMA(0, 0, At, B0); PG8_MMA(0, 1, At, B1); PG8_BAR; PG8_SCHED;
.LBB0_1821:
	s_waitcnt lgkmcnt(0)
	s_setprio 1
	s_barrier
	v_mfma_f32_16x16x32_bf16 v[62:65], v[146:149], v[186:189], v[62:65]
	v_mfma_f32_16x16x32_bf16 v[58:61], v[154:157], v[186:189], v[58:61]
	v_mfma_f32_16x16x32_bf16 v[46:49], v[146:149], v[178:181], v[46:49]
	v_mfma_f32_16x16x32_bf16 v[42:45], v[154:157], v[178:181], v[42:45]
	v_mfma_f32_16x16x32_bf16 v[30:33], v[146:149], v[170:173], v[30:33]
	v_mfma_f32_16x16x32_bf16 v[26:29], v[154:157], v[170:173], v[26:29]
	v_mfma_f32_16x16x32_bf16 v[14:17], v[146:149], v[162:165], v[14:17]
	v_mfma_f32_16x16x32_bf16 v[10:13], v[154:157], v[162:165], v[10:13]
	v_mfma_f32_16x16x32_bf16 v[62:65], v[150:153], v[190:193], v[62:65]
	v_mfma_f32_16x16x32_bf16 v[58:61], v[158:161], v[190:193], v[58:61]
	v_mfma_f32_16x16x32_bf16 v[46:49], v[150:153], v[182:185], v[46:49]
	v_mfma_f32_16x16x32_bf16 v[42:45], v[158:161], v[182:185], v[42:45]
	v_mfma_f32_16x16x32_bf16 v[30:33], v[150:153], v[174:177], v[30:33]
	v_mfma_f32_16x16x32_bf16 v[26:29], v[158:161], v[174:177], v[26:29]
	v_mfma_f32_16x16x32_bf16 v[14:17], v[150:153], v[166:169], v[14:17]
	v_mfma_f32_16x16x32_bf16 v[10:13], v[158:161], v[166:169], v[10:13]
	s_setprio 0
	s_setprio 1
	v_mfma_f32_16x16x32_bf16 v[54:57], v[130:133], v[186:189], v[54:57]
	v_mfma_f32_16x16x32_bf16 v[50:53], v[138:141], v[186:189], v[50:53]
	v_mfma_f32_16x16x32_bf16 v[38:41], v[130:133], v[178:181], v[38:41]
	v_mfma_f32_16x16x32_bf16 v[34:37], v[138:141], v[178:181], v[34:37]
	v_mfma_f32_16x16x32_bf16 v[22:25], v[130:133], v[170:173], v[22:25]
	v_mfma_f32_16x16x32_bf16 v[18:21], v[138:141], v[170:173], v[18:21]
	v_mfma_f32_16x16x32_bf16 v[6:9], v[130:133], v[162:165], v[6:9]
	v_mfma_f32_16x16x32_bf16 v[2:5], v[138:141], v[162:165], v[2:5]
	v_mfma_f32_16x16x32_bf16 v[54:57], v[134:137], v[190:193], v[54:57]
	v_mfma_f32_16x16x32_bf16 v[50:53], v[142:145], v[190:193], v[50:53]
	v_mfma_f32_16x16x32_bf16 v[38:41], v[134:137], v[182:185], v[38:41]
	v_mfma_f32_16x16x32_bf16 v[34:37], v[142:145], v[182:185], v[34:37]
	v_mfma_f32_16x16x32_bf16 v[22:25], v[134:137], v[174:177], v[22:25]
	v_mfma_f32_16x16x32_bf16 v[18:21], v[142:145], v[174:177], v[18:21]
	v_mfma_f32_16x16x32_bf16 v[6:9], v[134:137], v[166:169], v[6:9]
	v_mfma_f32_16x16x32_bf16 v[2:5], v[142:145], v[166:169], v[2:5]
	s_barrier
	s_setprio 0
	s_add_i32 s26, 0, 0x18000
	s_add_i32 s27, 0, 0x1c000
	v_add_u32_e32 v142, s26, v246
	v_add_u32_e32 v158, s27, v246
	ds_read_b128 v[130:133], v142
	ds_read_b128 v[134:137], v142 offset:1024
	ds_read_b128 v[138:141], v142 offset:2048
	ds_read_b128 v[142:145], v142 offset:3072
	ds_read_b128 v[146:149], v158
	ds_read_b128 v[150:153], v158 offset:1024
	ds_read_b128 v[154:157], v158 offset:2048
	ds_read_b128 v[158:161], v158 offset:3072
	s_add_u32 s24, s24, 0x40000
	s_addc_u32 s25, s25, 0
	s_mov_b32 m0, s50
	v_lshl_add_u64 v[194:195], s[24:25], 0, v[210:211]
	ds_read_b128 v[162:165], v247 offset:32768
	ds_read_b128 v[166:169], v247 offset:33792
	ds_read_b128 v[170:173], v247 offset:34816
	ds_read_b128 v[174:177], v247 offset:35840
	ds_read_b128 v[178:181], v247 offset:36864
	ds_read_b128 v[182:185], v247 offset:37888
	ds_read_b128 v[186:189], v247 offset:38912
	ds_read_b128 v[190:193], v247 offset:39936
	global_load_lds_dwordx4 v[194:195], off
	v_lshl_add_u64 v[194:195], s[24:25], 0, v[214:215]
	s_mov_b32 m0, s51
	s_nop 0
	global_load_lds_dwordx4 v[194:195], off
	s_waitcnt vmcnt(26)
	s_cmp_eq_u32 s100, 0
	s_cbranch_scc1 .Lthird_wait_relaxed_3
	s_waitcnt vmcnt(8)
; #define PG8_STAGE(bufoff, gbase, voff) do { _Pragma("unroll") for (int _i = 0; _i < 2; ++_i) \
;         __builtin_amdgcn_global_load_lds((const unsigned*)((const char*)(gbase) + (voff)[_i]), (PG8_LAS unsigned*)(lds + (bufoff) + ldsw + _i * 8192), 16, 0, 0); } while (0)
; #define PG8_WAIT_V(n) asm volatile("s_waitcnt vmcnt(" #n ")" ::: "memory")
; #define PG8_WAIT_VN(n) asm volatile("s_waitcnt vmcnt(%0)" :: "n"(n) : "memory")
; template <class Epi, class Sched, bool ALIGN_EPI = false, bool SP2 = false>
; __device__ __forceinline__ void gemm_phase(PG8_LAS unsigned char* lds, const Gemm g, const Sched& S, const Epi& E, const int wave_id) {
;     ...
;         for (int t = 0; t < nt; t += 2) {
;             const bool last = (t == nt - 2);
;             const char* a1 = cA + (size_t)(t + 1) * kstep;
;             const char* a2 = last ? nA : cA + (size_t)(t + 2) * kstep; const char* b2 = last ? nB : cB + (size_t)(t + 2) * kstep;
;             const char* a3 = a2 + kstep; const char* b3 = b2 + kstep;
;             if (last && has_next) S.a_ready(nxt);
;             if constexpr (SP2) {
;             int tz_ = __builtin_amdgcn_readfirstlane(t | (ui > 0 ? 0 : 1)); asm volatile("" : "+s"(tz_));
;             const bool strict = !(Epi::NS > 0 && tz_ == 0);
;             PG8_LDB(B0, 0, 0); PG8_LDB(B1, 0, 1); PG8_SCHED; PG8_LDA(At, 0, 0); PG8_STAGE(PG8_SA(1, 1), a1 + hstep, voffA);
;             PG8_WAIT_VN(8 + Epi::NS); if (strict) PG8_WAIT_V(8); PG8_WAIT_L(0); PG8_BAR; PG8_MMA(0, 0, At, B0); PG8_MMA(0, 1, At, B1); PG8_BAR; PG8_SCHED;
;             PG8_LDA(At, 0, 1); PG8_STAGE(PG8_SB(0, 0), b2, voffB); PG8_STAGE(PG8_SB(0, 1), b2 + hstep, voffB); PG8_STAGE(PG8_SA(0, 0), a2, voffA);
;             PG8_WAIT_VN(8 + Epi::NS); if (strict) PG8_WAIT_V(8); PG8_WAIT_L(0); PG8_BAR; PG8_MMA(1, 0, At, B0); PG8_MMA(1, 1, At, B1); PG8_BAR; PG8_SCHED;
;             PG8_LDB(B0, 1, 0); PG8_LDB(B1, 1, 1); PG8_SCHED; PG8_LDA(At, 1, 0); PG8_STAGE(PG8_SA(0, 1), a2 + hstep, voffA);
;             PG8_WAIT_V(8); PG8_WAIT_L(0); PG8_BAR; PG8_MMA(0, 0, At, B0); PG8_MMA(0, 1, At, B1); PG8_BAR; PG8_SCHED;
;             PG8_LDA(At, 1, 1); PG8_STAGE(PG8_SB(1, 0), b3, voffB); PG8_STAGE(PG8_SB(1, 1), b3 + hstep, voffB); PG8_STAGE(PG8_SA(1, 0), a3, voffA);
;             PG8_WAIT_V(8); PG8_WAIT_L(0); PG8_BAR; PG8_MMA(1, 0, At, B0); PG8_MMA(1, 1, At, B1); PG8_BAR; PG8_SCHED;
.Lthird_wait_relaxed_3:
	s_waitcnt lgkmcnt(0)
	s_setprio 1
	s_barrier
	v_mfma_f32_16x16x32_bf16 v[126:129], v[130:133], v[162:165], v[126:129]
	v_mfma_f32_16x16x32_bf16 v[122:125], v[138:141], v[162:165], v[122:125]
	v_mfma_f32_16x16x32_bf16 v[110:113], v[130:133], v[170:173], v[110:113]
	v_mfma_f32_16x16x32_bf16 v[106:109], v[138:141], v[170:173], v[106:109]
	v_mfma_f32_16x16x32_bf16 v[94:97], v[130:133], v[178:181], v[94:97]
	v_mfma_f32_16x16x32_bf16 v[90:93], v[138:141], v[178:181], v[90:93]
	v_mfma_f32_16x16x32_bf16 v[78:81], v[130:133], v[186:189], v[78:81]
	v_mfma_f32_16x16x32_bf16 v[74:77], v[138:141], v[186:189], v[74:77]
	v_mfma_f32_16x16x32_bf16 v[126:129], v[134:137], v[166:169], v[126:129]
	v_mfma_f32_16x16x32_bf16 v[122:125], v[142:145], v[166:169], v[122:125]
	v_mfma_f32_16x16x32_bf16 v[110:113], v[134:137], v[174:177], v[110:113]
	v_mfma_f32_16x16x32_bf16 v[106:109], v[142:145], v[174:177], v[106:109]
	v_mfma_f32_16x16x32_bf16 v[94:97], v[134:137], v[182:185], v[94:97]
	v_mfma_f32_16x16x32_bf16 v[90:93], v[142:145], v[182:185], v[90:93]
	v_mfma_f32_16x16x32_bf16 v[78:81], v[134:137], v[190:193], v[78:81]
	v_mfma_f32_16x16x32_bf16 v[74:77], v[142:145], v[190:193], v[74:77]
	s_setprio 0
	s_setprio 1
	v_mfma_f32_16x16x32_bf16 v[118:121], v[146:149], v[162:165], v[118:121]
	v_mfma_f32_16x16x32_bf16 v[114:117], v[154:157], v[162:165], v[114:117]
	v_mfma_f32_16x16x32_bf16 v[102:105], v[146:149], v[170:173], v[102:105]
	v_mfma_f32_16x16x32_bf16 v[98:101], v[154:157], v[170:173], v[98:101]
	v_mfma_f32_16x16x32_bf16 v[86:89], v[146:149], v[178:181], v[86:89]
	v_mfma_f32_16x16x32_bf16 v[82:85], v[154:157], v[178:181], v[82:85]
	v_mfma_f32_16x16x32_bf16 v[70:73], v[146:149], v[186:189], v[70:73]
	v_mfma_f32_16x16x32_bf16 v[66:69], v[154:157], v[186:189], v[66:69]
	v_mfma_f32_16x16x32_bf16 v[118:121], v[150:153], v[166:169], v[118:121]
	v_mfma_f32_16x16x32_bf16 v[114:117], v[158:161], v[166:169], v[114:117]
	v_mfma_f32_16x16x32_bf16 v[102:105], v[150:153], v[174:177], v[102:105]
	v_mfma_f32_16x16x32_bf16 v[98:101], v[158:161], v[174:177], v[98:101]
	v_mfma_f32_16x16x32_bf16 v[86:89], v[150:153], v[182:185], v[86:89]
	v_mfma_f32_16x16x32_bf16 v[82:85], v[158:161], v[182:185], v[82:85]
	v_mfma_f32_16x16x32_bf16 v[70:73], v[150:153], v[190:193], v[70:73]
	v_mfma_f32_16x16x32_bf16 v[66:69], v[158:161], v[190:193], v[66:69]
	s_barrier
	s_setprio 0
	s_add_i32 s24, s26, s38
	v_lshl_add_u64 v[194:195], v[232:233], 0, s[64:65]
	s_mov_b32 m0, s24
	ds_read_b128 v[162:165], v247 offset:49152
	ds_read_b128 v[166:169], v247 offset:50176
	ds_read_b128 v[170:173], v247 offset:51200
	ds_read_b128 v[174:177], v247 offset:52224
	ds_read_b128 v[178:181], v247 offset:53248
	ds_read_b128 v[182:185], v247 offset:54272
	ds_read_b128 v[186:189], v247 offset:55296
	ds_read_b128 v[190:193], v247 offset:56320
	global_load_lds_dwordx4 v[194:195], off
	s_add_i32 m0, s24, 0x2000
	s_add_u32 s22, s22, 0x40080
	v_lshl_add_u64 v[194:195], v[230:231], 0, s[64:65]
	s_addc_u32 s23, s23, 0
	s_add_i32 s24, s27, s38
	global_load_lds_dwordx4 v[194:195], off
	v_lshl_add_u64 v[194:195], s[22:23], 0, v[212:213]
	s_mov_b32 m0, s24
	s_nop 0
	global_load_lds_dwordx4 v[194:195], off
	v_lshl_add_u64 v[194:195], s[22:23], 0, v[216:217]
	s_add_i32 m0, s24, 0x2000
	s_nop 0
	global_load_lds_dwordx4 v[194:195], off
	v_lshl_add_u64 v[194:195], v[226:227], 0, s[64:65]
	s_mov_b32 m0, s54
	s_nop 0
	global_load_lds_dwordx4 v[194:195], off
	v_lshl_add_u64 v[194:195], v[228:229], 0, s[64:65]
	s_mov_b32 m0, s56
	s_nop 0
	global_load_lds_dwordx4 v[194:195], off
	s_waitcnt vmcnt(8)
	s_waitcnt lgkmcnt(0)
	s_setprio 1
	s_barrier
	v_mfma_f32_16x16x32_bf16 v[62:65], v[130:133], v[162:165], v[62:65]
	v_mfma_f32_16x16x32_bf16 v[58:61], v[138:141], v[162:165], v[58:61]
	v_mfma_f32_16x16x32_bf16 v[46:49], v[130:133], v[170:173], v[46:49]
	v_mfma_f32_16x16x32_bf16 v[42:45], v[138:141], v[170:173], v[42:45]
	v_mfma_f32_16x16x32_bf16 v[30:33], v[130:133], v[178:181], v[30:33]
	v_mfma_f32_16x16x32_bf16 v[26:29], v[138:141], v[178:181], v[26:29]
	v_mfma_f32_16x16x32_bf16 v[14:17], v[130:133], v[186:189], v[14:17]
	v_mfma_f32_16x16x32_bf16 v[10:13], v[138:141], v[186:189], v[10:13]
	v_mfma_f32_16x16x32_bf16 v[62:65], v[134:137], v[166:169], v[62:65]
	v_mfma_f32_16x16x32_bf16 v[58:61], v[142:145], v[166:169], v[58:61]
	v_mfma_f32_16x16x32_bf16 v[46:49], v[134:137], v[174:177], v[46:49]
	v_mfma_f32_16x16x32_bf16 v[42:45], v[142:145], v[174:177], v[42:45]
	v_mfma_f32_16x16x32_bf16 v[30:33], v[134:137], v[182:185], v[30:33]
	v_mfma_f32_16x16x32_bf16 v[26:29], v[142:145], v[182:185], v[26:29]
	v_mfma_f32_16x16x32_bf16 v[14:17], v[134:137], v[190:193], v[14:17]
	v_mfma_f32_16x16x32_bf16 v[10:13], v[142:145], v[190:193], v[10:13]
	s_setprio 0
	s_setprio 1
	v_mfma_f32_16x16x32_bf16 v[54:57], v[146:149], v[162:165], v[54:57]
	v_mfma_f32_16x16x32_bf16 v[50:53], v[154:157], v[162:165], v[50:53]
	v_mfma_f32_16x16x32_bf16 v[38:41], v[146:149], v[170:173], v[38:41]
	v_mfma_f32_16x16x32_bf16 v[34:37], v[154:157], v[170:173], v[34:37]
	v_mfma_f32_16x16x32_bf16 v[22:25], v[146:149], v[178:181], v[22:25]
	v_mfma_f32_16x16x32_bf16 v[18:21], v[154:157], v[178:181], v[18:21]
	v_mfma_f32_16x16x32_bf16 v[6:9], v[146:149], v[186:189], v[6:9]
	v_mfma_f32_16x16x32_bf16 v[2:5], v[154:157], v[186:189], v[2:5]
	v_mfma_f32_16x16x32_bf16 v[54:57], v[150:153], v[166:169], v[54:57]
	v_mfma_f32_16x16x32_bf16 v[50:53], v[158:161], v[166:169], v[50:53]
	v_mfma_f32_16x16x32_bf16 v[38:41], v[150:153], v[174:177], v[38:41]
	v_mfma_f32_16x16x32_bf16 v[34:37], v[158:161], v[174:177], v[34:37]
	v_mfma_f32_16x16x32_bf16 v[22:25], v[150:153], v[182:185], v[22:25]
	v_mfma_f32_16x16x32_bf16 v[18:21], v[158:161], v[182:185], v[18:21]
	v_mfma_f32_16x16x32_bf16 v[6:9], v[150:153], v[190:193], v[6:9]
	v_mfma_f32_16x16x32_bf16 v[2:5], v[158:161], v[190:193], v[2:5]
	s_barrier
	s_setprio 0
	s_add_i32 s74, s74, 2
	s_add_u32 s20, s20, 0x100
	s_addc_u32 s21, s21, 0
	s_cmp_gt_u32 s74, 13
	s_cbranch_scc1 .LBB0_1826

; #define PG8_STAGE(bufoff, gbase, voff) do { _Pragma("unroll") for (int _i = 0; _i < 2; ++_i) \
;         __builtin_amdgcn_global_load_lds((const unsigned*)((const char*)(gbase) + (voff)[_i]), (PG8_LAS unsigned*)(lds + (bufoff) + ldsw + _i * 8192), 16, 0, 0); } while (0)
; #define PG8_LDA(dst, b, h) do { _Pragma("unroll") for (int m = 0; m < 4; ++m) _Pragma("unroll") for (int k = 0; k < 2; ++k) dst[m][k] = *(const PG8_LAS bf16x8*)(lds + PG8_SA(b, h) + aoff + m * 2048 + k * 1024); } while (0)
; #define PG8_LDB(dst, b, h) do { _Pragma("unroll") for (int n = 0; n < 2; ++n) _Pragma("unroll") for (int k = 0; k < 2; ++k) dst[n][k] = *(const PG8_LAS bf16x8*)(lds + PG8_SB(b, h) + boff + n * 2048 + k * 1024); } while (0)
; #define PG8_WAIT_V(n) asm volatile("s_waitcnt vmcnt(" #n ")" ::: "memory")
; #define PG8_WAIT_VN(n) asm volatile("s_waitcnt vmcnt(%0)" :: "n"(n) : "memory")
; #define PG8_WAIT_L(n) asm volatile("s_waitcnt lgkmcnt(" #n ")" ::: "memory")
; template <class Epi, class Sched, bool ALIGN_EPI = false, bool SP2 = false>
; __device__ __forceinline__ void gemm_phase(PG8_LAS unsigned char* lds, const Gemm g, const Sched& S, const Epi& E, const int wave_id) {
;     ...
;         for (int t = 0; t < nt; t += 2) {
;             const bool last = (t == nt - 2);
;             const char* a1 = cA + (size_t)(t + 1) * kstep;
;             const char* a2 = last ? nA : cA + (size_t)(t + 2) * kstep; const char* b2 = last ? nB : cB + (size_t)(t + 2) * kstep;
;             const char* a3 = a2 + kstep; const char* b3 = b2 + kstep;
;             if (last && has_next) S.a_ready(nxt);
;             if constexpr (SP2) {
;             int tz_ = __builtin_amdgcn_readfirstlane(t | (ui > 0 ? 0 : 1)); asm volatile("" : "+s"(tz_));
;             const bool strict = !(Epi::NS > 0 && tz_ == 0);
;             PG8_LDB(B0, 0, 0); PG8_LDB(B1, 0, 1); PG8_SCHED; PG8_LDA(At, 0, 0); PG8_STAGE(PG8_SA(1, 1), a1 + hstep, voffA);
;             PG8_WAIT_VN(8 + Epi::NS); if (strict) PG8_WAIT_V(8); PG8_WAIT_L(0); PG8_BAR; PG8_MMA(0, 0, At, B0); PG8_MMA(0, 1, At, B1); PG8_BAR; PG8_SCHED;
;             PG8_LDA(At, 0, 1); PG8_STAGE(PG8_SB(0, 0), b2, voffB); PG8_STAGE(PG8_SB(0, 1), b2 + hstep, voffB); PG8_STAGE(PG8_SA(0, 0), a2, voffA);
;             PG8_WAIT_VN(8 + Epi::NS); if (strict) PG8_WAIT_V(8); PG8_WAIT_L(0); PG8_BAR; PG8_MMA(1, 0, At, B0); PG8_MMA(1, 1, At, B1); PG8_BAR; PG8_SCHED;
.LBB0_1824:
	s_add_u32 s22, s18, s20
	s_addc_u32 s23, s19, s21
	s_add_u32 s22, s22, 0x100
	s_addc_u32 s23, s23, 0
	s_add_u32 s53, s68, s20
	s_addc_u32 s75, s69, s21
	s_cmpk_eq_i32 s20, 0x700
	s_cselect_b32 s25, s11, s23
	s_cselect_b32 s24, s63, s22
	s_cselect_b32 s23, s9, s75
	s_cselect_b32 s22, s67, s53
	s_waitcnt lgkmcnt(0)
	s_setprio 1
	s_barrier
	v_mfma_f32_16x16x32_bf16 v[126:129], v[146:149], v[186:189], v[126:129]
	v_mfma_f32_16x16x32_bf16 v[122:125], v[154:157], v[186:189], v[122:125]
	v_mfma_f32_16x16x32_bf16 v[110:113], v[146:149], v[178:181], v[110:113]
	v_mfma_f32_16x16x32_bf16 v[106:109], v[154:157], v[178:181], v[106:109]
	v_mfma_f32_16x16x32_bf16 v[94:97], v[146:149], v[170:173], v[94:97]
	v_mfma_f32_16x16x32_bf16 v[90:93], v[154:157], v[170:173], v[90:93]
	v_mfma_f32_16x16x32_bf16 v[78:81], v[146:149], v[162:165], v[78:81]
	v_mfma_f32_16x16x32_bf16 v[74:77], v[154:157], v[162:165], v[74:77]
	v_mfma_f32_16x16x32_bf16 v[126:129], v[150:153], v[190:193], v[126:129]
	v_mfma_f32_16x16x32_bf16 v[122:125], v[158:161], v[190:193], v[122:125]
	v_mfma_f32_16x16x32_bf16 v[110:113], v[150:153], v[182:185], v[110:113]
	v_mfma_f32_16x16x32_bf16 v[106:109], v[158:161], v[182:185], v[106:109]
	v_mfma_f32_16x16x32_bf16 v[94:97], v[150:153], v[174:177], v[94:97]
	v_mfma_f32_16x16x32_bf16 v[90:93], v[158:161], v[174:177], v[90:93]
	v_mfma_f32_16x16x32_bf16 v[78:81], v[150:153], v[166:169], v[78:81]
	v_mfma_f32_16x16x32_bf16 v[74:77], v[158:161], v[166:169], v[74:77]
	s_setprio 0
	s_setprio 1
	v_mfma_f32_16x16x32_bf16 v[118:121], v[130:133], v[186:189], v[118:121]
	v_mfma_f32_16x16x32_bf16 v[114:117], v[138:141], v[186:189], v[114:117]
	v_mfma_f32_16x16x32_bf16 v[102:105], v[130:133], v[178:181], v[102:105]
	v_mfma_f32_16x16x32_bf16 v[98:101], v[138:141], v[178:181], v[98:101]
	v_mfma_f32_16x16x32_bf16 v[86:89], v[130:133], v[170:173], v[86:89]
	v_mfma_f32_16x16x32_bf16 v[82:85], v[138:141], v[170:173], v[82:85]
	v_mfma_f32_16x16x32_bf16 v[70:73], v[130:133], v[162:165], v[70:73]
	v_mfma_f32_16x16x32_bf16 v[66:69], v[138:141], v[162:165], v[66:69]
	v_mfma_f32_16x16x32_bf16 v[118:121], v[134:137], v[190:193], v[118:121]
	v_mfma_f32_16x16x32_bf16 v[114:117], v[142:145], v[190:193], v[114:117]
	v_mfma_f32_16x16x32_bf16 v[102:105], v[134:137], v[182:185], v[102:105]
	v_mfma_f32_16x16x32_bf16 v[98:101], v[142:145], v[182:185], v[98:101]
	v_mfma_f32_16x16x32_bf16 v[86:89], v[134:137], v[174:177], v[86:89]
	v_mfma_f32_16x16x32_bf16 v[82:85], v[142:145], v[174:177], v[82:85]
	v_mfma_f32_16x16x32_bf16 v[70:73], v[134:137], v[166:169], v[70:73]
	v_mfma_f32_16x16x32_bf16 v[66:69], v[142:145], v[166:169], v[66:69]
	s_barrier
	s_setprio 0
	s_mov_b32 m0, s40
	v_lshl_add_u64 v[232:233], s[22:23], 0, v[212:213]
	s_add_u32 s90, s22, 0x40000
	ds_read_b128 v[186:189], v247 offset:16384
	ds_read_b128 v[190:193], v247 offset:17408
	ds_read_b128 v[178:181], v247 offset:18432
	ds_read_b128 v[182:185], v247 offset:19456
	ds_read_b128 v[170:173], v247 offset:20480
	ds_read_b128 v[174:177], v247 offset:21504
	ds_read_b128 v[162:165], v247 offset:22528
	ds_read_b128 v[166:169], v247 offset:23552
	global_load_lds_dwordx4 v[232:233], off
	v_lshl_add_u64 v[230:231], s[22:23], 0, v[216:217]
	s_mov_b32 m0, s41
	s_addc_u32 s91, s23, 0
	global_load_lds_dwordx4 v[230:231], off
	v_lshl_add_u64 v[194:195], s[90:91], 0, v[212:213]
	s_mov_b32 m0, s42
	v_lshl_add_u64 v[226:227], s[24:25], 0, v[210:211]
	global_load_lds_dwordx4 v[194:195], off
	v_lshl_add_u64 v[194:195], s[90:91], 0, v[216:217]
	s_mov_b32 m0, s43
	v_lshl_add_u64 v[228:229], s[24:25], 0, v[214:215]
	global_load_lds_dwordx4 v[194:195], off
	s_mov_b32 m0, s39
	s_andn2_b64 vcc, exec, s[26:27]
	global_load_lds_dwordx4 v[226:227], off
	s_mov_b32 m0, s49
	s_nop 0
	global_load_lds_dwordx4 v[228:229], off
	s_waitcnt vmcnt(24)
	s_cbranch_vccnz .LBB0_1821
	s_waitcnt vmcnt(8)
	s_branch .LBB0_1821

; #define PG8_STAGE(bufoff, gbase, voff) do { _Pragma("unroll") for (int _i = 0; _i < 2; ++_i) \
;         __builtin_amdgcn_global_load_lds((const unsigned*)((const char*)(gbase) + (voff)[_i]), (PG8_LAS unsigned*)(lds + (bufoff) + ldsw + _i * 8192), 16, 0, 0); } while (0)
; #define PG8_LDA(dst, b, h) do { _Pragma("unroll") for (int m = 0; m < 4; ++m) _Pragma("unroll") for (int k = 0; k < 2; ++k) dst[m][k] = *(const PG8_LAS bf16x8*)(lds + PG8_SA(b, h) + aoff + m * 2048 + k * 1024); } while (0)
; #define PG8_LDB(dst, b, h) do { _Pragma("unroll") for (int n = 0; n < 2; ++n) _Pragma("unroll") for (int k = 0; k < 2; ++k) dst[n][k] = *(const PG8_LAS bf16x8*)(lds + PG8_SB(b, h) + boff + n * 2048 + k * 1024); } while (0)
; #define PG8_MMA(ai, bj, At, Bt) do { __builtin_amdgcn_s_setprio(1); _Pragma("unroll") for (int m = 0; m < 4; ++m) _Pragma("unroll") for (int n = 0; n < 2; ++n) _Pragma("unroll") for (int k = 0; k < 2; ++k) \
;         acc[ai][bj][m][n] = __builtin_amdgcn_mfma_f32_16x16x32_bf16(Bt[n][k], At[m][k], acc[ai][bj][m][n], 0, 0, 0); __builtin_amdgcn_s_setprio(0); } while (0)
; #define PG8_WAIT_V(n) asm volatile("s_waitcnt vmcnt(" #n ")" ::: "memory")
; #define PG8_WAIT_VN(n) asm volatile("s_waitcnt vmcnt(%0)" :: "n"(n) : "memory")
; #define PG8_WAIT_L(n) asm volatile("s_waitcnt lgkmcnt(" #n ")" ::: "memory")
; #define PG8_BAR __builtin_amdgcn_s_barrier()
; #define PG8_SCHED __builtin_amdgcn_sched_barrier(0)
; template <class Epi, class Sched, bool ALIGN_EPI = false, bool SP2 = false>
; __device__ __forceinline__ void gemm_phase(PG8_LAS unsigned char* lds, const Gemm g, const Sched& S, const Epi& E, const int wave_id) {
;     ...
;             PG8_WAIT_VN(8 + Epi::NS); if (strict) PG8_WAIT_V(8); PG8_WAIT_L(0); PG8_BAR; PG8_MMA(0, 0, At, B0); PG8_MMA(0, 1, At, B1); PG8_BAR; PG8_SCHED;
;             PG8_LDA(At, 0, 1); PG8_STAGE(PG8_SB(0, 0), b2, voffB); PG8_STAGE(PG8_SB(0, 1), b2 + hstep, voffB); PG8_STAGE(PG8_SA(0, 0), a2, voffA);
;             PG8_WAIT_VN(8 + Epi::NS); if (strict) PG8_WAIT_V(8); PG8_WAIT_L(0); PG8_BAR; PG8_MMA(1, 0, At, B0); PG8_MMA(1, 1, At, B1); PG8_BAR; PG8_SCHED;
;             PG8_LDB(B0, 1, 0); PG8_LDB(B1, 1, 1); PG8_SCHED; PG8_LDA(At, 1, 0); PG8_STAGE(PG8_SA(0, 1), a2 + hstep, voffA);
;             PG8_WAIT_V(8); PG8_WAIT_L(0); PG8_BAR; PG8_MMA(0, 0, At, B0); PG8_MMA(0, 1, At, B1); PG8_BAR; PG8_SCHED;
.LBB0_1889:
	s_waitcnt lgkmcnt(0)
	s_setprio 1
	s_barrier
	v_mfma_f32_16x16x32_bf16 v[62:65], v[146:149], v[186:189], v[62:65]
	v_mfma_f32_16x16x32_bf16 v[58:61], v[154:157], v[186:189], v[58:61]
	v_mfma_f32_16x16x32_bf16 v[54:57], v[146:149], v[178:181], v[54:57]
	v_mfma_f32_16x16x32_bf16 v[50:53], v[154:157], v[178:181], v[50:53]
	v_mfma_f32_16x16x32_bf16 v[30:33], v[146:149], v[170:173], v[30:33]
	v_mfma_f32_16x16x32_bf16 v[26:29], v[154:157], v[170:173], v[26:29]
	v_mfma_f32_16x16x32_bf16 v[22:25], v[146:149], v[162:165], v[22:25]
	v_mfma_f32_16x16x32_bf16 v[18:21], v[154:157], v[162:165], v[18:21]
	v_mfma_f32_16x16x32_bf16 v[62:65], v[150:153], v[190:193], v[62:65]
	v_mfma_f32_16x16x32_bf16 v[58:61], v[158:161], v[190:193], v[58:61]
	v_mfma_f32_16x16x32_bf16 v[54:57], v[150:153], v[182:185], v[54:57]
	v_mfma_f32_16x16x32_bf16 v[50:53], v[158:161], v[182:185], v[50:53]
	v_mfma_f32_16x16x32_bf16 v[30:33], v[150:153], v[174:177], v[30:33]
	v_mfma_f32_16x16x32_bf16 v[26:29], v[158:161], v[174:177], v[26:29]
	v_mfma_f32_16x16x32_bf16 v[22:25], v[150:153], v[166:169], v[22:25]
	v_mfma_f32_16x16x32_bf16 v[18:21], v[158:161], v[166:169], v[18:21]
	s_setprio 0
	s_setprio 1
	v_mfma_f32_16x16x32_bf16 v[46:49], v[130:133], v[186:189], v[46:49]
	v_mfma_f32_16x16x32_bf16 v[42:45], v[138:141], v[186:189], v[42:45]
	v_mfma_f32_16x16x32_bf16 v[38:41], v[130:133], v[178:181], v[38:41]
	v_mfma_f32_16x16x32_bf16 v[34:37], v[138:141], v[178:181], v[34:37]
	v_mfma_f32_16x16x32_bf16 v[14:17], v[130:133], v[170:173], v[14:17]
	v_mfma_f32_16x16x32_bf16 v[10:13], v[138:141], v[170:173], v[10:13]
	v_mfma_f32_16x16x32_bf16 v[6:9], v[130:133], v[162:165], v[6:9]
	v_mfma_f32_16x16x32_bf16 v[2:5], v[138:141], v[162:165], v[2:5]
	v_mfma_f32_16x16x32_bf16 v[46:49], v[134:137], v[190:193], v[46:49]
	v_mfma_f32_16x16x32_bf16 v[42:45], v[142:145], v[190:193], v[42:45]
	v_mfma_f32_16x16x32_bf16 v[38:41], v[134:137], v[182:185], v[38:41]
	v_mfma_f32_16x16x32_bf16 v[34:37], v[142:145], v[182:185], v[34:37]
	v_mfma_f32_16x16x32_bf16 v[14:17], v[134:137], v[174:177], v[14:17]
	v_mfma_f32_16x16x32_bf16 v[10:13], v[142:145], v[174:177], v[10:13]
	v_mfma_f32_16x16x32_bf16 v[6:9], v[134:137], v[166:169], v[6:9]
	v_mfma_f32_16x16x32_bf16 v[2:5], v[142:145], v[166:169], v[2:5]
	s_barrier
	s_setprio 0
	s_add_i32 s16, 0, 0x18000
	s_add_i32 s17, 0, 0x1c000
	v_add_u32_e32 v142, s16, v231
	v_add_u32_e32 v158, s17, v231
	ds_read_b128 v[130:133], v142
	ds_read_b128 v[134:137], v142 offset:1024
	ds_read_b128 v[138:141], v142 offset:2048
	ds_read_b128 v[142:145], v142 offset:3072
	ds_read_b128 v[146:149], v158
	ds_read_b128 v[150:153], v158 offset:1024
	ds_read_b128 v[154:157], v158 offset:2048
	ds_read_b128 v[158:161], v158 offset:3072
	s_add_u32 s14, s14, 0x40000
	s_addc_u32 s15, s15, 0
	s_mov_b32 m0, s28
	v_lshl_add_u64 v[194:195], s[14:15], 0, v[210:211]
	ds_read_b128 v[162:165], v232 offset:32768
	ds_read_b128 v[166:169], v232 offset:33792
	ds_read_b128 v[170:173], v232 offset:34816
	ds_read_b128 v[174:177], v232 offset:35840
	ds_read_b128 v[178:181], v232 offset:36864
	ds_read_b128 v[182:185], v232 offset:37888
	ds_read_b128 v[186:189], v232 offset:38912
	ds_read_b128 v[190:193], v232 offset:39936
	global_load_lds_dwordx4 v[194:195], off
	v_lshl_add_u64 v[194:195], s[14:15], 0, v[214:215]
	s_mov_b32 m0, s29
	s_nop 0
	global_load_lds_dwordx4 v[194:195], off
	s_waitcnt vmcnt(8)
	s_waitcnt lgkmcnt(0)
	s_setprio 1
	s_barrier
	v_mfma_f32_16x16x32_bf16 v[126:129], v[130:133], v[162:165], v[126:129]
	v_mfma_f32_16x16x32_bf16 v[122:125], v[138:141], v[162:165], v[122:125]
	v_mfma_f32_16x16x32_bf16 v[118:121], v[130:133], v[170:173], v[118:121]
	v_mfma_f32_16x16x32_bf16 v[114:117], v[138:141], v[170:173], v[114:117]
	v_mfma_f32_16x16x32_bf16 v[94:97], v[130:133], v[178:181], v[94:97]
	v_mfma_f32_16x16x32_bf16 v[90:93], v[138:141], v[178:181], v[90:93]
	v_mfma_f32_16x16x32_bf16 v[86:89], v[130:133], v[186:189], v[86:89]
	v_mfma_f32_16x16x32_bf16 v[82:85], v[138:141], v[186:189], v[82:85]
	v_mfma_f32_16x16x32_bf16 v[126:129], v[134:137], v[166:169], v[126:129]
	v_mfma_f32_16x16x32_bf16 v[122:125], v[142:145], v[166:169], v[122:125]
	v_mfma_f32_16x16x32_bf16 v[118:121], v[134:137], v[174:177], v[118:121]
	v_mfma_f32_16x16x32_bf16 v[114:117], v[142:145], v[174:177], v[114:117]
	v_mfma_f32_16x16x32_bf16 v[94:97], v[134:137], v[182:185], v[94:97]
	v_mfma_f32_16x16x32_bf16 v[90:93], v[142:145], v[182:185], v[90:93]
	v_mfma_f32_16x16x32_bf16 v[86:89], v[134:137], v[190:193], v[86:89]
	v_mfma_f32_16x16x32_bf16 v[82:85], v[142:145], v[190:193], v[82:85]
	s_setprio 0
	s_setprio 1
	v_mfma_f32_16x16x32_bf16 v[110:113], v[146:149], v[162:165], v[110:113]
	v_mfma_f32_16x16x32_bf16 v[106:109], v[154:157], v[162:165], v[106:109]
	v_mfma_f32_16x16x32_bf16 v[102:105], v[146:149], v[170:173], v[102:105]
	v_mfma_f32_16x16x32_bf16 v[98:101], v[154:157], v[170:173], v[98:101]
	v_mfma_f32_16x16x32_bf16 v[78:81], v[146:149], v[178:181], v[78:81]
	v_mfma_f32_16x16x32_bf16 v[74:77], v[154:157], v[178:181], v[74:77]
	v_mfma_f32_16x16x32_bf16 v[70:73], v[146:149], v[186:189], v[70:73]
	v_mfma_f32_16x16x32_bf16 v[66:69], v[154:157], v[186:189], v[66:69]
	v_mfma_f32_16x16x32_bf16 v[110:113], v[150:153], v[166:169], v[110:113]
	v_mfma_f32_16x16x32_bf16 v[106:109], v[158:161], v[166:169], v[106:109]
	v_mfma_f32_16x16x32_bf16 v[102:105], v[150:153], v[174:177], v[102:105]
	v_mfma_f32_16x16x32_bf16 v[98:101], v[158:161], v[174:177], v[98:101]
	v_mfma_f32_16x16x32_bf16 v[78:81], v[150:153], v[182:185], v[78:81]
	v_mfma_f32_16x16x32_bf16 v[74:77], v[158:161], v[182:185], v[74:77]
	v_mfma_f32_16x16x32_bf16 v[70:73], v[150:153], v[190:193], v[70:73]
	v_mfma_f32_16x16x32_bf16 v[66:69], v[158:161], v[190:193], v[66:69]
	s_barrier
; #define PG8_STAGE(bufoff, gbase, voff) do { _Pragma("unroll") for (int _i = 0; _i < 2; ++_i) \
;         __builtin_amdgcn_global_load_lds((const unsigned*)((const char*)(gbase) + (voff)[_i]), (PG8_LAS unsigned*)(lds + (bufoff) + ldsw + _i * 8192), 16, 0, 0); } while (0)
; #define PG8_LDA(dst, b, h) do { _Pragma("unroll") for (int m = 0; m < 4; ++m) _Pragma("unroll") for (int k = 0; k < 2; ++k) dst[m][k] = *(const PG8_LAS bf16x8*)(lds + PG8_SA(b, h) + aoff + m * 2048 + k * 1024); } while (0)
; #define PG8_MMA(ai, bj, At, Bt) do { __builtin_amdgcn_s_setprio(1); _Pragma("unroll") for (int m = 0; m < 4; ++m) _Pragma("unroll") for (int n = 0; n < 2; ++n) _Pragma("unroll") for (int k = 0; k < 2; ++k) \
;         acc[ai][bj][m][n] = __builtin_amdgcn_mfma_f32_16x16x32_bf16(Bt[n][k], At[m][k], acc[ai][bj][m][n], 0, 0, 0); __builtin_amdgcn_s_setprio(0); } while (0)
; #define PG8_WAIT_V(n) asm volatile("s_waitcnt vmcnt(" #n ")" ::: "memory")
; #define PG8_WAIT_L(n) asm volatile("s_waitcnt lgkmcnt(" #n ")" ::: "memory")
; #define PG8_BAR __builtin_amdgcn_s_barrier()
; #define PG8_SCHED __builtin_amdgcn_sched_barrier(0)
; template <class Epi, class Sched, bool ALIGN_EPI = false, bool SP2 = false>
; __device__ __forceinline__ void gemm_phase(PG8_LAS unsigned char* lds, const Gemm g, const Sched& S, const Epi& E, const int wave_id) {
;     ...
;         for (int t = 0; t < nt; t += 2) {
;     ...
;             PG8_LDA(At, 1, 1); PG8_STAGE(PG8_SB(1, 0), b3, voffB); PG8_STAGE(PG8_SB(1, 1), b3 + hstep, voffB); PG8_STAGE(PG8_SA(1, 0), a3, voffA);
;             PG8_WAIT_V(8); PG8_WAIT_L(0); PG8_BAR; PG8_MMA(1, 0, At, B0); PG8_MMA(1, 1, At, B1); PG8_BAR; PG8_SCHED;
	s_setprio 0
	s_add_i32 s14, s16, s21
	v_lshl_add_u64 v[194:195], v[228:229], 0, s[64:65]
	s_mov_b32 m0, s14
	ds_read_b128 v[162:165], v232 offset:49152
	ds_read_b128 v[166:169], v232 offset:50176
	ds_read_b128 v[170:173], v232 offset:51200
	ds_read_b128 v[174:177], v232 offset:52224
	ds_read_b128 v[178:181], v232 offset:53248
	ds_read_b128 v[182:185], v232 offset:54272
	ds_read_b128 v[186:189], v232 offset:55296
	ds_read_b128 v[190:193], v232 offset:56320
	global_load_lds_dwordx4 v[194:195], off
	s_add_i32 m0, s14, 0x2000
	s_add_u32 s12, s12, 0x40080
	v_lshl_add_u64 v[194:195], v[226:227], 0, s[64:65]
	s_addc_u32 s13, s13, 0
	s_add_i32 s14, s17, s21
	global_load_lds_dwordx4 v[194:195], off
	v_lshl_add_u64 v[194:195], s[12:13], 0, v[212:213]
	s_mov_b32 m0, s14
	s_nop 0
	global_load_lds_dwordx4 v[194:195], off
	v_lshl_add_u64 v[194:195], s[12:13], 0, v[216:217]
	s_add_i32 m0, s14, 0x2000
	s_nop 0
	global_load_lds_dwordx4 v[194:195], off
	v_lshl_add_u64 v[194:195], v[222:223], 0, s[64:65]
	s_mov_b32 m0, s30
	s_nop 0
	global_load_lds_dwordx4 v[194:195], off
	v_lshl_add_u64 v[194:195], v[224:225], 0, s[64:65]
	s_mov_b32 m0, s31
	s_nop 0
	global_load_lds_dwordx4 v[194:195], off
	s_waitcnt vmcnt(8)
	s_waitcnt lgkmcnt(0)
	s_setprio 1
	s_barrier
	v_mfma_f32_16x16x32_bf16 v[62:65], v[130:133], v[162:165], v[62:65]
	v_mfma_f32_16x16x32_bf16 v[58:61], v[138:141], v[162:165], v[58:61]
	v_mfma_f32_16x16x32_bf16 v[54:57], v[130:133], v[170:173], v[54:57]
	v_mfma_f32_16x16x32_bf16 v[50:53], v[138:141], v[170:173], v[50:53]
	v_mfma_f32_16x16x32_bf16 v[30:33], v[130:133], v[178:181], v[30:33]
	v_mfma_f32_16x16x32_bf16 v[26:29], v[138:141], v[178:181], v[26:29]
	v_mfma_f32_16x16x32_bf16 v[22:25], v[130:133], v[186:189], v[22:25]
	v_mfma_f32_16x16x32_bf16 v[18:21], v[138:141], v[186:189], v[18:21]
	v_mfma_f32_16x16x32_bf16 v[62:65], v[134:137], v[166:169], v[62:65]
	v_mfma_f32_16x16x32_bf16 v[58:61], v[142:145], v[166:169], v[58:61]
	v_mfma_f32_16x16x32_bf16 v[54:57], v[134:137], v[174:177], v[54:57]
	v_mfma_f32_16x16x32_bf16 v[50:53], v[142:145], v[174:177], v[50:53]
	v_mfma_f32_16x16x32_bf16 v[30:33], v[134:137], v[182:185], v[30:33]
	v_mfma_f32_16x16x32_bf16 v[26:29], v[142:145], v[182:185], v[26:29]
	v_mfma_f32_16x16x32_bf16 v[22:25], v[134:137], v[190:193], v[22:25]
	v_mfma_f32_16x16x32_bf16 v[18:21], v[142:145], v[190:193], v[18:21]
	s_setprio 0
	s_setprio 1
	v_mfma_f32_16x16x32_bf16 v[46:49], v[146:149], v[162:165], v[46:49]
	v_mfma_f32_16x16x32_bf16 v[42:45], v[154:157], v[162:165], v[42:45]
	v_mfma_f32_16x16x32_bf16 v[38:41], v[146:149], v[170:173], v[38:41]
	v_mfma_f32_16x16x32_bf16 v[34:37], v[154:157], v[170:173], v[34:37]
	v_mfma_f32_16x16x32_bf16 v[14:17], v[146:149], v[178:181], v[14:17]
	v_mfma_f32_16x16x32_bf16 v[10:13], v[154:157], v[178:181], v[10:13]
	v_mfma_f32_16x16x32_bf16 v[6:9], v[146:149], v[186:189], v[6:9]
	v_mfma_f32_16x16x32_bf16 v[2:5], v[154:157], v[186:189], v[2:5]
	v_mfma_f32_16x16x32_bf16 v[46:49], v[150:153], v[166:169], v[46:49]
	v_mfma_f32_16x16x32_bf16 v[42:45], v[158:161], v[166:169], v[42:45]
	v_mfma_f32_16x16x32_bf16 v[38:41], v[150:153], v[174:177], v[38:41]
	v_mfma_f32_16x16x32_bf16 v[34:37], v[158:161], v[174:177], v[34:37]
	v_mfma_f32_16x16x32_bf16 v[14:17], v[150:153], v[182:185], v[14:17]
	v_mfma_f32_16x16x32_bf16 v[10:13], v[158:161], v[182:185], v[10:13]
	v_mfma_f32_16x16x32_bf16 v[6:9], v[150:153], v[190:193], v[6:9]
	v_mfma_f32_16x16x32_bf16 v[2:5], v[158:161], v[190:193], v[2:5]
	s_barrier
	s_setprio 0
	s_add_u32 s10, s10, 0x100
	s_addc_u32 s11, s11, 0
	s_cmp_gt_u32 s38, 13
	v_readlane_b32 s40, v254, 55
	s_cbranch_scc1 .LBB0_1894

; #define PG8_STAGE(bufoff, gbase, voff) do { _Pragma("unroll") for (int _i = 0; _i < 2; ++_i) \
;         __builtin_amdgcn_global_load_lds((const unsigned*)((const char*)(gbase) + (voff)[_i]), (PG8_LAS unsigned*)(lds + (bufoff) + ldsw + _i * 8192), 16, 0, 0); } while (0)
; #define PG8_LDA(dst, b, h) do { _Pragma("unroll") for (int m = 0; m < 4; ++m) _Pragma("unroll") for (int k = 0; k < 2; ++k) dst[m][k] = *(const PG8_LAS bf16x8*)(lds + PG8_SA(b, h) + aoff + m * 2048 + k * 1024); } while (0)
; #define PG8_LDB(dst, b, h) do { _Pragma("unroll") for (int n = 0; n < 2; ++n) _Pragma("unroll") for (int k = 0; k < 2; ++k) dst[n][k] = *(const PG8_LAS bf16x8*)(lds + PG8_SB(b, h) + boff + n * 2048 + k * 1024); } while (0)
; #define PG8_WAIT_V(n) asm volatile("s_waitcnt vmcnt(" #n ")" ::: "memory")
; #define PG8_WAIT_VN(n) asm volatile("s_waitcnt vmcnt(%0)" :: "n"(n) : "memory")
; #define PG8_WAIT_L(n) asm volatile("s_waitcnt lgkmcnt(" #n ")" ::: "memory")
; template <class Epi, class Sched, bool ALIGN_EPI = false, bool SP2 = false>
; __device__ __forceinline__ void gemm_phase(PG8_LAS unsigned char* lds, const Gemm g, const Sched& S, const Epi& E, const int wave_id) {
;     ...
;         for (int t = 0; t < nt; t += 2) {
;             const bool last = (t == nt - 2);
;             const char* a1 = cA + (size_t)(t + 1) * kstep;
;             const char* a2 = last ? nA : cA + (size_t)(t + 2) * kstep; const char* b2 = last ? nB : cB + (size_t)(t + 2) * kstep;
;             const char* a3 = a2 + kstep; const char* b3 = b2 + kstep;
;             if (last && has_next) S.a_ready(nxt);
;             if constexpr (SP2) {
;             int tz_ = __builtin_amdgcn_readfirstlane(t | (ui > 0 ? 0 : 1)); asm volatile("" : "+s"(tz_));
;             const bool strict = !(Epi::NS > 0 && tz_ == 0);
;             PG8_LDB(B0, 0, 0); PG8_LDB(B1, 0, 1); PG8_SCHED; PG8_LDA(At, 0, 0); PG8_STAGE(PG8_SA(1, 1), a1 + hstep, voffA);
;             PG8_WAIT_VN(8 + Epi::NS); if (strict) PG8_WAIT_V(8); PG8_WAIT_L(0); PG8_BAR; PG8_MMA(0, 0, At, B0); PG8_MMA(0, 1, At, B1); PG8_BAR; PG8_SCHED;
;             PG8_LDA(At, 0, 1); PG8_STAGE(PG8_SB(0, 0), b2, voffB); PG8_STAGE(PG8_SB(0, 1), b2 + hstep, voffB); PG8_STAGE(PG8_SA(0, 0), a2, voffA);
;             PG8_WAIT_VN(8 + Epi::NS); if (strict) PG8_WAIT_V(8); PG8_WAIT_L(0); PG8_BAR; PG8_MMA(1, 0, At, B0); PG8_MMA(1, 1, At, B1); PG8_BAR; PG8_SCHED;
.LBB0_1892:
	s_add_u32 s12, s36, s10
	s_addc_u32 s13, s37, s11
	s_add_u32 s12, s12, 0x8200100
	s_addc_u32 s13, s13, 0
	s_add_u32 s39, s34, s10
	s_addc_u32 s40, s35, s11
	s_cmpk_eq_i32 s10, 0x700
	s_cselect_b32 s15, s9, s13
	s_cselect_b32 s14, s8, s12
	s_cselect_b32 s13, s7, s40
	s_cselect_b32 s12, s6, s39
	s_waitcnt lgkmcnt(0)
	s_setprio 1
	s_barrier
	v_mfma_f32_16x16x32_bf16 v[126:129], v[146:149], v[186:189], v[126:129]
	v_mfma_f32_16x16x32_bf16 v[122:125], v[154:157], v[186:189], v[122:125]
	v_mfma_f32_16x16x32_bf16 v[118:121], v[146:149], v[178:181], v[118:121]
	v_mfma_f32_16x16x32_bf16 v[114:117], v[154:157], v[178:181], v[114:117]
	v_mfma_f32_16x16x32_bf16 v[94:97], v[146:149], v[170:173], v[94:97]
	v_mfma_f32_16x16x32_bf16 v[90:93], v[154:157], v[170:173], v[90:93]
	v_mfma_f32_16x16x32_bf16 v[86:89], v[146:149], v[162:165], v[86:89]
	v_mfma_f32_16x16x32_bf16 v[82:85], v[154:157], v[162:165], v[82:85]
	v_mfma_f32_16x16x32_bf16 v[126:129], v[150:153], v[190:193], v[126:129]
	v_mfma_f32_16x16x32_bf16 v[122:125], v[158:161], v[190:193], v[122:125]
	v_mfma_f32_16x16x32_bf16 v[118:121], v[150:153], v[182:185], v[118:121]
	v_mfma_f32_16x16x32_bf16 v[114:117], v[158:161], v[182:185], v[114:117]
	v_mfma_f32_16x16x32_bf16 v[94:97], v[150:153], v[174:177], v[94:97]
	v_mfma_f32_16x16x32_bf16 v[90:93], v[158:161], v[174:177], v[90:93]
	v_mfma_f32_16x16x32_bf16 v[86:89], v[150:153], v[166:169], v[86:89]
	v_mfma_f32_16x16x32_bf16 v[82:85], v[158:161], v[166:169], v[82:85]
	s_setprio 0
	s_setprio 1
	v_mfma_f32_16x16x32_bf16 v[110:113], v[130:133], v[186:189], v[110:113]
	v_mfma_f32_16x16x32_bf16 v[106:109], v[138:141], v[186:189], v[106:109]
	v_mfma_f32_16x16x32_bf16 v[102:105], v[130:133], v[178:181], v[102:105]
	v_mfma_f32_16x16x32_bf16 v[98:101], v[138:141], v[178:181], v[98:101]
	v_mfma_f32_16x16x32_bf16 v[78:81], v[130:133], v[170:173], v[78:81]
	v_mfma_f32_16x16x32_bf16 v[74:77], v[138:141], v[170:173], v[74:77]
	v_mfma_f32_16x16x32_bf16 v[70:73], v[130:133], v[162:165], v[70:73]
	v_mfma_f32_16x16x32_bf16 v[66:69], v[138:141], v[162:165], v[66:69]
	v_mfma_f32_16x16x32_bf16 v[110:113], v[134:137], v[190:193], v[110:113]
	v_mfma_f32_16x16x32_bf16 v[106:109], v[142:145], v[190:193], v[106:109]
	v_mfma_f32_16x16x32_bf16 v[102:105], v[134:137], v[182:185], v[102:105]
	v_mfma_f32_16x16x32_bf16 v[98:101], v[142:145], v[182:185], v[98:101]
	v_mfma_f32_16x16x32_bf16 v[78:81], v[134:137], v[174:177], v[78:81]
	v_mfma_f32_16x16x32_bf16 v[74:77], v[142:145], v[174:177], v[74:77]
	v_mfma_f32_16x16x32_bf16 v[70:73], v[134:137], v[166:169], v[70:73]
	v_mfma_f32_16x16x32_bf16 v[66:69], v[142:145], v[166:169], v[66:69]
	s_barrier
	s_setprio 0
	s_mov_b32 m0, s22
	v_lshl_add_u64 v[228:229], s[12:13], 0, v[212:213]
	s_add_u32 s40, s12, 0x40000
	ds_read_b128 v[186:189], v232 offset:16384
	ds_read_b128 v[190:193], v232 offset:17408
	ds_read_b128 v[178:181], v232 offset:18432
	ds_read_b128 v[182:185], v232 offset:19456
	ds_read_b128 v[170:173], v232 offset:20480
	ds_read_b128 v[174:177], v232 offset:21504
	ds_read_b128 v[162:165], v232 offset:22528
	ds_read_b128 v[166:169], v232 offset:23552
	global_load_lds_dwordx4 v[228:229], off
	v_lshl_add_u64 v[226:227], s[12:13], 0, v[216:217]
	s_mov_b32 m0, s23
	s_addc_u32 s41, s13, 0
	global_load_lds_dwordx4 v[226:227], off
	v_lshl_add_u64 v[194:195], s[40:41], 0, v[212:213]
	s_mov_b32 m0, s24
	v_lshl_add_u64 v[222:223], s[14:15], 0, v[210:211]
	global_load_lds_dwordx4 v[194:195], off
	v_lshl_add_u64 v[194:195], s[40:41], 0, v[216:217]
	s_mov_b32 m0, s25
	v_lshl_add_u64 v[224:225], s[14:15], 0, v[214:215]
	global_load_lds_dwordx4 v[194:195], off
	s_mov_b32 m0, s5
	s_andn2_b64 vcc, exec, s[16:17]
	global_load_lds_dwordx4 v[222:223], off
	s_mov_b32 m0, s26
	s_nop 0
	global_load_lds_dwordx4 v[224:225], off
	s_waitcnt vmcnt(16)
	s_cbranch_vccnz .LBB0_1889
	s_waitcnt vmcnt(8)
	s_branch .LBB0_1889

; #define PG8_STAGE(bufoff, gbase, voff) do { _Pragma("unroll") for (int _i = 0; _i < 2; ++_i) \
;         __builtin_amdgcn_global_load_lds((const unsigned*)((const char*)(gbase) + (voff)[_i]), (PG8_LAS unsigned*)(lds + (bufoff) + ldsw + _i * 8192), 16, 0, 0); } while (0)
; #define PG8_LDA(dst, b, h) do { _Pragma("unroll") for (int m = 0; m < 4; ++m) _Pragma("unroll") for (int k = 0; k < 2; ++k) dst[m][k] = *(const PG8_LAS bf16x8*)(lds + PG8_SA(b, h) + aoff + m * 2048 + k * 1024); } while (0)
; #define PG8_LDB(dst, b, h) do { _Pragma("unroll") for (int n = 0; n < 2; ++n) _Pragma("unroll") for (int k = 0; k < 2; ++k) dst[n][k] = *(const PG8_LAS bf16x8*)(lds + PG8_SB(b, h) + boff + n * 2048 + k * 1024); } while (0)
; #define PG8_MMA(ai, bj, At, Bt) do { __builtin_amdgcn_s_setprio(1); _Pragma("unroll") for (int m = 0; m < 4; ++m) _Pragma("unroll") for (int n = 0; n < 2; ++n) _Pragma("unroll") for (int k = 0; k < 2; ++k) \
;         acc[ai][bj][m][n] = __builtin_amdgcn_mfma_f32_16x16x32_bf16(Bt[n][k], At[m][k], acc[ai][bj][m][n], 0, 0, 0); __builtin_amdgcn_s_setprio(0); } while (0)
; #define PG8_WAIT_V(n) asm volatile("s_waitcnt vmcnt(" #n ")" ::: "memory")
; #define PG8_WAIT_VN(n) asm volatile("s_waitcnt vmcnt(%0)" :: "n"(n) : "memory")
; #define PG8_WAIT_L(n) asm volatile("s_waitcnt lgkmcnt(" #n ")" ::: "memory")
; template <class Epi, class Sched, bool ALIGN_EPI = false, bool SP2 = false>
; __device__ __forceinline__ void gemm_phase(PG8_LAS unsigned char* lds, const Gemm g, const Sched& S, const Epi& E, const int wave_id) {
;     ...
;             PG8_LDB(B0, 0, 0); PG8_LDB(B1, 0, 1); PG8_SCHED; PG8_LDA(At, 0, 0); PG8_STAGE(PG8_SA(1, 1), a1 + hstep, voffA);
;             PG8_WAIT_VN(8 + Epi::NS); if (strict) PG8_WAIT_V(8); PG8_WAIT_L(0); PG8_BAR; PG8_MMA(0, 0, At, B0); PG8_MMA(0, 1, At, B1); PG8_BAR; PG8_SCHED;
;             PG8_LDA(At, 0, 1); PG8_STAGE(PG8_SB(0, 0), b2, voffB); PG8_STAGE(PG8_SB(0, 1), b2 + hstep, voffB); PG8_STAGE(PG8_SA(0, 0), a2, voffA);
;             PG8_WAIT_VN(8 + Epi::NS); if (strict) PG8_WAIT_V(8); PG8_WAIT_L(0); PG8_BAR; PG8_MMA(1, 0, At, B0); PG8_MMA(1, 1, At, B1); PG8_BAR; PG8_SCHED;
;             PG8_LDB(B0, 1, 0); PG8_LDB(B1, 1, 1); PG8_SCHED; PG8_LDA(At, 1, 0); PG8_STAGE(PG8_SA(0, 1), a2 + hstep, voffA);
;             PG8_WAIT_V(8); PG8_WAIT_L(0); PG8_BAR; PG8_MMA(0, 0, At, B0); PG8_MMA(0, 1, At, B1); PG8_BAR; PG8_SCHED;
.LBB0_1952:
	s_waitcnt lgkmcnt(0)
	s_setprio 1
	s_barrier
	v_mfma_f32_16x16x32_bf16 v[62:65], v[146:149], v[186:189], v[62:65]
	v_mfma_f32_16x16x32_bf16 v[58:61], v[154:157], v[186:189], v[58:61]
	v_mfma_f32_16x16x32_bf16 v[54:57], v[146:149], v[178:181], v[54:57]
	v_mfma_f32_16x16x32_bf16 v[50:53], v[154:157], v[178:181], v[50:53]
	v_mfma_f32_16x16x32_bf16 v[30:33], v[146:149], v[170:173], v[30:33]
	v_mfma_f32_16x16x32_bf16 v[26:29], v[154:157], v[170:173], v[26:29]
	v_mfma_f32_16x16x32_bf16 v[22:25], v[146:149], v[162:165], v[22:25]
	v_mfma_f32_16x16x32_bf16 v[18:21], v[154:157], v[162:165], v[18:21]
	v_mfma_f32_16x16x32_bf16 v[62:65], v[150:153], v[190:193], v[62:65]
	v_mfma_f32_16x16x32_bf16 v[58:61], v[158:161], v[190:193], v[58:61]
	v_mfma_f32_16x16x32_bf16 v[54:57], v[150:153], v[182:185], v[54:57]
	v_mfma_f32_16x16x32_bf16 v[50:53], v[158:161], v[182:185], v[50:53]
	v_mfma_f32_16x16x32_bf16 v[30:33], v[150:153], v[174:177], v[30:33]
	v_mfma_f32_16x16x32_bf16 v[26:29], v[158:161], v[174:177], v[26:29]
	v_mfma_f32_16x16x32_bf16 v[22:25], v[150:153], v[166:169], v[22:25]
	v_mfma_f32_16x16x32_bf16 v[18:21], v[158:161], v[166:169], v[18:21]
	s_setprio 0
	s_setprio 1
	v_mfma_f32_16x16x32_bf16 v[46:49], v[130:133], v[186:189], v[46:49]
	v_mfma_f32_16x16x32_bf16 v[42:45], v[138:141], v[186:189], v[42:45]
	v_mfma_f32_16x16x32_bf16 v[38:41], v[130:133], v[178:181], v[38:41]
	v_mfma_f32_16x16x32_bf16 v[34:37], v[138:141], v[178:181], v[34:37]
	v_mfma_f32_16x16x32_bf16 v[14:17], v[130:133], v[170:173], v[14:17]
	v_mfma_f32_16x16x32_bf16 v[10:13], v[138:141], v[170:173], v[10:13]
	v_mfma_f32_16x16x32_bf16 v[6:9], v[130:133], v[162:165], v[6:9]
	v_mfma_f32_16x16x32_bf16 v[2:5], v[138:141], v[162:165], v[2:5]
	v_mfma_f32_16x16x32_bf16 v[46:49], v[134:137], v[190:193], v[46:49]
	v_mfma_f32_16x16x32_bf16 v[42:45], v[142:145], v[190:193], v[42:45]
	v_mfma_f32_16x16x32_bf16 v[38:41], v[134:137], v[182:185], v[38:41]
	v_mfma_f32_16x16x32_bf16 v[34:37], v[142:145], v[182:185], v[34:37]
	v_mfma_f32_16x16x32_bf16 v[14:17], v[134:137], v[174:177], v[14:17]
	v_mfma_f32_16x16x32_bf16 v[10:13], v[142:145], v[174:177], v[10:13]
	v_mfma_f32_16x16x32_bf16 v[6:9], v[134:137], v[166:169], v[6:9]
	v_mfma_f32_16x16x32_bf16 v[2:5], v[142:145], v[166:169], v[2:5]
	s_barrier
	s_setprio 0
	s_add_i32 s28, 0, 0x18000
	s_add_i32 s29, 0, 0x1c000
	v_add_u32_e32 v142, s28, v246
	v_add_u32_e32 v158, s29, v246
	ds_read_b128 v[130:133], v142
	ds_read_b128 v[134:137], v142 offset:1024
	ds_read_b128 v[138:141], v142 offset:2048
	ds_read_b128 v[142:145], v142 offset:3072
	ds_read_b128 v[146:149], v158
	ds_read_b128 v[150:153], v158 offset:1024
	ds_read_b128 v[154:157], v158 offset:2048
	ds_read_b128 v[158:161], v158 offset:3072
	s_add_u32 s26, s26, 0x40000
	s_addc_u32 s27, s27, 0
	s_mov_b32 m0, s52
	v_lshl_add_u64 v[194:195], s[26:27], 0, v[216:217]
	ds_read_b128 v[162:165], v247 offset:32768
	ds_read_b128 v[166:169], v247 offset:33792
	ds_read_b128 v[170:173], v247 offset:34816
	ds_read_b128 v[174:177], v247 offset:35840
	ds_read_b128 v[178:181], v247 offset:36864
	ds_read_b128 v[182:185], v247 offset:37888
	ds_read_b128 v[186:189], v247 offset:38912
	ds_read_b128 v[190:193], v247 offset:39936
	global_load_lds_dwordx4 v[194:195], off
	v_lshl_add_u64 v[194:195], s[26:27], 0, v[212:213]
	s_mov_b32 m0, s54
	s_nop 0
	global_load_lds_dwordx4 v[194:195], off
	s_waitcnt vmcnt(18)
	s_cmp_eq_u32 s100, 0
	s_cbranch_scc1 .Lthird_wait_relaxed_2
	s_waitcnt vmcnt(8)
; #define PG8_STAGE(bufoff, gbase, voff) do { _Pragma("unroll") for (int _i = 0; _i < 2; ++_i) \
;         __builtin_amdgcn_global_load_lds((const unsigned*)((const char*)(gbase) + (voff)[_i]), (PG8_LAS unsigned*)(lds + (bufoff) + ldsw + _i * 8192), 16, 0, 0); } while (0)
; #define PG8_LDA(dst, b, h) do { _Pragma("unroll") for (int m = 0; m < 4; ++m) _Pragma("unroll") for (int k = 0; k < 2; ++k) dst[m][k] = *(const PG8_LAS bf16x8*)(lds + PG8_SA(b, h) + aoff + m * 2048 + k * 1024); } while (0)
; #define PG8_LDB(dst, b, h) do { _Pragma("unroll") for (int n = 0; n < 2; ++n) _Pragma("unroll") for (int k = 0; k < 2; ++k) dst[n][k] = *(const PG8_LAS bf16x8*)(lds + PG8_SB(b, h) + boff + n * 2048 + k * 1024); } while (0)
; #define PG8_MMA(ai, bj, At, Bt) do { __builtin_amdgcn_s_setprio(1); _Pragma("unroll") for (int m = 0; m < 4; ++m) _Pragma("unroll") for (int n = 0; n < 2; ++n) _Pragma("unroll") for (int k = 0; k < 2; ++k) \
;         acc[ai][bj][m][n] = __builtin_amdgcn_mfma_f32_16x16x32_bf16(Bt[n][k], At[m][k], acc[ai][bj][m][n], 0, 0, 0); __builtin_amdgcn_s_setprio(0); } while (0)
; #define PG8_WAIT_V(n) asm volatile("s_waitcnt vmcnt(" #n ")" ::: "memory")
; #define PG8_WAIT_L(n) asm volatile("s_waitcnt lgkmcnt(" #n ")" ::: "memory")
; #define PG8_BAR __builtin_amdgcn_s_barrier()
; #define PG8_SCHED __builtin_amdgcn_sched_barrier(0)
; template <class Epi, class Sched, bool ALIGN_EPI = false, bool SP2 = false>
; __device__ __forceinline__ void gemm_phase(PG8_LAS unsigned char* lds, const Gemm g, const Sched& S, const Epi& E, const int wave_id) {
;     ...
;             PG8_LDB(B0, 1, 0); PG8_LDB(B1, 1, 1); PG8_SCHED; PG8_LDA(At, 1, 0); PG8_STAGE(PG8_SA(0, 1), a2 + hstep, voffA);
;             PG8_WAIT_V(8); PG8_WAIT_L(0); PG8_BAR; PG8_MMA(0, 0, At, B0); PG8_MMA(0, 1, At, B1); PG8_BAR; PG8_SCHED;
;             PG8_LDA(At, 1, 1); PG8_STAGE(PG8_SB(1, 0), b3, voffB); PG8_STAGE(PG8_SB(1, 1), b3 + hstep, voffB); PG8_STAGE(PG8_SA(1, 0), a3, voffA);
;             PG8_WAIT_V(8); PG8_WAIT_L(0); PG8_BAR; PG8_MMA(1, 0, At, B0); PG8_MMA(1, 1, At, B1); PG8_BAR; PG8_SCHED;
.Lthird_wait_relaxed_2:
	s_waitcnt lgkmcnt(0)
	s_setprio 1
	s_barrier
	v_mfma_f32_16x16x32_bf16 v[126:129], v[130:133], v[162:165], v[126:129]
	v_mfma_f32_16x16x32_bf16 v[122:125], v[138:141], v[162:165], v[122:125]
	v_mfma_f32_16x16x32_bf16 v[118:121], v[130:133], v[170:173], v[118:121]
	v_mfma_f32_16x16x32_bf16 v[114:117], v[138:141], v[170:173], v[114:117]
	v_mfma_f32_16x16x32_bf16 v[94:97], v[130:133], v[178:181], v[94:97]
	v_mfma_f32_16x16x32_bf16 v[90:93], v[138:141], v[178:181], v[90:93]
	v_mfma_f32_16x16x32_bf16 v[86:89], v[130:133], v[186:189], v[86:89]
	v_mfma_f32_16x16x32_bf16 v[82:85], v[138:141], v[186:189], v[82:85]
	v_mfma_f32_16x16x32_bf16 v[126:129], v[134:137], v[166:169], v[126:129]
	v_mfma_f32_16x16x32_bf16 v[122:125], v[142:145], v[166:169], v[122:125]
	v_mfma_f32_16x16x32_bf16 v[118:121], v[134:137], v[174:177], v[118:121]
	v_mfma_f32_16x16x32_bf16 v[114:117], v[142:145], v[174:177], v[114:117]
	v_mfma_f32_16x16x32_bf16 v[94:97], v[134:137], v[182:185], v[94:97]
	v_mfma_f32_16x16x32_bf16 v[90:93], v[142:145], v[182:185], v[90:93]
	v_mfma_f32_16x16x32_bf16 v[86:89], v[134:137], v[190:193], v[86:89]
	v_mfma_f32_16x16x32_bf16 v[82:85], v[142:145], v[190:193], v[82:85]
	s_setprio 0
	s_setprio 1
	v_mfma_f32_16x16x32_bf16 v[110:113], v[146:149], v[162:165], v[110:113]
	v_mfma_f32_16x16x32_bf16 v[106:109], v[154:157], v[162:165], v[106:109]
	v_mfma_f32_16x16x32_bf16 v[102:105], v[146:149], v[170:173], v[102:105]
	v_mfma_f32_16x16x32_bf16 v[98:101], v[154:157], v[170:173], v[98:101]
	v_mfma_f32_16x16x32_bf16 v[78:81], v[146:149], v[178:181], v[78:81]
	v_mfma_f32_16x16x32_bf16 v[74:77], v[154:157], v[178:181], v[74:77]
	v_mfma_f32_16x16x32_bf16 v[70:73], v[146:149], v[186:189], v[70:73]
	v_mfma_f32_16x16x32_bf16 v[66:69], v[154:157], v[186:189], v[66:69]
	v_mfma_f32_16x16x32_bf16 v[110:113], v[150:153], v[166:169], v[110:113]
	v_mfma_f32_16x16x32_bf16 v[106:109], v[158:161], v[166:169], v[106:109]
	v_mfma_f32_16x16x32_bf16 v[102:105], v[150:153], v[174:177], v[102:105]
	v_mfma_f32_16x16x32_bf16 v[98:101], v[158:161], v[174:177], v[98:101]
	v_mfma_f32_16x16x32_bf16 v[78:81], v[150:153], v[182:185], v[78:81]
	v_mfma_f32_16x16x32_bf16 v[74:77], v[158:161], v[182:185], v[74:77]
	v_mfma_f32_16x16x32_bf16 v[70:73], v[150:153], v[190:193], v[70:73]
	v_mfma_f32_16x16x32_bf16 v[66:69], v[158:161], v[190:193], v[66:69]
	s_barrier
	s_setprio 0
	s_add_i32 s26, s28, s39
	v_lshl_add_u64 v[194:195], v[232:233], 0, s[64:65]
	s_mov_b32 m0, s26
	ds_read_b128 v[162:165], v247 offset:49152
	ds_read_b128 v[166:169], v247 offset:50176
	ds_read_b128 v[170:173], v247 offset:51200
	ds_read_b128 v[174:177], v247 offset:52224
	ds_read_b128 v[178:181], v247 offset:53248
	ds_read_b128 v[182:185], v247 offset:54272
	ds_read_b128 v[186:189], v247 offset:55296
	ds_read_b128 v[190:193], v247 offset:56320
	global_load_lds_dwordx4 v[194:195], off
	s_add_i32 m0, s26, 0x2000
	s_add_u32 s24, s24, 0x40080
	v_lshl_add_u64 v[194:195], v[230:231], 0, s[64:65]
	s_addc_u32 s25, s25, 0
	s_add_i32 s26, s29, s39
	global_load_lds_dwordx4 v[194:195], off
	v_lshl_add_u64 v[194:195], s[24:25], 0, v[214:215]
	s_mov_b32 m0, s26
	s_nop 0
	global_load_lds_dwordx4 v[194:195], off
	v_lshl_add_u64 v[194:195], s[24:25], 0, v[210:211]
	s_add_i32 m0, s26, 0x2000
	s_nop 0
	global_load_lds_dwordx4 v[194:195], off
	v_lshl_add_u64 v[194:195], v[226:227], 0, s[64:65]
	s_mov_b32 m0, s57
	s_nop 0
	global_load_lds_dwordx4 v[194:195], off
	v_lshl_add_u64 v[194:195], v[228:229], 0, s[64:65]
	s_mov_b32 m0, s62
	s_nop 0
	global_load_lds_dwordx4 v[194:195], off
	s_waitcnt vmcnt(8)
	s_waitcnt lgkmcnt(0)
	s_setprio 1
	s_barrier
	v_mfma_f32_16x16x32_bf16 v[62:65], v[130:133], v[162:165], v[62:65]
	v_mfma_f32_16x16x32_bf16 v[58:61], v[138:141], v[162:165], v[58:61]
	v_mfma_f32_16x16x32_bf16 v[54:57], v[130:133], v[170:173], v[54:57]
	v_mfma_f32_16x16x32_bf16 v[50:53], v[138:141], v[170:173], v[50:53]
	v_mfma_f32_16x16x32_bf16 v[30:33], v[130:133], v[178:181], v[30:33]
	v_mfma_f32_16x16x32_bf16 v[26:29], v[138:141], v[178:181], v[26:29]
	v_mfma_f32_16x16x32_bf16 v[22:25], v[130:133], v[186:189], v[22:25]
	v_mfma_f32_16x16x32_bf16 v[18:21], v[138:141], v[186:189], v[18:21]
	v_mfma_f32_16x16x32_bf16 v[62:65], v[134:137], v[166:169], v[62:65]
	v_mfma_f32_16x16x32_bf16 v[58:61], v[142:145], v[166:169], v[58:61]
	v_mfma_f32_16x16x32_bf16 v[54:57], v[134:137], v[174:177], v[54:57]
	v_mfma_f32_16x16x32_bf16 v[50:53], v[142:145], v[174:177], v[50:53]
	v_mfma_f32_16x16x32_bf16 v[30:33], v[134:137], v[182:185], v[30:33]
	v_mfma_f32_16x16x32_bf16 v[26:29], v[142:145], v[182:185], v[26:29]
	v_mfma_f32_16x16x32_bf16 v[22:25], v[134:137], v[190:193], v[22:25]
	v_mfma_f32_16x16x32_bf16 v[18:21], v[142:145], v[190:193], v[18:21]
	s_setprio 0
	s_setprio 1
	v_mfma_f32_16x16x32_bf16 v[46:49], v[146:149], v[162:165], v[46:49]
	v_mfma_f32_16x16x32_bf16 v[42:45], v[154:157], v[162:165], v[42:45]
	v_mfma_f32_16x16x32_bf16 v[38:41], v[146:149], v[170:173], v[38:41]
	v_mfma_f32_16x16x32_bf16 v[34:37], v[154:157], v[170:173], v[34:37]
	v_mfma_f32_16x16x32_bf16 v[14:17], v[146:149], v[178:181], v[14:17]
	v_mfma_f32_16x16x32_bf16 v[10:13], v[154:157], v[178:181], v[10:13]
	v_mfma_f32_16x16x32_bf16 v[6:9], v[146:149], v[186:189], v[6:9]
	v_mfma_f32_16x16x32_bf16 v[2:5], v[154:157], v[186:189], v[2:5]
	v_mfma_f32_16x16x32_bf16 v[46:49], v[150:153], v[166:169], v[46:49]
	v_mfma_f32_16x16x32_bf16 v[42:45], v[158:161], v[166:169], v[42:45]
	v_mfma_f32_16x16x32_bf16 v[38:41], v[150:153], v[174:177], v[38:41]
	v_mfma_f32_16x16x32_bf16 v[34:37], v[158:161], v[174:177], v[34:37]
	v_mfma_f32_16x16x32_bf16 v[14:17], v[150:153], v[182:185], v[14:17]
	v_mfma_f32_16x16x32_bf16 v[10:13], v[158:161], v[182:185], v[10:13]
	v_mfma_f32_16x16x32_bf16 v[6:9], v[150:153], v[190:193], v[6:9]
	v_mfma_f32_16x16x32_bf16 v[2:5], v[158:161], v[190:193], v[2:5]
	s_barrier
	s_setprio 0
	s_add_i32 s76, s76, 2
	s_add_u32 s22, s22, 0x100
	s_addc_u32 s23, s23, 0
	s_cmp_gt_u32 s76, 13
	s_cbranch_scc1 .LBB0_1957

; #define PG8_STAGE(bufoff, gbase, voff) do { _Pragma("unroll") for (int _i = 0; _i < 2; ++_i) \
;         __builtin_amdgcn_global_load_lds((const unsigned*)((const char*)(gbase) + (voff)[_i]), (PG8_LAS unsigned*)(lds + (bufoff) + ldsw + _i * 8192), 16, 0, 0); } while (0)
; #define PG8_LDA(dst, b, h) do { _Pragma("unroll") for (int m = 0; m < 4; ++m) _Pragma("unroll") for (int k = 0; k < 2; ++k) dst[m][k] = *(const PG8_LAS bf16x8*)(lds + PG8_SA(b, h) + aoff + m * 2048 + k * 1024); } while (0)
; #define PG8_LDB(dst, b, h) do { _Pragma("unroll") for (int n = 0; n < 2; ++n) _Pragma("unroll") for (int k = 0; k < 2; ++k) dst[n][k] = *(const PG8_LAS bf16x8*)(lds + PG8_SB(b, h) + boff + n * 2048 + k * 1024); } while (0)
; #define PG8_WAIT_V(n) asm volatile("s_waitcnt vmcnt(" #n ")" ::: "memory")
; #define PG8_WAIT_VN(n) asm volatile("s_waitcnt vmcnt(%0)" :: "n"(n) : "memory")
; #define PG8_WAIT_L(n) asm volatile("s_waitcnt lgkmcnt(" #n ")" ::: "memory")
; #define PG8_BAR __builtin_amdgcn_s_barrier()
; #define PG8_SCHED __builtin_amdgcn_sched_barrier(0)
; template <class Epi, class Sched, bool ALIGN_EPI = false, bool SP2 = false>
; __device__ __forceinline__ void gemm_phase(PG8_LAS unsigned char* lds, const Gemm g, const Sched& S, const Epi& E, const int wave_id) {
;     ...
;             const char* a1 = cA + (size_t)(t + 1) * kstep;
;             const char* a2 = last ? nA : cA + (size_t)(t + 2) * kstep; const char* b2 = last ? nB : cB + (size_t)(t + 2) * kstep;
;             const char* a3 = a2 + kstep; const char* b3 = b2 + kstep;
;             if (last && has_next) S.a_ready(nxt);
;             if constexpr (SP2) {
;             int tz_ = __builtin_amdgcn_readfirstlane(t | (ui > 0 ? 0 : 1)); asm volatile("" : "+s"(tz_));
;             const bool strict = !(Epi::NS > 0 && tz_ == 0);
;             PG8_LDB(B0, 0, 0); PG8_LDB(B1, 0, 1); PG8_SCHED; PG8_LDA(At, 0, 0); PG8_STAGE(PG8_SA(1, 1), a1 + hstep, voffA);
;             PG8_WAIT_VN(8 + Epi::NS); if (strict) PG8_WAIT_V(8); PG8_WAIT_L(0); PG8_BAR; PG8_MMA(0, 0, At, B0); PG8_MMA(0, 1, At, B1); PG8_BAR; PG8_SCHED;
;             PG8_LDA(At, 0, 1); PG8_STAGE(PG8_SB(0, 0), b2, voffB); PG8_STAGE(PG8_SB(0, 1), b2 + hstep, voffB); PG8_STAGE(PG8_SA(0, 0), a2, voffA);
;             PG8_WAIT_VN(8 + Epi::NS); if (strict) PG8_WAIT_V(8); PG8_WAIT_L(0); PG8_BAR; PG8_MMA(1, 0, At, B0); PG8_MMA(1, 1, At, B1); PG8_BAR; PG8_SCHED;
.LBB0_1955:
	s_add_u32 s24, s20, s22
	s_addc_u32 s25, s21, s23
	s_add_u32 s24, s24, 0x100
	s_addc_u32 s25, s25, 0
	s_add_u32 s53, s74, s22
	s_addc_u32 s78, s75, s23
	s_cmpk_eq_i32 s22, 0x700
	s_cselect_b32 s27, s13, s25
	s_cselect_b32 s26, s68, s24
	s_cselect_b32 s25, s11, s78
	s_cselect_b32 s24, s69, s53
	s_waitcnt lgkmcnt(0)
	s_setprio 1
	s_barrier
	v_mfma_f32_16x16x32_bf16 v[126:129], v[146:149], v[186:189], v[126:129]
	v_mfma_f32_16x16x32_bf16 v[122:125], v[154:157], v[186:189], v[122:125]
	v_mfma_f32_16x16x32_bf16 v[118:121], v[146:149], v[178:181], v[118:121]
	v_mfma_f32_16x16x32_bf16 v[114:117], v[154:157], v[178:181], v[114:117]
	v_mfma_f32_16x16x32_bf16 v[94:97], v[146:149], v[170:173], v[94:97]
	v_mfma_f32_16x16x32_bf16 v[90:93], v[154:157], v[170:173], v[90:93]
	v_mfma_f32_16x16x32_bf16 v[86:89], v[146:149], v[162:165], v[86:89]
	v_mfma_f32_16x16x32_bf16 v[82:85], v[154:157], v[162:165], v[82:85]
	v_mfma_f32_16x16x32_bf16 v[126:129], v[150:153], v[190:193], v[126:129]
	v_mfma_f32_16x16x32_bf16 v[122:125], v[158:161], v[190:193], v[122:125]
	v_mfma_f32_16x16x32_bf16 v[118:121], v[150:153], v[182:185], v[118:121]
	v_mfma_f32_16x16x32_bf16 v[114:117], v[158:161], v[182:185], v[114:117]
	v_mfma_f32_16x16x32_bf16 v[94:97], v[150:153], v[174:177], v[94:97]
	v_mfma_f32_16x16x32_bf16 v[90:93], v[158:161], v[174:177], v[90:93]
	v_mfma_f32_16x16x32_bf16 v[86:89], v[150:153], v[166:169], v[86:89]
	v_mfma_f32_16x16x32_bf16 v[82:85], v[158:161], v[166:169], v[82:85]
	s_setprio 0
	s_setprio 1
	v_mfma_f32_16x16x32_bf16 v[110:113], v[130:133], v[186:189], v[110:113]
	v_mfma_f32_16x16x32_bf16 v[106:109], v[138:141], v[186:189], v[106:109]
	v_mfma_f32_16x16x32_bf16 v[102:105], v[130:133], v[178:181], v[102:105]
	v_mfma_f32_16x16x32_bf16 v[98:101], v[138:141], v[178:181], v[98:101]
	v_mfma_f32_16x16x32_bf16 v[78:81], v[130:133], v[170:173], v[78:81]
	v_mfma_f32_16x16x32_bf16 v[74:77], v[138:141], v[170:173], v[74:77]
	v_mfma_f32_16x16x32_bf16 v[70:73], v[130:133], v[162:165], v[70:73]
	v_mfma_f32_16x16x32_bf16 v[66:69], v[138:141], v[162:165], v[66:69]
	v_mfma_f32_16x16x32_bf16 v[110:113], v[134:137], v[190:193], v[110:113]
	v_mfma_f32_16x16x32_bf16 v[106:109], v[142:145], v[190:193], v[106:109]
	v_mfma_f32_16x16x32_bf16 v[102:105], v[134:137], v[182:185], v[102:105]
	v_mfma_f32_16x16x32_bf16 v[98:101], v[142:145], v[182:185], v[98:101]
	v_mfma_f32_16x16x32_bf16 v[78:81], v[134:137], v[174:177], v[78:81]
	v_mfma_f32_16x16x32_bf16 v[74:77], v[142:145], v[174:177], v[74:77]
	v_mfma_f32_16x16x32_bf16 v[70:73], v[134:137], v[166:169], v[70:73]
	v_mfma_f32_16x16x32_bf16 v[66:69], v[142:145], v[166:169], v[66:69]
	s_barrier
	s_setprio 0
	s_mov_b32 m0, s42
	v_lshl_add_u64 v[232:233], s[24:25], 0, v[214:215]
	s_add_u32 s90, s24, 0x40000
	ds_read_b128 v[186:189], v247 offset:16384
	ds_read_b128 v[190:193], v247 offset:17408
	ds_read_b128 v[178:181], v247 offset:18432
	ds_read_b128 v[182:185], v247 offset:19456
	ds_read_b128 v[170:173], v247 offset:20480
	ds_read_b128 v[174:177], v247 offset:21504
	ds_read_b128 v[162:165], v247 offset:22528
	ds_read_b128 v[166:169], v247 offset:23552
	global_load_lds_dwordx4 v[232:233], off
	v_lshl_add_u64 v[230:231], s[24:25], 0, v[210:211]
	s_mov_b32 m0, s43
	s_addc_u32 s91, s25, 0
	global_load_lds_dwordx4 v[230:231], off
	v_lshl_add_u64 v[194:195], s[90:91], 0, v[214:215]
	s_mov_b32 m0, s49
	v_lshl_add_u64 v[226:227], s[26:27], 0, v[216:217]
	global_load_lds_dwordx4 v[194:195], off
	v_lshl_add_u64 v[194:195], s[90:91], 0, v[210:211]
	s_mov_b32 m0, s50
	v_lshl_add_u64 v[228:229], s[26:27], 0, v[212:213]
	global_load_lds_dwordx4 v[194:195], off
	s_mov_b32 m0, s41
	s_andn2_b64 vcc, exec, s[28:29]
	global_load_lds_dwordx4 v[226:227], off
	s_mov_b32 m0, s51
	s_nop 0
	global_load_lds_dwordx4 v[228:229], off
	s_waitcnt vmcnt(16)
	s_cbranch_vccnz .LBB0_1952
	s_waitcnt vmcnt(8)
	s_branch .LBB0_1952

; #define PG8_STAGE(bufoff, gbase, voff) do { _Pragma("unroll") for (int _i = 0; _i < 2; ++_i) \
;         __builtin_amdgcn_global_load_lds((const unsigned*)((const char*)(gbase) + (voff)[_i]), (PG8_LAS unsigned*)(lds + (bufoff) + ldsw + _i * 8192), 16, 0, 0); } while (0)
; #define PG8_LDA(dst, b, h) do { _Pragma("unroll") for (int m = 0; m < 4; ++m) _Pragma("unroll") for (int k = 0; k < 2; ++k) dst[m][k] = *(const PG8_LAS bf16x8*)(lds + PG8_SA(b, h) + aoff + m * 2048 + k * 1024); } while (0)
; #define PG8_LDB(dst, b, h) do { _Pragma("unroll") for (int n = 0; n < 2; ++n) _Pragma("unroll") for (int k = 0; k < 2; ++k) dst[n][k] = *(const PG8_LAS bf16x8*)(lds + PG8_SB(b, h) + boff + n * 2048 + k * 1024); } while (0)
; #define PG8_WAIT_V(n) asm volatile("s_waitcnt vmcnt(" #n ")" ::: "memory")
; #define PG8_WAIT_VN(n) asm volatile("s_waitcnt vmcnt(%0)" :: "n"(n) : "memory")
; #define PG8_WAIT_L(n) asm volatile("s_waitcnt lgkmcnt(" #n ")" ::: "memory")
; #define PG8_BAR __builtin_amdgcn_s_barrier()
; #define PG8_SCHED __builtin_amdgcn_sched_barrier(0)
; template <class Epi, class Sched, bool ALIGN_EPI = false, bool SP2 = false>
; __device__ __forceinline__ void gemm_phase(PG8_LAS unsigned char* lds, const Gemm g, const Sched& S, const Epi& E, const int wave_id) {
;     ...
;             const char* a1 = cA + (size_t)(t + 1) * kstep;
;             const char* a2 = last ? nA : cA + (size_t)(t + 2) * kstep; const char* b2 = last ? nB : cB + (size_t)(t + 2) * kstep;
;             const char* a3 = a2 + kstep; const char* b3 = b2 + kstep;
;             if (last && has_next) S.a_ready(nxt);
;             if constexpr (SP2) {
;             int tz_ = __builtin_amdgcn_readfirstlane(t | (ui > 0 ? 0 : 1)); asm volatile("" : "+s"(tz_));
;             const bool strict = !(Epi::NS > 0 && tz_ == 0);
;             PG8_LDB(B0, 0, 0); PG8_LDB(B1, 0, 1); PG8_SCHED; PG8_LDA(At, 0, 0); PG8_STAGE(PG8_SA(1, 1), a1 + hstep, voffA);
;             PG8_WAIT_VN(8 + Epi::NS); if (strict) PG8_WAIT_V(8); PG8_WAIT_L(0); PG8_BAR; PG8_MMA(0, 0, At, B0); PG8_MMA(0, 1, At, B1); PG8_BAR; PG8_SCHED;
;             PG8_LDA(At, 0, 1); PG8_STAGE(PG8_SB(0, 0), b2, voffB); PG8_STAGE(PG8_SB(0, 1), b2 + hstep, voffB); PG8_STAGE(PG8_SA(0, 0), a2, voffA);
;             PG8_WAIT_VN(8 + Epi::NS); if (strict) PG8_WAIT_V(8); PG8_WAIT_L(0); PG8_BAR; PG8_MMA(1, 0, At, B0); PG8_MMA(1, 1, At, B1); PG8_BAR; PG8_SCHED;
.LBB0_2033:
	s_add_u32 s16, s12, s14
	s_addc_u32 s17, s13, s15
	s_add_u32 s16, s16, 0x100
	s_addc_u32 s17, s17, 0
	s_add_u32 s53, s57, s14
	s_addc_u32 s67, s62, s15
	s_cmpk_eq_i32 s14, 0x1500
	s_cselect_b32 s19, s9, s17
	s_cselect_b32 s18, s8, s16
	s_cselect_b32 s17, s11, s67
	s_cselect_b32 s16, s10, s53
	s_waitcnt lgkmcnt(0)
	s_setprio 1
	s_barrier
	v_mfma_f32_16x16x32_bf16 v[126:129], v[146:149], v[186:189], v[126:129]
	v_mfma_f32_16x16x32_bf16 v[122:125], v[154:157], v[186:189], v[122:125]
	v_mfma_f32_16x16x32_bf16 v[110:113], v[146:149], v[178:181], v[110:113]
	v_mfma_f32_16x16x32_bf16 v[106:109], v[154:157], v[178:181], v[106:109]
	v_mfma_f32_16x16x32_bf16 v[94:97], v[146:149], v[170:173], v[94:97]
	v_mfma_f32_16x16x32_bf16 v[90:93], v[154:157], v[170:173], v[90:93]
	v_mfma_f32_16x16x32_bf16 v[78:81], v[146:149], v[162:165], v[78:81]
	v_mfma_f32_16x16x32_bf16 v[74:77], v[154:157], v[162:165], v[74:77]
	v_mfma_f32_16x16x32_bf16 v[126:129], v[150:153], v[190:193], v[126:129]
	v_mfma_f32_16x16x32_bf16 v[122:125], v[158:161], v[190:193], v[122:125]
	v_mfma_f32_16x16x32_bf16 v[110:113], v[150:153], v[182:185], v[110:113]
	v_mfma_f32_16x16x32_bf16 v[106:109], v[158:161], v[182:185], v[106:109]
	v_mfma_f32_16x16x32_bf16 v[94:97], v[150:153], v[174:177], v[94:97]
	v_mfma_f32_16x16x32_bf16 v[90:93], v[158:161], v[174:177], v[90:93]
	v_mfma_f32_16x16x32_bf16 v[78:81], v[150:153], v[166:169], v[78:81]
	v_mfma_f32_16x16x32_bf16 v[74:77], v[158:161], v[166:169], v[74:77]
	s_setprio 0
	s_setprio 1
	v_mfma_f32_16x16x32_bf16 v[118:121], v[130:133], v[186:189], v[118:121]
	v_mfma_f32_16x16x32_bf16 v[114:117], v[138:141], v[186:189], v[114:117]
	v_mfma_f32_16x16x32_bf16 v[102:105], v[130:133], v[178:181], v[102:105]
	v_mfma_f32_16x16x32_bf16 v[98:101], v[138:141], v[178:181], v[98:101]
	v_mfma_f32_16x16x32_bf16 v[86:89], v[130:133], v[170:173], v[86:89]
	v_mfma_f32_16x16x32_bf16 v[82:85], v[138:141], v[170:173], v[82:85]
	v_mfma_f32_16x16x32_bf16 v[70:73], v[130:133], v[162:165], v[70:73]
	v_mfma_f32_16x16x32_bf16 v[66:69], v[138:141], v[162:165], v[66:69]
	v_mfma_f32_16x16x32_bf16 v[118:121], v[134:137], v[190:193], v[118:121]
	v_mfma_f32_16x16x32_bf16 v[114:117], v[142:145], v[190:193], v[114:117]
	v_mfma_f32_16x16x32_bf16 v[102:105], v[134:137], v[182:185], v[102:105]
	v_mfma_f32_16x16x32_bf16 v[98:101], v[142:145], v[182:185], v[98:101]
	v_mfma_f32_16x16x32_bf16 v[86:89], v[134:137], v[174:177], v[86:89]
	v_mfma_f32_16x16x32_bf16 v[82:85], v[142:145], v[174:177], v[82:85]
	v_mfma_f32_16x16x32_bf16 v[70:73], v[134:137], v[166:169], v[70:73]
	v_mfma_f32_16x16x32_bf16 v[66:69], v[142:145], v[166:169], v[66:69]
	s_barrier
	s_setprio 0
	s_mov_b32 m0, s34
	v_lshl_add_u64 v[232:233], s[16:17], 0, v[212:213]
	s_add_u32 s68, s16, 0xb0000
	ds_read_b128 v[186:189], v247 offset:16384
	ds_read_b128 v[190:193], v247 offset:17408
	ds_read_b128 v[178:181], v247 offset:18432
	ds_read_b128 v[182:185], v247 offset:19456
	ds_read_b128 v[170:173], v247 offset:20480
	ds_read_b128 v[174:177], v247 offset:21504
	ds_read_b128 v[162:165], v247 offset:22528
	ds_read_b128 v[166:169], v247 offset:23552
	global_load_lds_dwordx4 v[232:233], off
	v_lshl_add_u64 v[230:231], s[16:17], 0, v[216:217]
	s_mov_b32 m0, s35
	s_addc_u32 s69, s17, 0
	global_load_lds_dwordx4 v[230:231], off
	v_lshl_add_u64 v[194:195], s[68:69], 0, v[212:213]
	s_mov_b32 m0, s36
	v_lshl_add_u64 v[226:227], s[18:19], 0, v[210:211]
	global_load_lds_dwordx4 v[194:195], off
	v_lshl_add_u64 v[194:195], s[68:69], 0, v[216:217]
	s_mov_b32 m0, s37
	v_lshl_add_u64 v[228:229], s[18:19], 0, v[214:215]
	global_load_lds_dwordx4 v[194:195], off
	s_mov_b32 m0, s31
	s_andn2_b64 vcc, exec, s[20:21]
	global_load_lds_dwordx4 v[226:227], off
	s_mov_b32 m0, s38
	s_nop 0
	global_load_lds_dwordx4 v[228:229], off
	s_waitcnt vmcnt(24)
	s_cbranch_vccnz .LBB0_2030
	s_waitcnt vmcnt(8)
	s_branch .LBB0_2030
